# k-blocked weight layout extended to NSA_IN, KVQ (WKV, WDQ) and DQ GEMM loops (besides FFN1); OUTPROJ and FFN2 weights still row-major
# speedup vs baseline: 1.0318x; 1.0129x over previous
.LBB0_29:
	s_ashr_i32 s13, s12, 31
	s_lshr_b32 s13, s13, 28
	s_add_i32 s13, s12, s13
	s_and_b32 s40, s13, 0x1fffff0
	s_sub_i32 s12, s12, s40
	s_add_i32 s12, s12, s15
	s_lshl_b32 s57, s12, 7
	s_lshl_b32 s12, s13, 4
	s_waitcnt vmcnt(6)
	v_mov_b32_e32 v58, v224
	s_and_b32 s54, s12, 0xffffff00
	s_waitcnt vmcnt(0)
	s_nop 0
	v_readfirstlane_b32 s12, v58
	v_bfe_u32 v59, v58, 4, 2
	s_and_b32 s40, s12, 0xffffffc0
	s_waitcnt vmcnt(4)
	v_bfe_u32 v42, v58, 2, 4
	v_sub_u32_e32 v60, 0, v59
	s_add_i32 s40, s40, s54
	v_xor_b32_e32 v0, v58, v60
	v_or_b32_e32 v6, s40, v42
	v_lshlrev_b32_e32 v0, 4, v0
	v_min_i32_e32 v4, 0x3ff, v6
	v_and_b32_e32 v0, 48, v0
	v_ashrrev_i32_e32 v5, 31, v4
	v_lshl_add_u64 v[2:3], s[48:49], 0, v[0:1]
	v_lshlrev_b64 v[4:5], 6, v[4:5]
	v_lshl_add_u64 v[34:35], v[2:3], 0, v[4:5]
	v_or_b32_e32 v4, 16, v6
	v_min_i32_e32 v4, 0x3ff, v4
	v_ashrrev_i32_e32 v5, 31, v4
	v_lshlrev_b64 v[4:5], 6, v[4:5]
	v_lshl_add_u64 v[36:37], v[2:3], 0, v[4:5]
	v_or_b32_e32 v4, 32, v6
	v_min_i32_e32 v4, 0x3ff, v4
	s_ashr_i32 s13, s12, 6
	v_ashrrev_i32_e32 v5, 31, v4
	s_and_b32 s42, s13, 1
	v_lshlrev_b64 v[4:5], 6, v[4:5]
	v_lshl_add_u64 v[38:39], v[2:3], 0, v[4:5]
	v_or_b32_e32 v4, 48, v6
	s_lshl_b32 s40, s42, 6
	v_min_i32_e32 v4, 0x3ff, v4
	v_and_b32_e32 v61, 15, v58
	s_or_b32 s40, s40, s57
	v_ashrrev_i32_e32 v5, 31, v4
	s_waitcnt vmcnt(1)
	v_or_b32_e32 v14, s40, v61
	v_lshlrev_b64 v[4:5], 6, v[4:5]
	v_ashrrev_i32_e32 v15, 31, v14
	v_lshl_add_u64 v[40:41], v[2:3], 0, v[4:5]
	v_lshlrev_b64 v[2:3], 5, v[14:15]
	v_lshl_add_u64 v[2:3], s[46:47], 0, v[2:3]
	s_barrier
	global_load_dwordx4 v[6:9], v[2:3], off offset:16
	global_load_dwordx4 v[22:25], v[2:3], off
	v_or_b32_e32 v2, 16, v14
	v_ashrrev_i32_e32 v3, 31, v2
	v_lshlrev_b64 v[2:3], 5, v[2:3]
	v_lshl_add_u64 v[10:11], s[46:47], 0, v[2:3]
	global_load_dwordx4 v[2:5], v[10:11], off offset:16
	global_load_dwordx4 v[18:21], v[10:11], off
	v_or_b32_e32 v10, 32, v14
	v_or_b32_e32 v14, 48, v14
	v_ashrrev_i32_e32 v11, 31, v10
	v_ashrrev_i32_e32 v15, 31, v14
	v_lshlrev_b64 v[10:11], 5, v[10:11]
	v_lshlrev_b64 v[14:15], 5, v[14:15]
	v_lshl_add_u64 v[16:17], s[46:47], 0, v[10:11]
	v_lshl_add_u64 v[30:31], s[46:47], 0, v[14:15]
	global_load_dwordx4 v[10:13], v[16:17], off offset:16
	global_load_dwordx4 v[26:29], v[16:17], off
	s_nop 0
	global_load_dwordx4 v[14:17], v[30:31], off offset:16
	s_nop 0
	global_load_dwordx4 v[30:33], v[30:31], off
	s_lshl_b32 s40, s13, 1
	s_waitcnt vmcnt(8)
	v_or_b32_e32 v46, s57, v42
	v_lshl_add_u32 v44, s13, 5, v46
	s_lshl_b32 s41, s40, 10
	s_or_b32 s40, s40, 1
	v_ashrrev_i32_e32 v45, 31, v44
	v_lshl_add_u32 v46, s40, 4, v46
	v_lshl_add_u64 v[42:43], s[0:1], 0, v[0:1]
	v_lshlrev_b64 v[162:163], 10, v[44:45]
	v_lshlrev_b64 v[44:45], 11, v[44:45]
	v_ashrrev_i32_e32 v47, 31, v46
	v_lshl_add_u64 v[44:45], v[42:43], 0, v[44:45]
	v_lshlrev_b64 v[164:165], 10, v[46:47]
	v_lshlrev_b64 v[46:47], 11, v[46:47]
	s_mov_b32 s45, m0
	s_mov_b32 m0, s41
	s_nop 0
	global_load_lds_dwordx4 v[44:45], off
	s_mov_b32 m0, s45
	v_lshl_add_u64 v[42:43], v[42:43], 0, v[46:47]
	s_lshl_b32 s43, s13, 12
	s_add_i32 s44, s41, 0x6000
	s_lshl_b32 s40, s40, 10
	s_mov_b32 s41, m0
	s_mov_b32 m0, s40
	s_nop 0
	global_load_lds_dwordx4 v[42:43], off
	s_mov_b32 m0, s41
	s_add_i32 s41, s43, 0x2000
	s_mov_b32 s45, m0
	s_mov_b32 m0, s41
	s_nop 0
	global_load_lds_dwordx4 v[34:35], off
	s_mov_b32 m0, s45
	s_add_i32 s45, s43, 0x2400
	s_mov_b32 s55, m0
	s_mov_b32 m0, s45
	s_nop 0
	global_load_lds_dwordx4 v[36:37], off
	s_mov_b32 m0, s55
	s_add_i32 s45, s43, 0x2800
	s_mov_b32 s55, m0
	s_mov_b32 m0, s45
	s_nop 0
	global_load_lds_dwordx4 v[38:39], off
	s_mov_b32 m0, s55
	s_add_i32 s45, s43, 0x2c00
	s_mov_b32 s55, m0
	s_mov_b32 m0, s45
	s_nop 0
	global_load_lds_dwordx4 v[40:41], off
	s_mov_b32 m0, s55
	v_lshl_add_u64 v[46:47], v[44:45], 0, 64
	s_mov_b32 s45, m0
	s_mov_b32 m0, s44
	s_nop 0
	global_load_lds_dwordx4 v[46:47], off
	s_mov_b32 m0, s45
	v_lshl_add_u64 v[48:49], v[42:43], 0, 64
	s_add_i32 s44, s40, 0x6000
	s_mov_b32 s45, m0
	s_mov_b32 m0, s44
	s_nop 0
	global_load_lds_dwordx4 v[48:49], off
	s_mov_b32 m0, s45
	v_lshrrev_b32_e32 v0, 2, v58
	s_mov_b32 s100, 0x10000
	s_mov_b32 s101, 0
	v_lshl_add_u64 v[50:51], v[34:35], 0, s[100:101]
	s_add_i32 s44, s43, 0x8000
	s_mov_b32 s45, m0
	s_mov_b32 m0, s44
	s_nop 0
	global_load_lds_dwordx4 v[50:51], off
	s_mov_b32 m0, s45
	v_sub_u32_e32 v0, 0, v0
	v_lshl_add_u64 v[52:53], v[36:37], 0, s[100:101]
	s_add_i32 s44, s43, 0x8400
	s_mov_b32 s45, m0
	s_mov_b32 m0, s44
	s_nop 0
	global_load_lds_dwordx4 v[52:53], off
	s_mov_b32 m0, s45
	v_bitop3_b32 v0, v59, v0, 3 bitop3:0x78
	s_and_b32 s12, s12, 0x3ffff80
	v_lshl_add_u64 v[54:55], v[38:39], 0, s[100:101]
	s_add_i32 s44, s43, 0x8800
	s_mov_b32 s45, m0
	s_mov_b32 m0, s44
	s_nop 0
	global_load_lds_dwordx4 v[54:55], off
	s_mov_b32 m0, s45
	v_lshlrev_b32_e32 v176, 4, v0
	v_or_b32_e32 v0, s12, v61
	v_lshl_add_u64 v[56:57], v[40:41], 0, s[100:101]
	s_add_i32 s43, s43, 0x8c00
	s_mov_b32 s44, m0
	s_mov_b32 m0, s43
	s_nop 0
	global_load_lds_dwordx4 v[56:57], off
	s_mov_b32 m0, s44
	v_lshlrev_b32_e32 v178, 6, v0
	v_bitop3_b32 v0, v58, 3, v60 bitop3:0x48
	s_mov_b32 s100, 0x20000
	v_lshl_add_u64 v[172:173], v[34:35], 0, s[100:101]
	v_lshlrev_b32_e32 v0, 4, v0
	v_mov_b32_e32 v34, 0
	s_lshl_b32 s55, s42, 12
	v_lshlrev_b32_e32 v177, 6, v61
	s_lshl_b32 s42, s13, 11
	v_lshl_add_u64 v[166:167], v[40:41], 0, s[100:101]
	v_lshl_add_u64 v[168:169], v[38:39], 0, s[100:101]
	v_lshl_add_u64 v[170:171], v[36:37], 0, s[100:101]
	v_lshl_add_u64 v[174:175], s[52:53], 0, v[0:1]
	s_mov_b64 s[12:13], 0
	s_mov_b32 s43, 0
	v_mov_b32_e32 v35, v34
	v_mov_b32_e32 v36, v34
	v_mov_b32_e32 v37, v34
	v_mov_b32_e32 v38, v34
	v_mov_b32_e32 v39, v34
	v_mov_b32_e32 v40, v34
	v_mov_b32_e32 v41, v34
	v_mov_b32_e32 v42, v34
	v_mov_b32_e32 v43, v34
	v_mov_b32_e32 v44, v34
	v_mov_b32_e32 v45, v34
	v_mov_b32_e32 v46, v34
	v_mov_b32_e32 v47, v34
	v_mov_b32_e32 v48, v34
	v_mov_b32_e32 v49, v34
	v_mov_b32_e32 v50, v34
	v_mov_b32_e32 v51, v34
	v_mov_b32_e32 v52, v34
	v_mov_b32_e32 v53, v34
	v_mov_b32_e32 v54, v34
	v_mov_b32_e32 v55, v34
	v_mov_b32_e32 v56, v34
	v_mov_b32_e32 v57, v34
	v_mov_b32_e32 v58, v34
	v_mov_b32_e32 v59, v34
	v_mov_b32_e32 v60, v34
	v_mov_b32_e32 v61, v34
	v_mov_b32_e32 v62, v34
	v_mov_b32_e32 v63, v34
	v_mov_b32_e32 v64, v34
	v_mov_b32_e32 v65, v34
	v_mov_b32_e32 v66, v34
	v_mov_b32_e32 v67, v34
	v_mov_b32_e32 v68, v34
	v_mov_b32_e32 v69, v34
	v_mov_b32_e32 v70, v34
	v_mov_b32_e32 v71, v34
	v_mov_b32_e32 v72, v34
	v_mov_b32_e32 v73, v34
	v_mov_b32_e32 v74, v34
	v_mov_b32_e32 v75, v34
	v_mov_b32_e32 v76, v34
	v_mov_b32_e32 v77, v34
	v_mov_b32_e32 v78, v34
	v_mov_b32_e32 v79, v34
	v_mov_b32_e32 v80, v34
	v_mov_b32_e32 v81, v34
	v_mov_b32_e32 v82, v34
	v_mov_b32_e32 v83, v34
	v_mov_b32_e32 v84, v34
	v_mov_b32_e32 v85, v34
	v_mov_b32_e32 v86, v34
	v_mov_b32_e32 v87, v34
	v_mov_b32_e32 v88, v34
	v_mov_b32_e32 v89, v34
	v_mov_b32_e32 v90, v34
	v_mov_b32_e32 v91, v34
	v_mov_b32_e32 v92, v34
	v_mov_b32_e32 v93, v34
	v_mov_b32_e32 v94, v34
	v_mov_b32_e32 v95, v34
	v_mov_b32_e32 v96, v34
	v_mov_b32_e32 v97, v34
	v_mov_b32_e32 v98, v34
	v_mov_b32_e32 v99, v34
	v_mov_b32_e32 v100, v34
	v_mov_b32_e32 v101, v34
	v_mov_b32_e32 v102, v34
	v_mov_b32_e32 v103, v34
	v_mov_b32_e32 v104, v34
	v_mov_b32_e32 v105, v34
	v_mov_b32_e32 v106, v34
	v_mov_b32_e32 v107, v34
	v_mov_b32_e32 v108, v34
	v_mov_b32_e32 v109, v34
	v_mov_b32_e32 v110, v34
	v_mov_b32_e32 v111, v34
	v_mov_b32_e32 v112, v34
	v_mov_b32_e32 v113, v34
	v_mov_b32_e32 v114, v34
	v_mov_b32_e32 v115, v34
	v_mov_b32_e32 v116, v34
	v_mov_b32_e32 v117, v34
	v_mov_b32_e32 v118, v34
	v_mov_b32_e32 v119, v34
	v_mov_b32_e32 v120, v34
	v_mov_b32_e32 v121, v34
	v_mov_b32_e32 v122, v34
	v_mov_b32_e32 v123, v34
	v_mov_b32_e32 v124, v34
	v_mov_b32_e32 v125, v34
	v_mov_b32_e32 v126, v34
	v_mov_b32_e32 v127, v34
	v_mov_b32_e32 v128, v34
	v_mov_b32_e32 v129, v34
	v_mov_b32_e32 v130, v34
	v_mov_b32_e32 v131, v34
	v_mov_b32_e32 v132, v34
	v_mov_b32_e32 v133, v34
	v_mov_b32_e32 v134, v34
	v_mov_b32_e32 v135, v34
	v_mov_b32_e32 v136, v34
	v_mov_b32_e32 v137, v34
	v_mov_b32_e32 v138, v34
	v_mov_b32_e32 v139, v34
	v_mov_b32_e32 v140, v34
	v_mov_b32_e32 v141, v34
	v_mov_b32_e32 v142, v34
	v_mov_b32_e32 v143, v34
	v_mov_b32_e32 v144, v34
	v_mov_b32_e32 v145, v34
	v_mov_b32_e32 v146, v34
	v_mov_b32_e32 v147, v34
	v_mov_b32_e32 v148, v34
	v_mov_b32_e32 v149, v34
	v_mov_b32_e32 v150, v34
	v_mov_b32_e32 v151, v34
	v_mov_b32_e32 v152, v34
	v_mov_b32_e32 v153, v34
	v_mov_b32_e32 v154, v34
	v_mov_b32_e32 v155, v34
	v_mov_b32_e32 v156, v34
	v_mov_b32_e32 v157, v34
	v_mov_b32_e32 v158, v34
	v_mov_b32_e32 v159, v34
	v_mov_b32_e32 v160, v34
	v_mov_b32_e32 v161, v34
.LBB0_30:
	s_mul_i32 s100, s12, 0x400
	s_mul_i32 s44, s43, 0x6000
	s_add_i32 s45, s44, 0xffffa000
	s_cmp_gt_i32 s43, 0
	s_waitcnt vmcnt(6)
	s_cselect_b32 s45, s45, 0xc000
	s_waitcnt lgkmcnt(0)
	s_barrier
	s_setprio 2
	v_add3_u32 v0, s44, v177, v176
	v_add_u32_e32 v0, s55, v0
	v_add3_u32 v212, s44, v178, v176
	ds_read_b128 v[196:199], v212 offset:8192
	ds_read_b128 v[180:183], v0
	ds_read_b128 v[184:187], v0 offset:1024
	ds_read_b128 v[188:191], v0 offset:2048
	ds_read_b128 v[192:195], v0 offset:3072
	ds_read_b128 v[200:203], v212 offset:9216
	ds_read_b128 v[204:207], v212 offset:10240
	ds_read_b128 v[208:211], v212 offset:11264
	ds_read_b128 v[216:219], v212 offset:12288
	ds_read_b128 v[226:229], v212 offset:13312
	ds_read_b128 v[230:233], v212 offset:14336
	ds_read_b128 v[234:237], v212 offset:15360
	v_lshl_add_u64 v[212:213], v[174:175], 0, s[12:13]
	v_lshl_add_u64 v[212:213], v[162:163], 1, v[212:213]
	s_add_i32 s68, s45, s42
	s_mov_b32 m0, s68
	s_nop 0
	global_load_lds_dwordx4 v[212:213], off
	v_lshl_add_u64 v[212:213], v[174:175], 0, s[12:13]
	v_lshl_add_u64 v[212:213], v[164:165], 1, v[212:213]
	s_add_i32 s68, s45, s40
	s_mov_b32 m0, s68
	s_nop 0
	global_load_lds_dwordx4 v[212:213], off
	s_add_i32 s45, s41, s45
	v_lshl_add_u64 v[212:213], v[172:173], 0, s[100:101]
	s_mov_b32 m0, s45
	s_nop 0
	global_load_lds_dwordx4 v[212:213], off
	v_lshl_add_u64 v[212:213], v[170:171], 0, s[100:101]
	s_add_i32 s68, s45, 0x400
	s_mov_b32 m0, s68
	s_nop 0
	global_load_lds_dwordx4 v[212:213], off
	v_lshl_add_u64 v[212:213], v[168:169], 0, s[100:101]
	s_add_i32 s68, s45, 0x800
	s_mov_b32 m0, s68
	s_nop 0
	global_load_lds_dwordx4 v[212:213], off
	s_addk_i32 s45, 0xc00
	v_lshl_add_u64 v[212:213], v[166:167], 0, s[100:101]
	s_mov_b32 m0, s45
	s_nop 0
	global_load_lds_dwordx4 v[212:213], off
	s_setprio 0
	s_waitcnt lgkmcnt(10)
	v_mfma_f32_16x16x32_bf16 v[34:37], v[196:199], v[180:183], v[34:37]
	s_waitcnt lgkmcnt(9)
	v_mfma_f32_16x16x32_bf16 v[38:41], v[196:199], v[184:187], v[38:41]
	s_waitcnt lgkmcnt(8)
	v_mfma_f32_16x16x32_bf16 v[42:45], v[196:199], v[188:191], v[42:45]
	s_waitcnt lgkmcnt(7)
	v_mfma_f32_16x16x32_bf16 v[46:49], v[196:199], v[192:195], v[46:49]
	s_waitcnt lgkmcnt(6)
	v_mfma_f32_16x16x32_bf16 v[50:53], v[200:203], v[180:183], v[50:53]
	v_mfma_f32_16x16x32_bf16 v[54:57], v[200:203], v[184:187], v[54:57]
	v_mfma_f32_16x16x32_bf16 v[58:61], v[200:203], v[188:191], v[58:61]
	v_mfma_f32_16x16x32_bf16 v[62:65], v[200:203], v[192:195], v[62:65]
	s_waitcnt lgkmcnt(5)
	v_mfma_f32_16x16x32_bf16 v[66:69], v[204:207], v[180:183], v[66:69]
	v_mfma_f32_16x16x32_bf16 v[70:73], v[204:207], v[184:187], v[70:73]
	v_mfma_f32_16x16x32_bf16 v[74:77], v[204:207], v[188:191], v[74:77]
	v_mfma_f32_16x16x32_bf16 v[78:81], v[204:207], v[192:195], v[78:81]
	s_waitcnt lgkmcnt(4)
	v_mfma_f32_16x16x32_bf16 v[82:85], v[208:211], v[180:183], v[82:85]
	v_mfma_f32_16x16x32_bf16 v[86:89], v[208:211], v[184:187], v[86:89]
	v_mfma_f32_16x16x32_bf16 v[90:93], v[208:211], v[188:191], v[90:93]
	v_mfma_f32_16x16x32_bf16 v[94:97], v[208:211], v[192:195], v[94:97]
	s_waitcnt lgkmcnt(3)
	v_mfma_f32_16x16x32_bf16 v[98:101], v[216:219], v[180:183], v[98:101]
	v_mfma_f32_16x16x32_bf16 v[102:105], v[216:219], v[184:187], v[102:105]
	v_mfma_f32_16x16x32_bf16 v[106:109], v[216:219], v[188:191], v[106:109]
	v_mfma_f32_16x16x32_bf16 v[110:113], v[216:219], v[192:195], v[110:113]
	s_waitcnt lgkmcnt(2)
	v_mfma_f32_16x16x32_bf16 v[114:117], v[226:229], v[180:183], v[114:117]
	v_mfma_f32_16x16x32_bf16 v[118:121], v[226:229], v[184:187], v[118:121]
	v_mfma_f32_16x16x32_bf16 v[122:125], v[226:229], v[188:191], v[122:125]
	v_mfma_f32_16x16x32_bf16 v[126:129], v[226:229], v[192:195], v[126:129]
	s_waitcnt lgkmcnt(1)
	v_mfma_f32_16x16x32_bf16 v[130:133], v[230:233], v[180:183], v[130:133]
	v_mfma_f32_16x16x32_bf16 v[134:137], v[230:233], v[184:187], v[134:137]
	v_mfma_f32_16x16x32_bf16 v[138:141], v[230:233], v[188:191], v[138:141]
	v_mfma_f32_16x16x32_bf16 v[142:145], v[230:233], v[192:195], v[142:145]
	s_waitcnt lgkmcnt(0)
	v_mfma_f32_16x16x32_bf16 v[146:149], v[234:237], v[180:183], v[146:149]
	v_mfma_f32_16x16x32_bf16 v[150:153], v[234:237], v[184:187], v[150:153]
	v_mfma_f32_16x16x32_bf16 v[154:157], v[234:237], v[188:191], v[154:157]
	v_mfma_f32_16x16x32_bf16 v[158:161], v[234:237], v[192:195], v[158:161]
	s_add_i32 s44, s43, 1
	s_cmp_lg_u32 s43, 2
	s_cselect_b32 s43, s44, 0
	s_add_u32 s12, s12, 64
	s_addc_u32 s13, s13, 0
	s_cmpk_eq_i32 s12, 0x780
	s_cbranch_scc0 .LBB0_30
	s_waitcnt vmcnt(6)
	v_mov_b32_e32 v162, v23
	v_mov_b32_e32 v163, v24
	v_mov_b32_e32 v23, v25
	v_mov_b32_e32 v164, v7
	v_mov_b32_e32 v165, v8
	v_pk_add_f32 v[22:23], v[162:163], v[22:23]
	v_mov_b32_e32 v7, v9
	v_pk_add_f32 v[6:7], v[164:165], v[6:7]
	v_add_f32_e32 v0, v22, v23
	v_add_f32_e32 v0, v0, v6
	v_add_f32_e32 v0, v0, v7
	v_fmamk_f32 v0, v0, 0x3a800000, v250
	s_mov_b32 s12, 0x800000
	s_waitcnt vmcnt(4)
	v_mov_b32_e32 v166, v19
	v_mov_b32_e32 v167, v20
	v_mov_b32_e32 v168, v3
	v_mul_f32_e32 v3, 0x4b800000, v0
	v_cmp_gt_f32_e32 vcc, s12, v0
	v_mov_b32_e32 v19, v21
	v_mov_b32_e32 v169, v4
	v_cndmask_b32_e32 v0, v0, v3, vcc
	v_pk_add_f32 v[6:7], v[166:167], v[18:19]
	v_mov_b32_e32 v3, v5
	v_pk_add_f32 v[2:3], v[168:169], v[2:3]
	v_add_f32_e32 v4, v6, v7
	v_add_f32_e32 v2, v4, v2
	v_add_f32_e32 v2, v2, v3
	v_fmamk_f32 v2, v2, 0x3a800000, v250
	v_mul_f32_e32 v3, 0x4b800000, v2
	v_cmp_gt_f32_e64 s[40:41], s12, v2
	s_waitcnt vmcnt(2)
	v_mov_b32_e32 v170, v27
	v_mov_b32_e32 v171, v28
	v_cndmask_b32_e64 v2, v2, v3, s[40:41]
	v_mov_b32_e32 v27, v29
	v_mov_b32_e32 v172, v11
	v_mov_b32_e32 v173, v12
	v_rsq_f32_e32 v179, v2
	v_pk_add_f32 v[2:3], v[170:171], v[26:27]
	v_mov_b32_e32 v11, v13
	v_pk_add_f32 v[4:5], v[172:173], v[10:11]
	v_add_f32_e32 v2, v2, v3
	v_add_f32_e32 v2, v2, v4
	v_add_f32_e32 v2, v2, v5
	v_fmamk_f32 v2, v2, 0x3a800000, v250
	v_mul_f32_e32 v3, 0x4b800000, v2
	v_cmp_gt_f32_e64 s[42:43], s12, v2
	s_waitcnt vmcnt(0)
	v_mov_b32_e32 v174, v31
	v_mov_b32_e32 v175, v32
	v_cndmask_b32_e64 v2, v2, v3, s[42:43]
	v_mov_b32_e32 v31, v33
	v_mov_b32_e32 v180, v15
	v_mov_b32_e32 v181, v16
	v_rsq_f32_e32 v182, v2
	v_pk_add_f32 v[2:3], v[174:175], v[30:31]
	v_mov_b32_e32 v15, v17
	v_pk_add_f32 v[4:5], v[180:181], v[14:15]
	v_add_f32_e32 v2, v2, v3
	v_add_f32_e32 v2, v2, v4
	v_add_f32_e32 v2, v2, v5
	v_fmamk_f32 v2, v2, 0x3a800000, v250
	v_mul_f32_e32 v3, 0x4b800000, v2
	v_cmp_gt_f32_e64 s[44:45], s12, v2
	s_waitcnt vmcnt(6)
	v_add_u32_e32 v183, v178, v176
	s_waitcnt lgkmcnt(0)
	s_barrier
	v_cndmask_b32_e64 v2, v2, v3, s[44:45]
	v_rsq_f32_e32 v180, v2
	ds_read_b128 v[2:5], v183 offset:15360
	ds_read_b128 v[6:9], v183 offset:14336
	ds_read_b128 v[10:13], v183 offset:13312
	ds_read_b128 v[14:17], v183 offset:12288
	ds_read_b128 v[18:21], v183 offset:11264
	ds_read_b128 v[22:25], v183 offset:10240
	ds_read_b128 v[26:29], v183 offset:9216
	ds_read_b128 v[30:33], v183 offset:8192
	v_add3_u32 v178, s55, v177, v176
	ds_read_b128 v[162:165], v178 offset:3072
	ds_read_b128 v[166:169], v178 offset:2048
	ds_read_b128 v[170:173], v178 offset:1024
	ds_read_b128 v[174:177], v178
	v_rsq_f32_e32 v0, v0
	v_mul_f32_e32 v184, 0x45800000, v179
	v_mul_f32_e32 v185, 0x45800000, v182
	v_mul_f32_e32 v186, 0x45800000, v180
	v_mul_f32_e32 v181, 0x45800000, v0
	s_waitcnt lgkmcnt(0)
	v_mfma_f32_16x16x32_bf16 v[34:37], v[30:33], v[174:177], v[34:37]
	v_mfma_f32_16x16x32_bf16 v[38:41], v[30:33], v[170:173], v[38:41]
	v_mfma_f32_16x16x32_bf16 v[42:45], v[30:33], v[166:169], v[42:45]
	v_mfma_f32_16x16x32_bf16 v[30:33], v[30:33], v[162:165], v[46:49]
	v_mfma_f32_16x16x32_bf16 v[46:49], v[26:29], v[174:177], v[50:53]
	v_mfma_f32_16x16x32_bf16 v[50:53], v[26:29], v[170:173], v[54:57]
	v_mfma_f32_16x16x32_bf16 v[54:57], v[26:29], v[166:169], v[58:61]
	v_mfma_f32_16x16x32_bf16 v[58:61], v[26:29], v[162:165], v[62:65]
	v_mfma_f32_16x16x32_bf16 v[62:65], v[22:25], v[174:177], v[66:69]
	v_mfma_f32_16x16x32_bf16 v[66:69], v[22:25], v[170:173], v[70:73]
	v_mfma_f32_16x16x32_bf16 v[70:73], v[22:25], v[166:169], v[74:77]
	v_mfma_f32_16x16x32_bf16 v[74:77], v[22:25], v[162:165], v[78:81]
	v_mfma_f32_16x16x32_bf16 v[78:81], v[18:21], v[174:177], v[82:85]
	v_mfma_f32_16x16x32_bf16 v[82:85], v[18:21], v[170:173], v[86:89]
	v_mfma_f32_16x16x32_bf16 v[86:89], v[18:21], v[166:169], v[90:93]
	v_mfma_f32_16x16x32_bf16 v[18:21], v[18:21], v[162:165], v[94:97]
	v_mfma_f32_16x16x32_bf16 v[90:93], v[14:17], v[174:177], v[98:101]
	v_mfma_f32_16x16x32_bf16 v[94:97], v[14:17], v[170:173], v[102:105]
	v_mfma_f32_16x16x32_bf16 v[98:101], v[14:17], v[166:169], v[106:109]
	v_mfma_f32_16x16x32_bf16 v[14:17], v[14:17], v[162:165], v[110:113]
	v_mfma_f32_16x16x32_bf16 v[102:105], v[10:13], v[174:177], v[114:117]
	v_mfma_f32_16x16x32_bf16 v[106:109], v[10:13], v[170:173], v[118:121]
	v_mfma_f32_16x16x32_bf16 v[110:113], v[10:13], v[166:169], v[122:125]
	v_mfma_f32_16x16x32_bf16 v[10:13], v[10:13], v[162:165], v[126:129]
	v_mfma_f32_16x16x32_bf16 v[114:117], v[6:9], v[174:177], v[130:133]
	v_mfma_f32_16x16x32_bf16 v[118:121], v[6:9], v[170:173], v[134:137]
	v_mfma_f32_16x16x32_bf16 v[122:125], v[6:9], v[166:169], v[138:141]
	v_mfma_f32_16x16x32_bf16 v[6:9], v[6:9], v[162:165], v[142:145]
	v_mfma_f32_16x16x32_bf16 v[126:129], v[2:5], v[174:177], v[146:149]
	v_mfma_f32_16x16x32_bf16 v[130:133], v[2:5], v[170:173], v[150:153]
	v_mfma_f32_16x16x32_bf16 v[134:137], v[2:5], v[166:169], v[154:157]
	v_mfma_f32_16x16x32_bf16 v[2:5], v[2:5], v[162:165], v[158:161]
	s_waitcnt vmcnt(0)
	v_cndmask_b32_e32 v26, v0, v181, vcc
	v_cndmask_b32_e64 v24, v179, v184, s[40:41]
	v_cndmask_b32_e64 v22, v182, v185, s[42:43]
	v_cndmask_b32_e64 v0, v180, v186, s[44:45]
	s_waitcnt lgkmcnt(0)
	s_barrier
	ds_read_b128 v[138:141], v178 offset:24576
	ds_read_b128 v[142:145], v178 offset:25600
	ds_read_b128 v[146:149], v178 offset:26624
	ds_read_b128 v[150:153], v178 offset:27648
	ds_read_b128 v[154:157], v183 offset:32768
	ds_read_b128 v[158:161], v183 offset:33792
	ds_read_b128 v[162:165], v183 offset:34816
	ds_read_b128 v[166:169], v183 offset:35840
	ds_read_b128 v[170:173], v183 offset:36864
	ds_read_b128 v[174:177], v183 offset:37888
	ds_read_b128 v[178:181], v183 offset:38912
	ds_read_b128 v[182:185], v183 offset:39936
	s_waitcnt lgkmcnt(7)
	v_mfma_f32_16x16x32_bf16 v[34:37], v[154:157], v[138:141], v[34:37]
	v_mfma_f32_16x16x32_bf16 v[38:41], v[154:157], v[142:145], v[38:41]
	v_mfma_f32_16x16x32_bf16 v[42:45], v[154:157], v[146:149], v[42:45]
	v_mfma_f32_16x16x32_bf16 v[28:31], v[154:157], v[150:153], v[30:33]
	s_waitcnt lgkmcnt(6)
	v_mfma_f32_16x16x32_bf16 v[46:49], v[158:161], v[138:141], v[46:49]
	v_mfma_f32_16x16x32_bf16 v[50:53], v[158:161], v[142:145], v[50:53]
	v_mfma_f32_16x16x32_bf16 v[54:57], v[158:161], v[146:149], v[54:57]
	v_mfma_f32_16x16x32_bf16 v[58:61], v[158:161], v[150:153], v[58:61]
	s_waitcnt lgkmcnt(5)
	v_mfma_f32_16x16x32_bf16 v[62:65], v[162:165], v[138:141], v[62:65]
	v_mfma_f32_16x16x32_bf16 v[66:69], v[162:165], v[142:145], v[66:69]
	v_mfma_f32_16x16x32_bf16 v[70:73], v[162:165], v[146:149], v[70:73]
	v_mfma_f32_16x16x32_bf16 v[74:77], v[162:165], v[150:153], v[74:77]
	s_waitcnt lgkmcnt(4)
	v_mfma_f32_16x16x32_bf16 v[78:81], v[166:169], v[138:141], v[78:81]
	v_mfma_f32_16x16x32_bf16 v[82:85], v[166:169], v[142:145], v[82:85]
	v_mfma_f32_16x16x32_bf16 v[86:89], v[166:169], v[146:149], v[86:89]
	v_mfma_f32_16x16x32_bf16 v[154:157], v[166:169], v[150:153], v[18:21]
	s_waitcnt lgkmcnt(3)
	v_mfma_f32_16x16x32_bf16 v[90:93], v[170:173], v[138:141], v[90:93]
	v_mfma_f32_16x16x32_bf16 v[94:97], v[170:173], v[142:145], v[94:97]
	v_mfma_f32_16x16x32_bf16 v[98:101], v[170:173], v[146:149], v[98:101]
	v_mfma_f32_16x16x32_bf16 v[158:161], v[170:173], v[150:153], v[14:17]
	s_waitcnt lgkmcnt(2)
	v_mfma_f32_16x16x32_bf16 v[102:105], v[174:177], v[138:141], v[102:105]
	v_mfma_f32_16x16x32_bf16 v[106:109], v[174:177], v[142:145], v[106:109]
	v_mfma_f32_16x16x32_bf16 v[110:113], v[174:177], v[146:149], v[110:113]
	v_mfma_f32_16x16x32_bf16 v[162:165], v[174:177], v[150:153], v[10:13]
	s_waitcnt lgkmcnt(1)
	v_mfma_f32_16x16x32_bf16 v[114:117], v[178:181], v[138:141], v[114:117]
	v_mfma_f32_16x16x32_bf16 v[118:121], v[178:181], v[142:145], v[118:121]
	v_mfma_f32_16x16x32_bf16 v[122:125], v[178:181], v[146:149], v[122:125]
	v_mfma_f32_16x16x32_bf16 v[18:21], v[178:181], v[150:153], v[6:9]
	s_waitcnt lgkmcnt(0)
	v_mfma_f32_16x16x32_bf16 v[14:17], v[182:185], v[138:141], v[126:129]
	v_mfma_f32_16x16x32_bf16 v[10:13], v[182:185], v[142:145], v[130:133]
	v_mfma_f32_16x16x32_bf16 v[6:9], v[182:185], v[146:149], v[134:137]
	v_mfma_f32_16x16x32_bf16 v[2:5], v[182:185], v[150:153], v[2:5]
	v_mov_b32_e32 v23, v224
	s_movk_i32 s12, 0x210
	v_lshrrev_b32_e32 v32, 1, v23
	v_and_b32_e32 v27, 0x7fffff80, v23
	v_and_b32_e32 v32, 24, v32
	v_and_b32_e32 v25, 0x4f, v23
	v_lshl_or_b32 v27, v27, 1, v32
	v_pk_mul_f32 v[32:33], v[26:27], v[34:35] op_sel_hi:[0,1]
	v_pk_mul_f32 v[34:35], v[26:27], v[36:37] op_sel_hi:[0,1]
	v_mad_u32_u24 v25, v25, s12, v27
	v_cvt_pk_bf16_f32 v32, v32, v33
	v_cvt_pk_bf16_f32 v33, v34, v35
	v_pk_mul_f32 v[34:35], v[24:25], v[38:39] op_sel_hi:[0,1]
	v_pk_mul_f32 v[36:37], v[24:25], v[40:41] op_sel_hi:[0,1]
	v_cvt_pk_bf16_f32 v34, v34, v35
	v_cvt_pk_bf16_f32 v35, v36, v37
	v_pk_mul_f32 v[36:37], v[22:23], v[42:43] op_sel_hi:[0,1]
	v_pk_mul_f32 v[38:39], v[22:23], v[44:45] op_sel_hi:[0,1]
	v_pk_mul_f32 v[28:29], v[0:1], v[28:29] op_sel_hi:[0,1]
	v_pk_mul_f32 v[30:31], v[0:1], v[30:31] op_sel_hi:[0,1]
	v_cvt_pk_bf16_f32 v36, v36, v37
	v_cvt_pk_bf16_f32 v37, v38, v39
	v_cvt_pk_bf16_f32 v28, v28, v29
	v_cvt_pk_bf16_f32 v29, v30, v31
	v_pk_mul_f32 v[30:31], v[26:27], v[46:47] op_sel_hi:[0,1]
	v_pk_mul_f32 v[38:39], v[26:27], v[48:49] op_sel_hi:[0,1]
	v_cvt_pk_bf16_f32 v30, v30, v31
	v_cvt_pk_bf16_f32 v31, v38, v39
	s_barrier
	ds_write2_b64 v25, v[32:33], v[30:31] offset1:4
	v_pk_mul_f32 v[30:31], v[24:25], v[50:51] op_sel_hi:[0,1]
	v_pk_mul_f32 v[32:33], v[24:25], v[52:53] op_sel_hi:[0,1]
	v_cvt_pk_bf16_f32 v30, v30, v31
	v_cvt_pk_bf16_f32 v31, v32, v33
	v_add_u32_e32 v27, 0x2000, v25
	ds_write2_b64 v27, v[34:35], v[30:31] offset0:32 offset1:36
	v_pk_mul_f32 v[30:31], v[22:23], v[54:55] op_sel_hi:[0,1]
	v_pk_mul_f32 v[32:33], v[22:23], v[56:57] op_sel_hi:[0,1]
	v_cvt_pk_bf16_f32 v30, v30, v31
	v_cvt_pk_bf16_f32 v31, v32, v33
	v_add_u32_e32 v40, 0x4000, v25
	ds_write2_b64 v40, v[36:37], v[30:31] offset0:64 offset1:68
	v_pk_mul_f32 v[30:31], v[0:1], v[58:59] op_sel_hi:[0,1]
	v_pk_mul_f32 v[32:33], v[0:1], v[60:61] op_sel_hi:[0,1]
	v_cvt_pk_bf16_f32 v30, v30, v31
	v_cvt_pk_bf16_f32 v31, v32, v33
	v_add_u32_e32 v41, 0x6000, v25
	ds_write2_b64 v41, v[28:29], v[30:31] offset0:96 offset1:100
	v_pk_mul_f32 v[28:29], v[26:27], v[62:63] op_sel_hi:[0,1]
	v_pk_mul_f32 v[30:31], v[26:27], v[64:65] op_sel_hi:[0,1]
	v_cvt_pk_bf16_f32 v28, v28, v29
	v_cvt_pk_bf16_f32 v29, v30, v31
	v_pk_mul_f32 v[30:31], v[24:25], v[66:67] op_sel_hi:[0,1]
	v_pk_mul_f32 v[32:33], v[24:25], v[68:69] op_sel_hi:[0,1]
	v_cvt_pk_bf16_f32 v30, v30, v31
	v_cvt_pk_bf16_f32 v31, v32, v33
	v_pk_mul_f32 v[32:33], v[22:23], v[70:71] op_sel_hi:[0,1]
	v_pk_mul_f32 v[34:35], v[22:23], v[72:73] op_sel_hi:[0,1]
	v_cvt_pk_bf16_f32 v32, v32, v33
	v_cvt_pk_bf16_f32 v33, v34, v35
	v_pk_mul_f32 v[34:35], v[0:1], v[74:75] op_sel_hi:[0,1]
	v_pk_mul_f32 v[36:37], v[0:1], v[76:77] op_sel_hi:[0,1]
	v_cvt_pk_bf16_f32 v34, v34, v35
	v_cvt_pk_bf16_f32 v35, v36, v37
	v_pk_mul_f32 v[36:37], v[26:27], v[78:79] op_sel_hi:[0,1]
	v_pk_mul_f32 v[38:39], v[26:27], v[80:81] op_sel_hi:[0,1]
	v_cvt_pk_bf16_f32 v36, v36, v37
	v_cvt_pk_bf16_f32 v37, v38, v39
	ds_write2_b64 v25, v[28:29], v[36:37] offset0:8 offset1:12
	v_pk_mul_f32 v[28:29], v[24:25], v[82:83] op_sel_hi:[0,1]
	v_pk_mul_f32 v[36:37], v[24:25], v[84:85] op_sel_hi:[0,1]
	v_cvt_pk_bf16_f32 v28, v28, v29
	v_cvt_pk_bf16_f32 v29, v36, v37
	ds_write2_b64 v27, v[30:31], v[28:29] offset0:40 offset1:44
	v_pk_mul_f32 v[28:29], v[22:23], v[86:87] op_sel_hi:[0,1]
	v_pk_mul_f32 v[30:31], v[22:23], v[88:89] op_sel_hi:[0,1]
	v_cvt_pk_bf16_f32 v28, v28, v29
	v_cvt_pk_bf16_f32 v29, v30, v31
	ds_write2_b64 v40, v[32:33], v[28:29] offset0:72 offset1:76
	v_pk_mul_f32 v[28:29], v[0:1], v[154:155] op_sel_hi:[0,1]
	v_pk_mul_f32 v[30:31], v[0:1], v[156:157] op_sel_hi:[0,1]
	v_cvt_pk_bf16_f32 v28, v28, v29
	v_cvt_pk_bf16_f32 v29, v30, v31
	ds_write2_b64 v41, v[34:35], v[28:29] offset0:104 offset1:108
	v_pk_mul_f32 v[28:29], v[26:27], v[90:91] op_sel_hi:[0,1]
	v_pk_mul_f32 v[30:31], v[26:27], v[92:93] op_sel_hi:[0,1]
	v_cvt_pk_bf16_f32 v28, v28, v29
	v_cvt_pk_bf16_f32 v29, v30, v31
	v_pk_mul_f32 v[30:31], v[24:25], v[94:95] op_sel_hi:[0,1]
	v_pk_mul_f32 v[32:33], v[24:25], v[96:97] op_sel_hi:[0,1]
	v_cvt_pk_bf16_f32 v30, v30, v31
	v_cvt_pk_bf16_f32 v31, v32, v33
	v_pk_mul_f32 v[32:33], v[22:23], v[98:99] op_sel_hi:[0,1]
	v_pk_mul_f32 v[34:35], v[22:23], v[100:101] op_sel_hi:[0,1]
	v_cvt_pk_bf16_f32 v32, v32, v33
	v_cvt_pk_bf16_f32 v33, v34, v35
	v_pk_mul_f32 v[34:35], v[0:1], v[158:159] op_sel_hi:[0,1]
	v_pk_mul_f32 v[36:37], v[0:1], v[160:161] op_sel_hi:[0,1]
	v_cvt_pk_bf16_f32 v34, v34, v35
	v_cvt_pk_bf16_f32 v35, v36, v37
	v_pk_mul_f32 v[36:37], v[26:27], v[102:103] op_sel_hi:[0,1]
	v_pk_mul_f32 v[38:39], v[26:27], v[104:105] op_sel_hi:[0,1]
	v_cvt_pk_bf16_f32 v36, v36, v37
	v_cvt_pk_bf16_f32 v37, v38, v39
	ds_write2_b64 v25, v[28:29], v[36:37] offset0:16 offset1:20
	v_pk_mul_f32 v[28:29], v[24:25], v[106:107] op_sel_hi:[0,1]
	v_pk_mul_f32 v[36:37], v[24:25], v[108:109] op_sel_hi:[0,1]
	v_cvt_pk_bf16_f32 v28, v28, v29
	v_cvt_pk_bf16_f32 v29, v36, v37
	ds_write2_b64 v27, v[30:31], v[28:29] offset0:48 offset1:52
	v_pk_mul_f32 v[28:29], v[22:23], v[110:111] op_sel_hi:[0,1]
	v_pk_mul_f32 v[30:31], v[22:23], v[112:113] op_sel_hi:[0,1]
	v_cvt_pk_bf16_f32 v28, v28, v29
	v_cvt_pk_bf16_f32 v29, v30, v31
	ds_write2_b64 v40, v[32:33], v[28:29] offset0:80 offset1:84
	v_pk_mul_f32 v[28:29], v[0:1], v[162:163] op_sel_hi:[0,1]
	v_pk_mul_f32 v[30:31], v[0:1], v[164:165] op_sel_hi:[0,1]
	v_cvt_pk_bf16_f32 v28, v28, v29
	v_cvt_pk_bf16_f32 v29, v30, v31
	ds_write2_b64 v41, v[34:35], v[28:29] offset0:112 offset1:116
	v_pk_mul_f32 v[28:29], v[26:27], v[114:115] op_sel_hi:[0,1]
	v_pk_mul_f32 v[30:31], v[26:27], v[116:117] op_sel_hi:[0,1]
	v_pk_mul_f32 v[18:19], v[0:1], v[18:19] op_sel_hi:[0,1]
	v_pk_mul_f32 v[20:21], v[0:1], v[20:21] op_sel_hi:[0,1]
	v_pk_mul_f32 v[2:3], v[0:1], v[2:3] op_sel_hi:[0,1]
	v_pk_mul_f32 v[4:5], v[0:1], v[4:5] op_sel_hi:[0,1]
	v_lshlrev_b32_e32 v0, 3, v23
	v_cvt_pk_bf16_f32 v28, v28, v29
	v_cvt_pk_bf16_f32 v29, v30, v31
	v_pk_mul_f32 v[30:31], v[24:25], v[118:119] op_sel_hi:[0,1]
	v_pk_mul_f32 v[32:33], v[24:25], v[120:121] op_sel_hi:[0,1]
	v_cvt_pk_bf16_f32 v18, v18, v19
	v_cvt_pk_bf16_f32 v19, v20, v21
	v_cvt_pk_bf16_f32 v2, v2, v3
	v_cvt_pk_bf16_f32 v3, v4, v5
	v_and_b32_e32 v0, 0xf8, v0
	v_cvt_pk_bf16_f32 v30, v30, v31
	v_cvt_pk_bf16_f32 v31, v32, v33
	v_pk_mul_f32 v[32:33], v[22:23], v[122:123] op_sel_hi:[0,1]
	v_pk_mul_f32 v[34:35], v[22:23], v[124:125] op_sel_hi:[0,1]
	v_pk_mul_f32 v[14:15], v[26:27], v[14:15] op_sel_hi:[0,1]
	v_pk_mul_f32 v[16:17], v[26:27], v[16:17] op_sel_hi:[0,1]
	v_pk_mul_f32 v[10:11], v[24:25], v[10:11] op_sel_hi:[0,1]
	v_pk_mul_f32 v[12:13], v[24:25], v[12:13] op_sel_hi:[0,1]
	v_pk_mul_f32 v[6:7], v[22:23], v[6:7] op_sel_hi:[0,1]
	v_pk_mul_f32 v[8:9], v[22:23], v[8:9] op_sel_hi:[0,1]
	ds_write2_b64 v41, v[18:19], v[2:3] offset0:120 offset1:124
	v_or_b32_e32 v2, s54, v0
	s_movk_i32 s12, 0x400
	v_cvt_pk_bf16_f32 v32, v32, v33
	v_cvt_pk_bf16_f32 v33, v34, v35
	v_cvt_pk_bf16_f32 v14, v14, v15
	v_cvt_pk_bf16_f32 v15, v16, v17
	v_cvt_pk_bf16_f32 v10, v10, v11
	v_cvt_pk_bf16_f32 v11, v12, v13
	v_cvt_pk_bf16_f32 v6, v6, v7
	v_cvt_pk_bf16_f32 v7, v8, v9
	v_cmp_gt_i32_e32 vcc, s12, v2
	ds_write2_b64 v25, v[28:29], v[14:15] offset0:24 offset1:28
	ds_write2_b64 v27, v[30:31], v[10:11] offset0:56 offset1:60
	ds_write2_b64 v40, v[32:33], v[6:7] offset0:88 offset1:92
	s_waitcnt lgkmcnt(0)
	s_barrier
	s_and_saveexec_b64 s[12:13], vcc
	s_cbranch_execz .LBB0_28
	v_ashrrev_i32_e32 v8, 5, v23
	v_lshlrev_b32_e32 v0, 1, v0
	s_movk_i32 s40, 0x210
	v_mad_u64_u32 v[6:7], s[40:41], v8, s40, v[0:1]
	v_add_u32_e32 v8, s57, v8
	ds_read_b128 v[2:5], v6
	v_ashrrev_i32_e32 v9, 31, v8
	s_ashr_i32 s55, s54, 31
	v_lshlrev_b64 v[10:11], 11, v[8:9]
	v_lshl_add_u64 v[10:11], s[4:5], 0, v[10:11]
	s_lshl_b64 s[40:41], s[54:55], 1
	v_lshl_add_u64 v[10:11], v[10:11], 0, s[40:41]
	v_lshl_add_u64 v[10:11], v[10:11], 0, v[0:1]
	s_waitcnt lgkmcnt(0)
	global_store_dwordx4 v[10:11], v[2:5], off
	v_add_u32_e32 v10, 8, v8
	ds_read_b128 v[2:5], v6 offset:4224
	v_ashrrev_i32_e32 v11, 31, v10
	v_lshlrev_b64 v[10:11], 11, v[10:11]
	v_lshl_add_u64 v[10:11], s[4:5], 0, v[10:11]
	v_lshl_add_u64 v[10:11], v[10:11], 0, s[40:41]
	v_lshl_add_u64 v[10:11], v[10:11], 0, v[0:1]
	s_waitcnt lgkmcnt(0)
	global_store_dwordx4 v[10:11], v[2:5], off
	v_add_u32_e32 v10, 16, v8
	ds_read_b128 v[2:5], v6 offset:8448
	v_ashrrev_i32_e32 v11, 31, v10
	v_lshlrev_b64 v[10:11], 11, v[10:11]
	v_lshl_add_u64 v[10:11], s[4:5], 0, v[10:11]
	v_lshl_add_u64 v[10:11], v[10:11], 0, s[40:41]
	v_lshl_add_u64 v[10:11], v[10:11], 0, v[0:1]
	s_waitcnt lgkmcnt(0)
	global_store_dwordx4 v[10:11], v[2:5], off
	v_add_u32_e32 v10, 24, v8
	ds_read_b128 v[2:5], v6 offset:12672
	v_ashrrev_i32_e32 v11, 31, v10
	v_lshlrev_b64 v[10:11], 11, v[10:11]
	v_lshl_add_u64 v[10:11], s[4:5], 0, v[10:11]
	v_lshl_add_u64 v[10:11], v[10:11], 0, s[40:41]
	v_lshl_add_u64 v[10:11], v[10:11], 0, v[0:1]
	s_waitcnt lgkmcnt(0)
	global_store_dwordx4 v[10:11], v[2:5], off
	v_add_u32_e32 v10, 32, v8
	ds_read_b128 v[2:5], v6 offset:16896
	v_ashrrev_i32_e32 v11, 31, v10
	v_lshlrev_b64 v[10:11], 11, v[10:11]
	v_lshl_add_u64 v[10:11], s[4:5], 0, v[10:11]
	v_lshl_add_u64 v[10:11], v[10:11], 0, s[40:41]
	v_lshl_add_u64 v[10:11], v[10:11], 0, v[0:1]
	s_waitcnt lgkmcnt(0)
	global_store_dwordx4 v[10:11], v[2:5], off
	v_add_u32_e32 v10, 40, v8
	ds_read_b128 v[2:5], v6 offset:21120
	v_ashrrev_i32_e32 v11, 31, v10
	v_lshlrev_b64 v[10:11], 11, v[10:11]
	v_lshl_add_u64 v[10:11], s[4:5], 0, v[10:11]
	v_lshl_add_u64 v[10:11], v[10:11], 0, s[40:41]
	v_lshl_add_u64 v[10:11], v[10:11], 0, v[0:1]
	s_waitcnt lgkmcnt(0)
	global_store_dwordx4 v[10:11], v[2:5], off
	v_add_u32_e32 v10, 48, v8
	ds_read_b128 v[2:5], v6 offset:25344
	v_ashrrev_i32_e32 v11, 31, v10
	v_lshlrev_b64 v[10:11], 11, v[10:11]
	v_lshl_add_u64 v[10:11], s[4:5], 0, v[10:11]
	v_lshl_add_u64 v[10:11], v[10:11], 0, s[40:41]
	v_lshl_add_u64 v[10:11], v[10:11], 0, v[0:1]
	s_waitcnt lgkmcnt(0)
	global_store_dwordx4 v[10:11], v[2:5], off
	v_add_u32_e32 v10, 56, v8
	ds_read_b128 v[2:5], v6 offset:29568
	v_ashrrev_i32_e32 v11, 31, v10
	v_lshlrev_b64 v[10:11], 11, v[10:11]
	v_lshl_add_u64 v[10:11], s[4:5], 0, v[10:11]
	v_lshl_add_u64 v[10:11], v[10:11], 0, s[40:41]
	v_lshl_add_u64 v[10:11], v[10:11], 0, v[0:1]
	s_waitcnt lgkmcnt(0)
	global_store_dwordx4 v[10:11], v[2:5], off
	v_add_u32_e32 v10, 64, v8
	ds_read_b128 v[2:5], v6 offset:33792
	v_ashrrev_i32_e32 v11, 31, v10
	v_lshlrev_b64 v[10:11], 11, v[10:11]
	v_lshl_add_u64 v[10:11], s[4:5], 0, v[10:11]
	v_lshl_add_u64 v[10:11], v[10:11], 0, s[40:41]
	v_lshl_add_u64 v[10:11], v[10:11], 0, v[0:1]
	s_waitcnt lgkmcnt(0)
	global_store_dwordx4 v[10:11], v[2:5], off
	v_add_u32_e32 v10, 0x48, v8
	ds_read_b128 v[2:5], v6 offset:38016
	v_ashrrev_i32_e32 v11, 31, v10
	v_lshlrev_b64 v[10:11], 11, v[10:11]
	v_lshl_add_u64 v[10:11], s[4:5], 0, v[10:11]
	v_lshl_add_u64 v[10:11], v[10:11], 0, s[40:41]
	v_lshl_add_u64 v[10:11], v[10:11], 0, v[0:1]
	s_waitcnt lgkmcnt(0)
	global_store_dwordx4 v[10:11], v[2:5], off
	v_add_u32_e32 v10, 0x50, v8
	ds_read_b128 v[2:5], v6 offset:42240
	v_ashrrev_i32_e32 v11, 31, v10
	v_lshlrev_b64 v[10:11], 11, v[10:11]
	v_lshl_add_u64 v[10:11], s[4:5], 0, v[10:11]
	v_lshl_add_u64 v[10:11], v[10:11], 0, s[40:41]
	v_lshl_add_u64 v[10:11], v[10:11], 0, v[0:1]
	s_waitcnt lgkmcnt(0)
	global_store_dwordx4 v[10:11], v[2:5], off
	v_add_u32_e32 v10, 0x58, v8
	ds_read_b128 v[2:5], v6 offset:46464
	v_ashrrev_i32_e32 v11, 31, v10
	v_lshlrev_b64 v[10:11], 11, v[10:11]
	v_lshl_add_u64 v[10:11], s[4:5], 0, v[10:11]
	v_lshl_add_u64 v[10:11], v[10:11], 0, s[40:41]
	v_lshl_add_u64 v[10:11], v[10:11], 0, v[0:1]
	s_waitcnt lgkmcnt(0)
	global_store_dwordx4 v[10:11], v[2:5], off
	v_add_u32_e32 v10, 0x60, v8
	ds_read_b128 v[2:5], v6 offset:50688
	v_ashrrev_i32_e32 v11, 31, v10
	v_lshlrev_b64 v[10:11], 11, v[10:11]
	v_lshl_add_u64 v[10:11], s[4:5], 0, v[10:11]
	v_lshl_add_u64 v[10:11], v[10:11], 0, s[40:41]
	v_lshl_add_u64 v[10:11], v[10:11], 0, v[0:1]
	s_waitcnt lgkmcnt(0)
	global_store_dwordx4 v[10:11], v[2:5], off
	v_add_u32_e32 v10, 0x68, v8
	ds_read_b128 v[2:5], v6 offset:54912
	v_ashrrev_i32_e32 v11, 31, v10
	v_lshlrev_b64 v[10:11], 11, v[10:11]
	v_lshl_add_u64 v[10:11], s[4:5], 0, v[10:11]
	v_lshl_add_u64 v[10:11], v[10:11], 0, s[40:41]
	v_lshl_add_u64 v[10:11], v[10:11], 0, v[0:1]
	s_waitcnt lgkmcnt(0)
	global_store_dwordx4 v[10:11], v[2:5], off
	v_add_u32_e32 v10, 0x70, v8
	ds_read_b128 v[2:5], v6 offset:59136
	v_ashrrev_i32_e32 v11, 31, v10
	v_lshlrev_b64 v[10:11], 11, v[10:11]
	v_lshl_add_u64 v[10:11], s[4:5], 0, v[10:11]
	v_lshl_add_u64 v[10:11], v[10:11], 0, s[40:41]
	v_lshl_add_u64 v[10:11], v[10:11], 0, v[0:1]
	s_waitcnt lgkmcnt(0)
	global_store_dwordx4 v[10:11], v[2:5], off
	ds_read_b128 v[2:5], v6 offset:63360
	v_add_u32_e32 v6, 0x78, v8
	v_ashrrev_i32_e32 v7, 31, v6
	v_lshlrev_b64 v[6:7], 11, v[6:7]
	v_lshl_add_u64 v[6:7], s[4:5], 0, v[6:7]
	v_lshl_add_u64 v[6:7], v[6:7], 0, s[40:41]
	v_lshl_add_u64 v[6:7], v[6:7], 0, v[0:1]
	s_waitcnt lgkmcnt(0)
	global_store_dwordx4 v[6:7], v[2:5], off
	s_branch .LBB0_28

.LBB0_70:
	s_ashr_i32 s1, s0, 31
	s_lshr_b32 s1, s1, 28
	s_add_i32 s1, s0, s1
	s_and_b32 s12, s1, 0x1fffff0
	s_sub_i32 s12, s0, s12
	s_add_i32 s12, s12, s69
	s_lshl_b32 s1, s1, 4
	s_lshl_b32 s71, s12, 7
	s_and_b32 s82, s1, 0xffffff00
	s_cmpk_gt_i32 s0, 0x7f
	s_cbranch_scc0 .LBB0_74
	s_waitcnt vmcnt(6)
	v_mov_b32_e32 v58, v224
	s_add_i32 s0, s82, 0xfffff800
	v_readfirstlane_b32 s12, v58
	v_bfe_u32 v59, v58, 4, 2
	s_and_b32 s15, s12, 0xffffffc0
	s_waitcnt vmcnt(4)
	v_bfe_u32 v42, v58, 2, 4
	v_sub_u32_e32 v60, 0, v59
	s_add_i32 s15, s15, s0
	v_xor_b32_e32 v0, v58, v60
	v_or_b32_e32 v6, s15, v42
	v_lshlrev_b32_e32 v0, 4, v0
	v_min_i32_e32 v4, 0x3ff, v6
	v_and_b32_e32 v0, 48, v0
	v_ashrrev_i32_e32 v5, 31, v4
	v_lshl_add_u64 v[2:3], s[52:53], 0, v[0:1]
	v_lshlrev_b64 v[4:5], 6, v[4:5]
	v_lshl_add_u64 v[34:35], v[2:3], 0, v[4:5]
	v_or_b32_e32 v4, 16, v6
	v_min_i32_e32 v4, 0x3ff, v4
	v_ashrrev_i32_e32 v5, 31, v4
	v_lshlrev_b64 v[4:5], 6, v[4:5]
	v_lshl_add_u64 v[36:37], v[2:3], 0, v[4:5]
	v_or_b32_e32 v4, 32, v6
	v_min_i32_e32 v4, 0x3ff, v4
	v_ashrrev_i32_e32 v5, 31, v4
	v_lshlrev_b64 v[4:5], 6, v[4:5]
	s_ashr_i32 s13, s12, 6
	v_lshl_add_u64 v[38:39], v[2:3], 0, v[4:5]
	v_or_b32_e32 v4, 48, v6
	s_and_b32 s14, s13, 1
	v_min_i32_e32 v4, 0x3ff, v4
	v_ashrrev_i32_e32 v5, 31, v4
	s_lshl_b32 s15, s14, 6
	v_lshlrev_b64 v[4:5], 6, v[4:5]
	v_and_b32_e32 v61, 15, v58
	s_or_b32 s15, s15, s71
	v_lshl_add_u64 v[40:41], v[2:3], 0, v[4:5]
	v_or_b32_e32 v4, s15, v61
	v_lshlrev_b32_e32 v2, 5, v4
	s_waitcnt vmcnt(0)
	s_barrier
	global_load_dwordx4 v[14:17], v2, s[48:49] offset:16
	global_load_dwordx4 v[30:33], v2, s[48:49]
	v_or_b32_e32 v2, 16, v4
	v_mov_b32_e32 v3, v1
	v_lshlrev_b64 v[2:3], 5, v[2:3]
	v_lshl_add_u64 v[2:3], s[48:49], 0, v[2:3]
	global_load_dwordx4 v[10:13], v[2:3], off offset:16
	global_load_dwordx4 v[26:29], v[2:3], off
	v_or_b32_e32 v2, 32, v4
	v_mov_b32_e32 v3, v1
	v_lshlrev_b64 v[2:3], 5, v[2:3]
	v_lshl_add_u64 v[2:3], s[48:49], 0, v[2:3]
	global_load_dwordx4 v[6:9], v[2:3], off offset:16
	global_load_dwordx4 v[22:25], v[2:3], off
	v_or_b32_e32 v2, 48, v4
	v_mov_b32_e32 v3, v1
	v_lshlrev_b64 v[2:3], 5, v[2:3]
	v_lshl_add_u64 v[18:19], s[48:49], 0, v[2:3]
	global_load_dwordx4 v[2:5], v[18:19], off offset:16
	s_nop 0
	global_load_dwordx4 v[18:21], v[18:19], off
	s_lshl_b32 s15, s13, 1
	s_waitcnt vmcnt(8)
	v_or_b32_e32 v46, s71, v42
	v_lshl_add_u32 v44, s13, 5, v46
	s_lshl_b32 s40, s15, 10
	s_or_b32 s15, s15, 1
	v_ashrrev_i32_e32 v45, 31, v44
	v_lshl_add_u32 v46, s15, 4, v46
	v_lshl_add_u64 v[42:43], s[4:5], 0, v[0:1]
	v_lshlrev_b64 v[162:163], 10, v[44:45]
	v_lshlrev_b64 v[44:45], 11, v[44:45]
	v_ashrrev_i32_e32 v47, 31, v46
	v_lshl_add_u64 v[44:45], v[42:43], 0, v[44:45]
	v_lshlrev_b64 v[164:165], 10, v[46:47]
	v_lshlrev_b64 v[46:47], 11, v[46:47]
	s_mov_b32 s43, m0
	s_mov_b32 m0, s40
	s_nop 0
	global_load_lds_dwordx4 v[44:45], off
	s_mov_b32 m0, s43
	v_lshl_add_u64 v[42:43], v[42:43], 0, v[46:47]
	s_lshl_b32 s41, s13, 12
	s_add_i32 s42, s40, 0x6000
	s_lshl_b32 s15, s15, 10
	s_mov_b32 s40, m0
	s_mov_b32 m0, s15
	s_nop 0
	global_load_lds_dwordx4 v[42:43], off
	s_mov_b32 m0, s40
	s_add_i32 s40, s41, 0x2000
	s_mov_b32 s43, m0
	s_mov_b32 m0, s40
	s_nop 0
	global_load_lds_dwordx4 v[34:35], off
	s_mov_b32 m0, s43
	s_add_i32 s43, s41, 0x2400
	s_mov_b32 s44, m0
	s_mov_b32 m0, s43
	s_nop 0
	global_load_lds_dwordx4 v[36:37], off
	s_mov_b32 m0, s44
	s_add_i32 s43, s41, 0x2800
	s_mov_b32 s44, m0
	s_mov_b32 m0, s43
	s_nop 0
	global_load_lds_dwordx4 v[38:39], off
	s_mov_b32 m0, s44
	s_add_i32 s43, s41, 0x2c00
	s_mov_b32 s44, m0
	s_mov_b32 m0, s43
	s_nop 0
	global_load_lds_dwordx4 v[40:41], off
	s_mov_b32 m0, s44
	v_lshl_add_u64 v[46:47], v[44:45], 0, 64
	s_mov_b32 s43, m0
	s_mov_b32 m0, s42
	s_nop 0
	global_load_lds_dwordx4 v[46:47], off
	s_mov_b32 m0, s43
	v_lshl_add_u64 v[48:49], v[42:43], 0, 64
	s_add_i32 s42, s15, 0x6000
	s_mov_b32 s43, m0
	s_mov_b32 m0, s42
	s_nop 0
	global_load_lds_dwordx4 v[48:49], off
	s_mov_b32 m0, s43
	v_lshrrev_b32_e32 v0, 2, v58
	s_waitcnt vmcnt(25)
	s_mov_b32 s100, 0x10000
	s_mov_b32 s101, 0
	v_lshl_add_u64 v[50:51], v[34:35], 0, s[100:101]
	s_add_i32 s42, s41, 0x8000
	s_mov_b32 s43, m0
	s_mov_b32 m0, s42
	s_nop 0
	global_load_lds_dwordx4 v[50:51], off
	s_mov_b32 m0, s43
	v_sub_u32_e32 v0, 0, v0
	v_lshl_add_u64 v[52:53], v[36:37], 0, s[100:101]
	s_add_i32 s42, s41, 0x8400
	s_mov_b32 s43, m0
	s_mov_b32 m0, s42
	s_nop 0
	global_load_lds_dwordx4 v[52:53], off
	s_mov_b32 m0, s43
	v_bitop3_b32 v0, v59, v0, 3 bitop3:0x78
	s_and_b32 s12, s12, 0x3ffff80
	v_lshl_add_u64 v[54:55], v[38:39], 0, s[100:101]
	s_add_i32 s42, s41, 0x8800
	s_mov_b32 s43, m0
	s_mov_b32 m0, s42
	s_nop 0
	global_load_lds_dwordx4 v[54:55], off
	s_mov_b32 m0, s43
	v_lshlrev_b32_e32 v176, 4, v0
	v_or_b32_e32 v0, s12, v61
	v_lshl_add_u64 v[56:57], v[40:41], 0, s[100:101]
	s_add_i32 s41, s41, 0x8c00
	s_mov_b32 s42, m0
	s_mov_b32 m0, s41
	s_nop 0
	global_load_lds_dwordx4 v[56:57], off
	s_mov_b32 m0, s42
	v_lshlrev_b32_e32 v178, 6, v0
	v_bitop3_b32 v0, v58, 3, v60 bitop3:0x48
	s_mov_b32 s100, 0x20000
	v_lshl_add_u64 v[172:173], v[34:35], 0, s[100:101]
	v_lshlrev_b32_e32 v0, 4, v0
	v_mov_b32_e32 v34, 0
	s_mov_b32 s1, 0
	s_lshl_b32 s14, s14, 12
	v_lshlrev_b32_e32 v177, 6, v61
	s_lshl_b32 s41, s13, 11
	v_lshl_add_u64 v[166:167], v[40:41], 0, s[100:101]
	v_lshl_add_u64 v[168:169], v[38:39], 0, s[100:101]
	v_lshl_add_u64 v[170:171], v[36:37], 0, s[100:101]
	v_lshl_add_u64 v[174:175], s[74:75], 0, v[0:1]
	s_mov_b64 s[12:13], 0
	v_mov_b32_e32 v35, v34
	v_mov_b32_e32 v36, v34
	v_mov_b32_e32 v37, v34
	v_mov_b32_e32 v38, v34
	v_mov_b32_e32 v39, v34
	v_mov_b32_e32 v40, v34
	v_mov_b32_e32 v41, v34
	v_mov_b32_e32 v42, v34
	v_mov_b32_e32 v43, v34
	v_mov_b32_e32 v44, v34
	v_mov_b32_e32 v45, v34
	v_mov_b32_e32 v46, v34
	v_mov_b32_e32 v47, v34
	v_mov_b32_e32 v48, v34
	v_mov_b32_e32 v49, v34
	v_mov_b32_e32 v50, v34
	v_mov_b32_e32 v51, v34
	v_mov_b32_e32 v52, v34
	v_mov_b32_e32 v53, v34
	v_mov_b32_e32 v54, v34
	v_mov_b32_e32 v55, v34
	v_mov_b32_e32 v56, v34
	v_mov_b32_e32 v57, v34
	v_mov_b32_e32 v58, v34
	v_mov_b32_e32 v59, v34
	v_mov_b32_e32 v60, v34
	v_mov_b32_e32 v61, v34
	s_waitcnt vmcnt(24)
	v_mov_b32_e32 v62, v34
	v_mov_b32_e32 v63, v34
	v_mov_b32_e32 v64, v34
	v_mov_b32_e32 v65, v34
	v_mov_b32_e32 v66, v34
	v_mov_b32_e32 v67, v34
	v_mov_b32_e32 v68, v34
	v_mov_b32_e32 v69, v34
	v_mov_b32_e32 v70, v34
	v_mov_b32_e32 v71, v34
	v_mov_b32_e32 v72, v34
	v_mov_b32_e32 v73, v34
	v_mov_b32_e32 v74, v34
	v_mov_b32_e32 v75, v34
	v_mov_b32_e32 v76, v34
	v_mov_b32_e32 v77, v34
	v_mov_b32_e32 v78, v34
	v_mov_b32_e32 v79, v34
	v_mov_b32_e32 v80, v34
	v_mov_b32_e32 v81, v34
	v_mov_b32_e32 v82, v34
	v_mov_b32_e32 v83, v34
	v_mov_b32_e32 v84, v34
	v_mov_b32_e32 v85, v34
	v_mov_b32_e32 v86, v34
	v_mov_b32_e32 v87, v34
	v_mov_b32_e32 v88, v34
	v_mov_b32_e32 v89, v34
	v_mov_b32_e32 v90, v34
	v_mov_b32_e32 v91, v34
	v_mov_b32_e32 v92, v34
	v_mov_b32_e32 v93, v34
	v_mov_b32_e32 v94, v34
	v_mov_b32_e32 v95, v34
	v_mov_b32_e32 v96, v34
	v_mov_b32_e32 v97, v34
	v_mov_b32_e32 v98, v34
	v_mov_b32_e32 v99, v34
	v_mov_b32_e32 v100, v34
	v_mov_b32_e32 v101, v34
	v_mov_b32_e32 v102, v34
	v_mov_b32_e32 v103, v34
	v_mov_b32_e32 v104, v34
	v_mov_b32_e32 v105, v34
	v_mov_b32_e32 v106, v34
	v_mov_b32_e32 v107, v34
	v_mov_b32_e32 v108, v34
	v_mov_b32_e32 v109, v34
	v_mov_b32_e32 v110, v34
	v_mov_b32_e32 v111, v34
	v_mov_b32_e32 v112, v34
	v_mov_b32_e32 v113, v34
	v_mov_b32_e32 v114, v34
	v_mov_b32_e32 v115, v34
	v_mov_b32_e32 v116, v34
	v_mov_b32_e32 v117, v34
	v_mov_b32_e32 v118, v34
	v_mov_b32_e32 v119, v34
	v_mov_b32_e32 v120, v34
	v_mov_b32_e32 v121, v34
	v_mov_b32_e32 v122, v34
	v_mov_b32_e32 v123, v34
	v_mov_b32_e32 v124, v34
	v_mov_b32_e32 v125, v34
	v_mov_b32_e32 v126, v34
	v_mov_b32_e32 v127, v34
	v_mov_b32_e32 v128, v34
	v_mov_b32_e32 v129, v34
	v_mov_b32_e32 v130, v34
	v_mov_b32_e32 v131, v34
	v_mov_b32_e32 v132, v34
	v_mov_b32_e32 v133, v34
	v_mov_b32_e32 v134, v34
	v_mov_b32_e32 v135, v34
	v_mov_b32_e32 v136, v34
	v_mov_b32_e32 v137, v34
	v_mov_b32_e32 v138, v34
	v_mov_b32_e32 v139, v34
	v_mov_b32_e32 v140, v34
	v_mov_b32_e32 v141, v34
	v_mov_b32_e32 v142, v34
	v_mov_b32_e32 v143, v34
	v_mov_b32_e32 v144, v34
	v_mov_b32_e32 v145, v34
	v_mov_b32_e32 v146, v34
	v_mov_b32_e32 v147, v34
	v_mov_b32_e32 v148, v34
	v_mov_b32_e32 v149, v34
	v_mov_b32_e32 v150, v34
	v_mov_b32_e32 v151, v34
	v_mov_b32_e32 v152, v34
	v_mov_b32_e32 v153, v34
	v_mov_b32_e32 v154, v34
	v_mov_b32_e32 v155, v34
	v_mov_b32_e32 v156, v34
	v_mov_b32_e32 v157, v34
	v_mov_b32_e32 v158, v34
	v_mov_b32_e32 v159, v34
	v_mov_b32_e32 v160, v34
	v_mov_b32_e32 v161, v34
.LBB0_72:
	s_mul_i32 s100, s12, 0x400
	s_mul_i32 s42, s1, 0x6000
	s_add_i32 s43, s42, 0xffffa000
	s_cmp_gt_i32 s1, 0
	s_waitcnt vmcnt(6)
	s_cselect_b32 s43, s43, 0xc000
	s_waitcnt lgkmcnt(0)
	s_barrier
	s_setprio 2
	v_add3_u32 v0, s42, v177, v176
	v_add_u32_e32 v0, s14, v0
	v_add3_u32 v212, s42, v178, v176
	ds_read_b128 v[196:199], v212 offset:8192
	ds_read_b128 v[180:183], v0
	ds_read_b128 v[184:187], v0 offset:1024
	ds_read_b128 v[188:191], v0 offset:2048
	ds_read_b128 v[192:195], v0 offset:3072
	ds_read_b128 v[200:203], v212 offset:9216
	ds_read_b128 v[204:207], v212 offset:10240
	ds_read_b128 v[208:211], v212 offset:11264
	ds_read_b128 v[216:219], v212 offset:12288
	ds_read_b128 v[226:229], v212 offset:13312
	ds_read_b128 v[230:233], v212 offset:14336
	ds_read_b128 v[234:237], v212 offset:15360
	v_lshl_add_u64 v[212:213], v[174:175], 0, s[12:13]
	v_lshl_add_u64 v[212:213], v[162:163], 1, v[212:213]
	s_add_i32 s44, s43, s41
	s_mov_b32 m0, s44
	s_nop 0
	global_load_lds_dwordx4 v[212:213], off
	v_lshl_add_u64 v[212:213], v[174:175], 0, s[12:13]
	v_lshl_add_u64 v[212:213], v[164:165], 1, v[212:213]
	s_add_i32 s44, s43, s15
	s_mov_b32 m0, s44
	s_nop 0
	global_load_lds_dwordx4 v[212:213], off
	s_add_i32 s43, s40, s43
	v_lshl_add_u64 v[212:213], v[172:173], 0, s[100:101]
	s_mov_b32 m0, s43
	s_nop 0
	global_load_lds_dwordx4 v[212:213], off
	v_lshl_add_u64 v[212:213], v[170:171], 0, s[100:101]
	s_add_i32 s44, s43, 0x400
	s_mov_b32 m0, s44
	s_nop 0
	global_load_lds_dwordx4 v[212:213], off
	v_lshl_add_u64 v[212:213], v[168:169], 0, s[100:101]
	s_add_i32 s44, s43, 0x800
	s_mov_b32 m0, s44
	s_nop 0
	global_load_lds_dwordx4 v[212:213], off
	s_addk_i32 s43, 0xc00
	v_lshl_add_u64 v[212:213], v[166:167], 0, s[100:101]
	s_mov_b32 m0, s43
	s_nop 0
	global_load_lds_dwordx4 v[212:213], off
	s_setprio 0
	s_waitcnt lgkmcnt(10)
	v_mfma_f32_16x16x32_bf16 v[34:37], v[196:199], v[180:183], v[34:37]
	s_waitcnt lgkmcnt(9)
	v_mfma_f32_16x16x32_bf16 v[38:41], v[196:199], v[184:187], v[38:41]
	s_waitcnt lgkmcnt(8)
	v_mfma_f32_16x16x32_bf16 v[42:45], v[196:199], v[188:191], v[42:45]
	s_waitcnt lgkmcnt(7)
	v_mfma_f32_16x16x32_bf16 v[46:49], v[196:199], v[192:195], v[46:49]
	s_waitcnt lgkmcnt(6)
	v_mfma_f32_16x16x32_bf16 v[50:53], v[200:203], v[180:183], v[50:53]
	v_mfma_f32_16x16x32_bf16 v[54:57], v[200:203], v[184:187], v[54:57]
	v_mfma_f32_16x16x32_bf16 v[58:61], v[200:203], v[188:191], v[58:61]
	v_mfma_f32_16x16x32_bf16 v[62:65], v[200:203], v[192:195], v[62:65]
	s_waitcnt lgkmcnt(5)
	v_mfma_f32_16x16x32_bf16 v[66:69], v[204:207], v[180:183], v[66:69]
	v_mfma_f32_16x16x32_bf16 v[70:73], v[204:207], v[184:187], v[70:73]
	v_mfma_f32_16x16x32_bf16 v[74:77], v[204:207], v[188:191], v[74:77]
	v_mfma_f32_16x16x32_bf16 v[78:81], v[204:207], v[192:195], v[78:81]
	s_waitcnt lgkmcnt(4)
	v_mfma_f32_16x16x32_bf16 v[82:85], v[208:211], v[180:183], v[82:85]
	v_mfma_f32_16x16x32_bf16 v[86:89], v[208:211], v[184:187], v[86:89]
	v_mfma_f32_16x16x32_bf16 v[90:93], v[208:211], v[188:191], v[90:93]
	v_mfma_f32_16x16x32_bf16 v[94:97], v[208:211], v[192:195], v[94:97]
	s_waitcnt lgkmcnt(3)
	v_mfma_f32_16x16x32_bf16 v[98:101], v[216:219], v[180:183], v[98:101]
	v_mfma_f32_16x16x32_bf16 v[102:105], v[216:219], v[184:187], v[102:105]
	v_mfma_f32_16x16x32_bf16 v[106:109], v[216:219], v[188:191], v[106:109]
	v_mfma_f32_16x16x32_bf16 v[110:113], v[216:219], v[192:195], v[110:113]
	s_waitcnt lgkmcnt(2)
	v_mfma_f32_16x16x32_bf16 v[114:117], v[226:229], v[180:183], v[114:117]
	v_mfma_f32_16x16x32_bf16 v[118:121], v[226:229], v[184:187], v[118:121]
	v_mfma_f32_16x16x32_bf16 v[122:125], v[226:229], v[188:191], v[122:125]
	v_mfma_f32_16x16x32_bf16 v[126:129], v[226:229], v[192:195], v[126:129]
	s_waitcnt lgkmcnt(1)
	v_mfma_f32_16x16x32_bf16 v[130:133], v[230:233], v[180:183], v[130:133]
	v_mfma_f32_16x16x32_bf16 v[134:137], v[230:233], v[184:187], v[134:137]
	v_mfma_f32_16x16x32_bf16 v[138:141], v[230:233], v[188:191], v[138:141]
	v_mfma_f32_16x16x32_bf16 v[142:145], v[230:233], v[192:195], v[142:145]
	s_waitcnt lgkmcnt(0)
	v_mfma_f32_16x16x32_bf16 v[146:149], v[234:237], v[180:183], v[146:149]
	v_mfma_f32_16x16x32_bf16 v[150:153], v[234:237], v[184:187], v[150:153]
	v_mfma_f32_16x16x32_bf16 v[154:157], v[234:237], v[188:191], v[154:157]
	v_mfma_f32_16x16x32_bf16 v[158:161], v[234:237], v[192:195], v[158:161]
	s_add_i32 s42, s1, 1
	s_cmp_lg_u32 s1, 2
	s_cselect_b32 s1, s42, 0
	s_add_u32 s12, s12, 64
	s_addc_u32 s13, s13, 0
	s_cmpk_eq_i32 s12, 0x780
	s_cbranch_scc0 .LBB0_72
	s_waitcnt vmcnt(6)
	v_mov_b32_e32 v162, v31
	v_mov_b32_e32 v163, v32
	v_mov_b32_e32 v31, v33
	v_mov_b32_e32 v164, v15
	v_mov_b32_e32 v165, v16
	v_pk_add_f32 v[30:31], v[162:163], v[30:31]
	v_mov_b32_e32 v15, v17
	v_pk_add_f32 v[14:15], v[164:165], v[14:15]
	v_add_f32_e32 v0, v30, v31
	v_add_f32_e32 v0, v0, v14
	v_add_f32_e32 v0, v0, v15
	s_waitcnt vmcnt(4)
	v_mov_b32_e32 v166, v27
	v_mov_b32_e32 v167, v28
	v_fmamk_f32 v0, v0, 0x3a800000, v250
	s_mov_b32 s1, 0x800000
	v_mov_b32_e32 v27, v29
	v_mov_b32_e32 v168, v11
	v_mov_b32_e32 v169, v12
	s_waitcnt vmcnt(1)
	v_mov_b32_e32 v180, v3
	v_mul_f32_e32 v3, 0x4b800000, v0
	v_cmp_gt_f32_e32 vcc, s1, v0
	v_pk_add_f32 v[14:15], v[166:167], v[26:27]
	v_mov_b32_e32 v11, v13
	v_cndmask_b32_e32 v0, v0, v3, vcc
	v_pk_add_f32 v[10:11], v[168:169], v[10:11]
	v_add_f32_e32 v3, v14, v15
	v_add_f32_e32 v3, v3, v10
	v_add_f32_e32 v3, v3, v11
	v_fmamk_f32 v3, v3, 0x3a800000, v250
	v_mov_b32_e32 v170, v23
	v_mov_b32_e32 v171, v24
	v_mov_b32_e32 v181, v4
	v_mul_f32_e32 v4, 0x4b800000, v3
	v_cmp_gt_f32_e64 s[40:41], s1, v3
	v_mov_b32_e32 v23, v25
	v_mov_b32_e32 v172, v7
	v_mov_b32_e32 v173, v8
	v_cndmask_b32_e64 v3, v3, v4, s[40:41]
	v_pk_add_f32 v[10:11], v[170:171], v[22:23]
	v_mov_b32_e32 v7, v9
	v_rsq_f32_e32 v179, v3
	v_pk_add_f32 v[6:7], v[172:173], v[6:7]
	v_add_f32_e32 v3, v10, v11
	v_add_f32_e32 v3, v3, v6
	v_add_f32_e32 v3, v3, v7
	v_fmamk_f32 v3, v3, 0x3a800000, v250
	v_mul_f32_e32 v4, 0x4b800000, v3
	v_cmp_gt_f32_e64 s[42:43], s1, v3
	s_waitcnt vmcnt(0)
	v_mov_b32_e32 v174, v19
	v_mov_b32_e32 v175, v20
	v_cndmask_b32_e64 v3, v3, v4, s[42:43]
	v_mov_b32_e32 v19, v21
	v_rsq_f32_e32 v182, v3
	v_pk_add_f32 v[6:7], v[174:175], v[18:19]
	v_mov_b32_e32 v3, v5
	v_pk_add_f32 v[2:3], v[180:181], v[2:3]
	v_add_f32_e32 v4, v6, v7
	v_add_f32_e32 v2, v4, v2
	v_add_f32_e32 v2, v2, v3
	v_fmamk_f32 v2, v2, 0x3a800000, v250
	v_mul_f32_e32 v3, 0x4b800000, v2
	v_cmp_gt_f32_e64 s[44:45], s1, v2
	s_waitcnt vmcnt(6)
	v_add_u32_e32 v183, v178, v176
	s_waitcnt lgkmcnt(0)
	s_barrier
	v_cndmask_b32_e64 v2, v2, v3, s[44:45]
	v_rsq_f32_e32 v180, v2
	ds_read_b128 v[2:5], v183 offset:15360
	ds_read_b128 v[6:9], v183 offset:14336
	ds_read_b128 v[10:13], v183 offset:13312
	ds_read_b128 v[14:17], v183 offset:12288
	ds_read_b128 v[18:21], v183 offset:11264
	ds_read_b128 v[22:25], v183 offset:10240
	ds_read_b128 v[26:29], v183 offset:9216
	ds_read_b128 v[30:33], v183 offset:8192
	v_add3_u32 v178, s14, v177, v176
	ds_read_b128 v[162:165], v178 offset:3072
	ds_read_b128 v[166:169], v178 offset:2048
	ds_read_b128 v[170:173], v178 offset:1024
	ds_read_b128 v[174:177], v178
	v_rsq_f32_e32 v0, v0
	v_mul_f32_e32 v184, 0x45800000, v179
	v_mul_f32_e32 v185, 0x45800000, v182
	v_mul_f32_e32 v186, 0x45800000, v180
	v_mul_f32_e32 v181, 0x45800000, v0
	s_waitcnt lgkmcnt(0)
	v_mfma_f32_16x16x32_bf16 v[34:37], v[30:33], v[174:177], v[34:37]
	v_mfma_f32_16x16x32_bf16 v[38:41], v[30:33], v[170:173], v[38:41]
	v_mfma_f32_16x16x32_bf16 v[42:45], v[30:33], v[166:169], v[42:45]
	v_mfma_f32_16x16x32_bf16 v[46:49], v[30:33], v[162:165], v[46:49]
	v_mfma_f32_16x16x32_bf16 v[50:53], v[26:29], v[174:177], v[50:53]
	v_mfma_f32_16x16x32_bf16 v[54:57], v[26:29], v[170:173], v[54:57]
	v_mfma_f32_16x16x32_bf16 v[58:61], v[26:29], v[166:169], v[58:61]
	v_mfma_f32_16x16x32_bf16 v[62:65], v[26:29], v[162:165], v[62:65]
	v_mfma_f32_16x16x32_bf16 v[66:69], v[22:25], v[174:177], v[66:69]
	v_mfma_f32_16x16x32_bf16 v[70:73], v[22:25], v[170:173], v[70:73]
	v_mfma_f32_16x16x32_bf16 v[74:77], v[22:25], v[166:169], v[74:77]
	v_mfma_f32_16x16x32_bf16 v[22:25], v[22:25], v[162:165], v[78:81]
	v_mfma_f32_16x16x32_bf16 v[78:81], v[18:21], v[174:177], v[82:85]
	v_mfma_f32_16x16x32_bf16 v[82:85], v[18:21], v[170:173], v[86:89]
	v_mfma_f32_16x16x32_bf16 v[86:89], v[18:21], v[166:169], v[90:93]
	v_mfma_f32_16x16x32_bf16 v[18:21], v[18:21], v[162:165], v[94:97]
	v_mfma_f32_16x16x32_bf16 v[90:93], v[14:17], v[174:177], v[98:101]
	v_mfma_f32_16x16x32_bf16 v[94:97], v[14:17], v[170:173], v[102:105]
	v_mfma_f32_16x16x32_bf16 v[98:101], v[14:17], v[166:169], v[106:109]
	v_mfma_f32_16x16x32_bf16 v[14:17], v[14:17], v[162:165], v[110:113]
	v_mfma_f32_16x16x32_bf16 v[102:105], v[10:13], v[174:177], v[114:117]
	v_mfma_f32_16x16x32_bf16 v[106:109], v[10:13], v[170:173], v[118:121]
	v_mfma_f32_16x16x32_bf16 v[110:113], v[10:13], v[166:169], v[122:125]
	v_mfma_f32_16x16x32_bf16 v[10:13], v[10:13], v[162:165], v[126:129]
	v_mfma_f32_16x16x32_bf16 v[114:117], v[6:9], v[174:177], v[130:133]
	v_mfma_f32_16x16x32_bf16 v[118:121], v[6:9], v[170:173], v[134:137]
	v_mfma_f32_16x16x32_bf16 v[122:125], v[6:9], v[166:169], v[138:141]
	v_mfma_f32_16x16x32_bf16 v[6:9], v[6:9], v[162:165], v[142:145]
	v_mfma_f32_16x16x32_bf16 v[126:129], v[2:5], v[174:177], v[146:149]
	v_mfma_f32_16x16x32_bf16 v[130:133], v[2:5], v[170:173], v[150:153]
	v_mfma_f32_16x16x32_bf16 v[134:137], v[2:5], v[166:169], v[154:157]
	v_mfma_f32_16x16x32_bf16 v[2:5], v[2:5], v[162:165], v[158:161]
	s_waitcnt vmcnt(0)
	v_cndmask_b32_e32 v30, v0, v181, vcc
	v_cndmask_b32_e64 v28, v179, v184, s[40:41]
	v_cndmask_b32_e64 v26, v182, v185, s[42:43]
	v_cndmask_b32_e64 v0, v180, v186, s[44:45]
	s_waitcnt lgkmcnt(0)
	s_barrier
	ds_read_b128 v[138:141], v178 offset:24576
	ds_read_b128 v[142:145], v178 offset:25600
	ds_read_b128 v[146:149], v178 offset:26624
	ds_read_b128 v[150:153], v178 offset:27648
	ds_read_b128 v[154:157], v183 offset:32768
	ds_read_b128 v[158:161], v183 offset:33792
	ds_read_b128 v[162:165], v183 offset:34816
	ds_read_b128 v[166:169], v183 offset:35840
	ds_read_b128 v[170:173], v183 offset:36864
	ds_read_b128 v[174:177], v183 offset:37888
	ds_read_b128 v[178:181], v183 offset:38912
	ds_read_b128 v[182:185], v183 offset:39936
	s_waitcnt lgkmcnt(7)
	v_mfma_f32_16x16x32_bf16 v[32:35], v[154:157], v[138:141], v[34:37]
	v_mfma_f32_16x16x32_bf16 v[36:39], v[154:157], v[142:145], v[38:41]
	v_mfma_f32_16x16x32_bf16 v[40:43], v[154:157], v[146:149], v[42:45]
	v_mfma_f32_16x16x32_bf16 v[44:47], v[154:157], v[150:153], v[46:49]
	s_waitcnt lgkmcnt(6)
	v_mfma_f32_16x16x32_bf16 v[48:51], v[158:161], v[138:141], v[50:53]
	v_mfma_f32_16x16x32_bf16 v[52:55], v[158:161], v[142:145], v[54:57]
	v_mfma_f32_16x16x32_bf16 v[56:59], v[158:161], v[146:149], v[58:61]
	v_mfma_f32_16x16x32_bf16 v[60:63], v[158:161], v[150:153], v[62:65]
	s_waitcnt lgkmcnt(5)
	v_mfma_f32_16x16x32_bf16 v[64:67], v[162:165], v[138:141], v[66:69]
	v_mfma_f32_16x16x32_bf16 v[68:71], v[162:165], v[142:145], v[70:73]
	v_mfma_f32_16x16x32_bf16 v[72:75], v[162:165], v[146:149], v[74:77]
	v_mfma_f32_16x16x32_bf16 v[154:157], v[162:165], v[150:153], v[22:25]
	s_waitcnt lgkmcnt(4)
	v_mfma_f32_16x16x32_bf16 v[76:79], v[166:169], v[138:141], v[78:81]
	v_mfma_f32_16x16x32_bf16 v[80:83], v[166:169], v[142:145], v[82:85]
	v_mfma_f32_16x16x32_bf16 v[84:87], v[166:169], v[146:149], v[86:89]
	v_mfma_f32_16x16x32_bf16 v[158:161], v[166:169], v[150:153], v[18:21]
	s_waitcnt lgkmcnt(3)
	v_mfma_f32_16x16x32_bf16 v[88:91], v[170:173], v[138:141], v[90:93]
	v_mfma_f32_16x16x32_bf16 v[92:95], v[170:173], v[142:145], v[94:97]
	v_mfma_f32_16x16x32_bf16 v[96:99], v[170:173], v[146:149], v[98:101]
	v_mfma_f32_16x16x32_bf16 v[162:165], v[170:173], v[150:153], v[14:17]
	s_waitcnt lgkmcnt(2)
	v_mfma_f32_16x16x32_bf16 v[100:103], v[174:177], v[138:141], v[102:105]
	v_mfma_f32_16x16x32_bf16 v[104:107], v[174:177], v[142:145], v[106:109]
	v_mfma_f32_16x16x32_bf16 v[108:111], v[174:177], v[146:149], v[110:113]
	v_mfma_f32_16x16x32_bf16 v[166:169], v[174:177], v[150:153], v[10:13]
	s_waitcnt lgkmcnt(1)
	v_mfma_f32_16x16x32_bf16 v[112:115], v[178:181], v[138:141], v[114:117]
	v_mfma_f32_16x16x32_bf16 v[116:119], v[178:181], v[142:145], v[118:121]
	v_mfma_f32_16x16x32_bf16 v[22:25], v[178:181], v[146:149], v[122:125]
	v_mfma_f32_16x16x32_bf16 v[18:21], v[178:181], v[150:153], v[6:9]
	s_waitcnt lgkmcnt(0)
	v_mfma_f32_16x16x32_bf16 v[14:17], v[182:185], v[138:141], v[126:129]
	v_mfma_f32_16x16x32_bf16 v[10:13], v[182:185], v[142:145], v[130:133]
	v_mfma_f32_16x16x32_bf16 v[6:9], v[182:185], v[146:149], v[134:137]
	v_mfma_f32_16x16x32_bf16 v[2:5], v[182:185], v[150:153], v[2:5]
	v_mov_b32_e32 v27, v224
	s_movk_i32 s1, 0x210
	v_lshrrev_b32_e32 v120, 1, v27
	v_and_b32_e32 v31, 0x7fffff80, v27
	v_and_b32_e32 v120, 24, v120
	v_and_b32_e32 v29, 0x4f, v27
	v_lshl_or_b32 v31, v31, 1, v120
	v_pk_mul_f32 v[32:33], v[30:31], v[32:33] op_sel_hi:[0,1]
	v_pk_mul_f32 v[34:35], v[30:31], v[34:35] op_sel_hi:[0,1]
	v_mad_u32_u24 v29, v29, s1, v31
	v_cvt_pk_bf16_f32 v32, v32, v33
	v_cvt_pk_bf16_f32 v33, v34, v35
	v_pk_mul_f32 v[34:35], v[28:29], v[36:37] op_sel_hi:[0,1]
	v_pk_mul_f32 v[36:37], v[28:29], v[38:39] op_sel_hi:[0,1]
	v_cvt_pk_bf16_f32 v34, v34, v35
	v_cvt_pk_bf16_f32 v35, v36, v37
	v_pk_mul_f32 v[36:37], v[26:27], v[40:41] op_sel_hi:[0,1]
	v_pk_mul_f32 v[38:39], v[26:27], v[42:43] op_sel_hi:[0,1]
	v_cvt_pk_bf16_f32 v36, v36, v37
	v_cvt_pk_bf16_f32 v37, v38, v39
	v_pk_mul_f32 v[38:39], v[0:1], v[44:45] op_sel_hi:[0,1]
	v_pk_mul_f32 v[40:41], v[0:1], v[46:47] op_sel_hi:[0,1]
	v_cvt_pk_bf16_f32 v38, v38, v39
	v_cvt_pk_bf16_f32 v39, v40, v41
	v_pk_mul_f32 v[40:41], v[30:31], v[48:49] op_sel_hi:[0,1]
	v_pk_mul_f32 v[42:43], v[30:31], v[50:51] op_sel_hi:[0,1]
	v_cvt_pk_bf16_f32 v40, v40, v41
	v_cvt_pk_bf16_f32 v41, v42, v43
	s_barrier
	ds_write2_b64 v29, v[32:33], v[40:41] offset1:4
	v_pk_mul_f32 v[32:33], v[28:29], v[52:53] op_sel_hi:[0,1]
	v_pk_mul_f32 v[40:41], v[28:29], v[54:55] op_sel_hi:[0,1]
	v_cvt_pk_bf16_f32 v32, v32, v33
	v_cvt_pk_bf16_f32 v33, v40, v41
	v_add_u32_e32 v31, 0x2000, v29
	ds_write2_b64 v31, v[34:35], v[32:33] offset0:32 offset1:36
	v_pk_mul_f32 v[32:33], v[26:27], v[56:57] op_sel_hi:[0,1]
	v_pk_mul_f32 v[34:35], v[26:27], v[58:59] op_sel_hi:[0,1]
	v_cvt_pk_bf16_f32 v32, v32, v33
	v_cvt_pk_bf16_f32 v33, v34, v35
	v_add_u32_e32 v44, 0x4000, v29
	ds_write2_b64 v44, v[36:37], v[32:33] offset0:64 offset1:68
	v_pk_mul_f32 v[32:33], v[0:1], v[60:61] op_sel_hi:[0,1]
	v_pk_mul_f32 v[34:35], v[0:1], v[62:63] op_sel_hi:[0,1]
	v_cvt_pk_bf16_f32 v32, v32, v33
	v_cvt_pk_bf16_f32 v33, v34, v35
	v_add_u32_e32 v45, 0x6000, v29
	ds_write2_b64 v45, v[38:39], v[32:33] offset0:96 offset1:100
	v_pk_mul_f32 v[32:33], v[30:31], v[64:65] op_sel_hi:[0,1]
	v_pk_mul_f32 v[34:35], v[30:31], v[66:67] op_sel_hi:[0,1]
	v_cvt_pk_bf16_f32 v32, v32, v33
	v_cvt_pk_bf16_f32 v33, v34, v35
	v_pk_mul_f32 v[34:35], v[28:29], v[68:69] op_sel_hi:[0,1]
	v_pk_mul_f32 v[36:37], v[28:29], v[70:71] op_sel_hi:[0,1]
	v_cvt_pk_bf16_f32 v34, v34, v35
	v_cvt_pk_bf16_f32 v35, v36, v37
	v_pk_mul_f32 v[36:37], v[26:27], v[72:73] op_sel_hi:[0,1]
	v_pk_mul_f32 v[38:39], v[26:27], v[74:75] op_sel_hi:[0,1]
	v_cvt_pk_bf16_f32 v36, v36, v37
	v_cvt_pk_bf16_f32 v37, v38, v39
	v_pk_mul_f32 v[38:39], v[0:1], v[154:155] op_sel_hi:[0,1]
	v_pk_mul_f32 v[40:41], v[0:1], v[156:157] op_sel_hi:[0,1]
	v_cvt_pk_bf16_f32 v38, v38, v39
	v_cvt_pk_bf16_f32 v39, v40, v41
	v_pk_mul_f32 v[40:41], v[30:31], v[76:77] op_sel_hi:[0,1]
	v_pk_mul_f32 v[42:43], v[30:31], v[78:79] op_sel_hi:[0,1]
	v_cvt_pk_bf16_f32 v40, v40, v41
	v_cvt_pk_bf16_f32 v41, v42, v43
	ds_write2_b64 v29, v[32:33], v[40:41] offset0:8 offset1:12
	v_pk_mul_f32 v[32:33], v[28:29], v[80:81] op_sel_hi:[0,1]
	v_pk_mul_f32 v[40:41], v[28:29], v[82:83] op_sel_hi:[0,1]
	v_cvt_pk_bf16_f32 v32, v32, v33
	v_cvt_pk_bf16_f32 v33, v40, v41
	ds_write2_b64 v31, v[34:35], v[32:33] offset0:40 offset1:44
	v_pk_mul_f32 v[32:33], v[26:27], v[84:85] op_sel_hi:[0,1]
	v_pk_mul_f32 v[34:35], v[26:27], v[86:87] op_sel_hi:[0,1]
	v_cvt_pk_bf16_f32 v32, v32, v33
	v_cvt_pk_bf16_f32 v33, v34, v35
	ds_write2_b64 v44, v[36:37], v[32:33] offset0:72 offset1:76
	v_pk_mul_f32 v[32:33], v[0:1], v[158:159] op_sel_hi:[0,1]
	v_pk_mul_f32 v[34:35], v[0:1], v[160:161] op_sel_hi:[0,1]
	v_cvt_pk_bf16_f32 v32, v32, v33
	v_cvt_pk_bf16_f32 v33, v34, v35
	ds_write2_b64 v45, v[38:39], v[32:33] offset0:104 offset1:108
	v_pk_mul_f32 v[32:33], v[30:31], v[88:89] op_sel_hi:[0,1]
	v_pk_mul_f32 v[34:35], v[30:31], v[90:91] op_sel_hi:[0,1]
	v_cvt_pk_bf16_f32 v32, v32, v33
	v_cvt_pk_bf16_f32 v33, v34, v35
	v_pk_mul_f32 v[34:35], v[28:29], v[92:93] op_sel_hi:[0,1]
	v_pk_mul_f32 v[36:37], v[28:29], v[94:95] op_sel_hi:[0,1]
	v_cvt_pk_bf16_f32 v34, v34, v35
	v_cvt_pk_bf16_f32 v35, v36, v37
	v_pk_mul_f32 v[36:37], v[26:27], v[96:97] op_sel_hi:[0,1]
	v_pk_mul_f32 v[38:39], v[26:27], v[98:99] op_sel_hi:[0,1]
	v_cvt_pk_bf16_f32 v36, v36, v37
	v_cvt_pk_bf16_f32 v37, v38, v39
	v_pk_mul_f32 v[38:39], v[0:1], v[162:163] op_sel_hi:[0,1]
	v_pk_mul_f32 v[40:41], v[0:1], v[164:165] op_sel_hi:[0,1]
	v_cvt_pk_bf16_f32 v38, v38, v39
	v_cvt_pk_bf16_f32 v39, v40, v41
	v_pk_mul_f32 v[40:41], v[30:31], v[100:101] op_sel_hi:[0,1]
	v_pk_mul_f32 v[42:43], v[30:31], v[102:103] op_sel_hi:[0,1]
	v_cvt_pk_bf16_f32 v40, v40, v41
	v_cvt_pk_bf16_f32 v41, v42, v43
	ds_write2_b64 v29, v[32:33], v[40:41] offset0:16 offset1:20
	v_pk_mul_f32 v[32:33], v[28:29], v[104:105] op_sel_hi:[0,1]
	v_pk_mul_f32 v[40:41], v[28:29], v[106:107] op_sel_hi:[0,1]
	v_cvt_pk_bf16_f32 v32, v32, v33
	v_cvt_pk_bf16_f32 v33, v40, v41
	ds_write2_b64 v31, v[34:35], v[32:33] offset0:48 offset1:52
	v_pk_mul_f32 v[32:33], v[26:27], v[108:109] op_sel_hi:[0,1]
	v_pk_mul_f32 v[34:35], v[26:27], v[110:111] op_sel_hi:[0,1]
	v_cvt_pk_bf16_f32 v32, v32, v33
	v_cvt_pk_bf16_f32 v33, v34, v35
	ds_write2_b64 v44, v[36:37], v[32:33] offset0:80 offset1:84
	v_pk_mul_f32 v[32:33], v[0:1], v[166:167] op_sel_hi:[0,1]
	v_pk_mul_f32 v[34:35], v[0:1], v[168:169] op_sel_hi:[0,1]
	v_cvt_pk_bf16_f32 v32, v32, v33
	v_cvt_pk_bf16_f32 v33, v34, v35
	v_pk_mul_f32 v[18:19], v[0:1], v[18:19] op_sel_hi:[0,1]
	v_pk_mul_f32 v[20:21], v[0:1], v[20:21] op_sel_hi:[0,1]
	v_pk_mul_f32 v[2:3], v[0:1], v[2:3] op_sel_hi:[0,1]
	v_pk_mul_f32 v[4:5], v[0:1], v[4:5] op_sel_hi:[0,1]
	v_lshlrev_b32_e32 v0, 3, v27
	ds_write2_b64 v45, v[38:39], v[32:33] offset0:112 offset1:116
	v_pk_mul_f32 v[32:33], v[30:31], v[112:113] op_sel_hi:[0,1]
	v_pk_mul_f32 v[34:35], v[30:31], v[114:115] op_sel_hi:[0,1]
	v_cvt_pk_bf16_f32 v18, v18, v19
	v_cvt_pk_bf16_f32 v19, v20, v21
	v_cvt_pk_bf16_f32 v2, v2, v3
	v_cvt_pk_bf16_f32 v3, v4, v5
	v_and_b32_e32 v0, 0xf8, v0
	v_cvt_pk_bf16_f32 v32, v32, v33
	v_cvt_pk_bf16_f32 v33, v34, v35
	v_pk_mul_f32 v[34:35], v[28:29], v[116:117] op_sel_hi:[0,1]
	v_pk_mul_f32 v[36:37], v[28:29], v[118:119] op_sel_hi:[0,1]
	v_pk_mul_f32 v[22:23], v[26:27], v[22:23] op_sel_hi:[0,1]
	v_pk_mul_f32 v[24:25], v[26:27], v[24:25] op_sel_hi:[0,1]
	v_pk_mul_f32 v[14:15], v[30:31], v[14:15] op_sel_hi:[0,1]
	v_pk_mul_f32 v[16:17], v[30:31], v[16:17] op_sel_hi:[0,1]
	v_pk_mul_f32 v[10:11], v[28:29], v[10:11] op_sel_hi:[0,1]
	v_pk_mul_f32 v[12:13], v[28:29], v[12:13] op_sel_hi:[0,1]
	v_pk_mul_f32 v[6:7], v[26:27], v[6:7] op_sel_hi:[0,1]
	v_pk_mul_f32 v[8:9], v[26:27], v[8:9] op_sel_hi:[0,1]
	ds_write2_b64 v45, v[18:19], v[2:3] offset0:120 offset1:124
	v_or_b32_e32 v2, s0, v0
	s_movk_i32 s1, 0x400
	v_cvt_pk_bf16_f32 v34, v34, v35
	v_cvt_pk_bf16_f32 v35, v36, v37
	v_cvt_pk_bf16_f32 v22, v22, v23
	v_cvt_pk_bf16_f32 v23, v24, v25
	v_cvt_pk_bf16_f32 v14, v14, v15
	v_cvt_pk_bf16_f32 v15, v16, v17
	v_cvt_pk_bf16_f32 v10, v10, v11
	v_cvt_pk_bf16_f32 v11, v12, v13
	v_cvt_pk_bf16_f32 v6, v6, v7
	v_cvt_pk_bf16_f32 v7, v8, v9
	v_cmp_gt_i32_e64 s[44:45], s1, v2
	ds_write2_b64 v29, v[32:33], v[14:15] offset0:24 offset1:28
	ds_write2_b64 v31, v[34:35], v[10:11] offset0:56 offset1:60
	ds_write2_b64 v44, v[22:23], v[6:7] offset0:88 offset1:92
	s_waitcnt lgkmcnt(0)
	s_barrier
	s_mov_b64 s[12:13], 11
	s_mov_b64 s[40:41], s[46:47]
	s_branch .LBB0_78
.LBB0_74:
	s_mov_b64 s[44:45], 0
	s_mov_b64 s[12:13], 11
	s_mov_b64 s[40:41], s[46:47]
	s_cbranch_execz .LBB0_78
	s_waitcnt vmcnt(6)
	v_mov_b32_e32 v58, v224
	s_waitcnt vmcnt(0)
	s_nop 0
	v_readfirstlane_b32 s0, v58
	v_bfe_u32 v59, v58, 4, 2
	s_and_b32 s14, s0, 0xffffffc0
	s_waitcnt vmcnt(4)
	v_bfe_u32 v42, v58, 2, 4
	v_sub_u32_e32 v60, 0, v59
	s_add_i32 s14, s14, s82
	v_xor_b32_e32 v0, v58, v60
	v_or_b32_e32 v6, s14, v42
	v_lshlrev_b32_e32 v0, 4, v0
	v_min_i32_e32 v4, 0x7ff, v6
	v_and_b32_e32 v0, 48, v0
	v_ashrrev_i32_e32 v5, 31, v4
	v_lshl_add_u64 v[2:3], s[56:57], 0, v[0:1]
	v_lshlrev_b64 v[4:5], 6, v[4:5]
	v_lshl_add_u64 v[34:35], v[2:3], 0, v[4:5]
	v_or_b32_e32 v4, 16, v6
	v_min_i32_e32 v4, 0x7ff, v4
	v_ashrrev_i32_e32 v5, 31, v4
	v_lshlrev_b64 v[4:5], 6, v[4:5]
	v_lshl_add_u64 v[36:37], v[2:3], 0, v[4:5]
	v_or_b32_e32 v4, 32, v6
	v_min_i32_e32 v4, 0x7ff, v4
	s_ashr_i32 s1, s0, 6
	v_ashrrev_i32_e32 v5, 31, v4
	s_and_b32 s13, s1, 1
	v_lshlrev_b64 v[4:5], 6, v[4:5]
	v_lshl_add_u64 v[38:39], v[2:3], 0, v[4:5]
	v_or_b32_e32 v4, 48, v6
	s_lshl_b32 s14, s13, 6
	v_min_i32_e32 v4, 0x7ff, v4
	v_and_b32_e32 v61, 15, v58
	s_or_b32 s14, s14, s71
	v_ashrrev_i32_e32 v5, 31, v4
	s_waitcnt vmcnt(1)
	v_or_b32_e32 v14, s14, v61
	v_lshlrev_b64 v[4:5], 6, v[4:5]
	v_ashrrev_i32_e32 v15, 31, v14
	v_lshl_add_u64 v[40:41], v[2:3], 0, v[4:5]
	v_lshlrev_b64 v[2:3], 5, v[14:15]
	v_lshl_add_u64 v[2:3], s[48:49], 0, v[2:3]
	s_barrier
	global_load_dwordx4 v[6:9], v[2:3], off offset:16
	global_load_dwordx4 v[22:25], v[2:3], off
	v_or_b32_e32 v2, 16, v14
	v_ashrrev_i32_e32 v3, 31, v2
	v_lshlrev_b64 v[2:3], 5, v[2:3]
	v_lshl_add_u64 v[10:11], s[48:49], 0, v[2:3]
	global_load_dwordx4 v[2:5], v[10:11], off offset:16
	global_load_dwordx4 v[18:21], v[10:11], off
	v_or_b32_e32 v10, 32, v14
	v_or_b32_e32 v14, 48, v14
	v_ashrrev_i32_e32 v11, 31, v10
	v_ashrrev_i32_e32 v15, 31, v14
	v_lshlrev_b64 v[10:11], 5, v[10:11]
	v_lshlrev_b64 v[14:15], 5, v[14:15]
	v_lshl_add_u64 v[16:17], s[48:49], 0, v[10:11]
	v_lshl_add_u64 v[30:31], s[48:49], 0, v[14:15]
	global_load_dwordx4 v[10:13], v[16:17], off offset:16
	global_load_dwordx4 v[26:29], v[16:17], off
	s_nop 0
	global_load_dwordx4 v[14:17], v[30:31], off offset:16
	s_nop 0
	global_load_dwordx4 v[30:33], v[30:31], off
	s_lshl_b32 s14, s1, 1
	s_waitcnt vmcnt(8)
	v_or_b32_e32 v46, s71, v42
	v_lshl_add_u32 v44, s1, 5, v46
	s_lshl_b32 s15, s14, 10
	s_or_b32 s14, s14, 1
	v_ashrrev_i32_e32 v45, 31, v44
	v_lshl_add_u32 v46, s14, 4, v46
	v_lshl_add_u64 v[42:43], s[4:5], 0, v[0:1]
	v_lshlrev_b64 v[162:163], 10, v[44:45]
	v_lshlrev_b64 v[44:45], 11, v[44:45]
	v_ashrrev_i32_e32 v47, 31, v46
	v_lshl_add_u64 v[44:45], v[42:43], 0, v[44:45]
	v_lshlrev_b64 v[164:165], 10, v[46:47]
	v_lshlrev_b64 v[46:47], 11, v[46:47]
	s_mov_b32 s42, m0
	s_mov_b32 m0, s15
	s_nop 0
	global_load_lds_dwordx4 v[44:45], off
	s_mov_b32 m0, s42
	v_lshl_add_u64 v[42:43], v[42:43], 0, v[46:47]
	s_lshl_b32 s40, s1, 12
	s_add_i32 s41, s15, 0x6000
	s_lshl_b32 s14, s14, 10
	s_mov_b32 s15, m0
	s_mov_b32 m0, s14
	s_nop 0
	global_load_lds_dwordx4 v[42:43], off
	s_mov_b32 m0, s15
	s_add_i32 s15, s40, 0x2000
	s_mov_b32 s42, m0
	s_mov_b32 m0, s15
	s_nop 0
	global_load_lds_dwordx4 v[34:35], off
	s_mov_b32 m0, s42
	s_add_i32 s42, s40, 0x2400
	s_mov_b32 s43, m0
	s_mov_b32 m0, s42
	s_nop 0
	global_load_lds_dwordx4 v[36:37], off
	s_mov_b32 m0, s43
	s_add_i32 s42, s40, 0x2800
	s_mov_b32 s43, m0
	s_mov_b32 m0, s42
	s_nop 0
	global_load_lds_dwordx4 v[38:39], off
	s_mov_b32 m0, s43
	s_add_i32 s42, s40, 0x2c00
	s_mov_b32 s43, m0
	s_mov_b32 m0, s42
	s_nop 0
	global_load_lds_dwordx4 v[40:41], off
	s_mov_b32 m0, s43
	v_lshl_add_u64 v[46:47], v[44:45], 0, 64
	s_mov_b32 s42, m0
	s_mov_b32 m0, s41
	s_nop 0
	global_load_lds_dwordx4 v[46:47], off
	s_mov_b32 m0, s42
	v_lshl_add_u64 v[48:49], v[42:43], 0, 64
	s_add_i32 s41, s14, 0x6000
	s_mov_b32 s42, m0
	s_mov_b32 m0, s41
	s_nop 0
	global_load_lds_dwordx4 v[48:49], off
	s_mov_b32 m0, s42
	v_lshrrev_b32_e32 v0, 2, v58
	s_waitcnt vmcnt(25)
	s_mov_b32 s100, 0x20000
	s_mov_b32 s101, 0
	v_lshl_add_u64 v[50:51], v[34:35], 0, s[100:101]
	s_add_i32 s41, s40, 0x8000
	s_mov_b32 s42, m0
	s_mov_b32 m0, s41
	s_nop 0
	global_load_lds_dwordx4 v[50:51], off
	s_mov_b32 m0, s42
	v_sub_u32_e32 v0, 0, v0
	v_lshl_add_u64 v[52:53], v[36:37], 0, s[100:101]
	s_add_i32 s41, s40, 0x8400
	s_mov_b32 s42, m0
	s_mov_b32 m0, s41
	s_nop 0
	global_load_lds_dwordx4 v[52:53], off
	s_mov_b32 m0, s42
	v_bitop3_b32 v0, v59, v0, 3 bitop3:0x78
	s_and_b32 s0, s0, 0x3ffff80
	v_lshl_add_u64 v[54:55], v[38:39], 0, s[100:101]
	s_add_i32 s41, s40, 0x8800
	s_mov_b32 s42, m0
	s_mov_b32 m0, s41
	s_nop 0
	global_load_lds_dwordx4 v[54:55], off
	s_mov_b32 m0, s42
	v_lshlrev_b32_e32 v176, 4, v0
	v_or_b32_e32 v0, s0, v61
	v_lshl_add_u64 v[56:57], v[40:41], 0, s[100:101]
	s_add_i32 s40, s40, 0x8c00
	s_mov_b32 s41, m0
	s_mov_b32 m0, s40
	s_nop 0
	global_load_lds_dwordx4 v[56:57], off
	s_mov_b32 m0, s41
	v_lshlrev_b32_e32 v178, 6, v0
	v_bitop3_b32 v0, v58, 3, v60 bitop3:0x48
	s_mov_b32 s100, 0x40000
	v_lshl_add_u64 v[172:173], v[34:35], 0, s[100:101]
	v_lshlrev_b32_e32 v0, 4, v0
	v_mov_b32_e32 v34, 0
	s_mov_b32 s12, 0
	s_lshl_b32 s13, s13, 12
	v_lshlrev_b32_e32 v177, 6, v61
	s_lshl_b32 s40, s1, 11
	v_lshl_add_u64 v[166:167], v[40:41], 0, s[100:101]
	v_lshl_add_u64 v[168:169], v[38:39], 0, s[100:101]
	v_lshl_add_u64 v[170:171], v[36:37], 0, s[100:101]
	v_lshl_add_u64 v[174:175], s[74:75], 0, v[0:1]
	s_mov_b64 s[0:1], 0
	v_mov_b32_e32 v35, v34
	v_mov_b32_e32 v36, v34
	v_mov_b32_e32 v37, v34
	v_mov_b32_e32 v38, v34
	v_mov_b32_e32 v39, v34
	v_mov_b32_e32 v40, v34
	v_mov_b32_e32 v41, v34
	v_mov_b32_e32 v42, v34
	v_mov_b32_e32 v43, v34
	v_mov_b32_e32 v44, v34
	v_mov_b32_e32 v45, v34
	v_mov_b32_e32 v46, v34
	v_mov_b32_e32 v47, v34
	v_mov_b32_e32 v48, v34
	v_mov_b32_e32 v49, v34
	v_mov_b32_e32 v50, v34
	v_mov_b32_e32 v51, v34
	v_mov_b32_e32 v52, v34
	v_mov_b32_e32 v53, v34
	v_mov_b32_e32 v54, v34
	v_mov_b32_e32 v55, v34
	v_mov_b32_e32 v56, v34
	v_mov_b32_e32 v57, v34
	v_mov_b32_e32 v58, v34
	v_mov_b32_e32 v59, v34
	v_mov_b32_e32 v60, v34
	v_mov_b32_e32 v61, v34
	s_waitcnt vmcnt(24)
	v_mov_b32_e32 v62, v34
	v_mov_b32_e32 v63, v34
	v_mov_b32_e32 v64, v34
	v_mov_b32_e32 v65, v34
	v_mov_b32_e32 v66, v34
	v_mov_b32_e32 v67, v34
	v_mov_b32_e32 v68, v34
	v_mov_b32_e32 v69, v34
	v_mov_b32_e32 v70, v34
	v_mov_b32_e32 v71, v34
	v_mov_b32_e32 v72, v34
	v_mov_b32_e32 v73, v34
	v_mov_b32_e32 v74, v34
	v_mov_b32_e32 v75, v34
	v_mov_b32_e32 v76, v34
	v_mov_b32_e32 v77, v34
	v_mov_b32_e32 v78, v34
	v_mov_b32_e32 v79, v34
	v_mov_b32_e32 v80, v34
	v_mov_b32_e32 v81, v34
	v_mov_b32_e32 v82, v34
	v_mov_b32_e32 v83, v34
	v_mov_b32_e32 v84, v34
	v_mov_b32_e32 v85, v34
	v_mov_b32_e32 v86, v34
	v_mov_b32_e32 v87, v34
	v_mov_b32_e32 v88, v34
	v_mov_b32_e32 v89, v34
	v_mov_b32_e32 v90, v34
	v_mov_b32_e32 v91, v34
	v_mov_b32_e32 v92, v34
	v_mov_b32_e32 v93, v34
	v_mov_b32_e32 v94, v34
	v_mov_b32_e32 v95, v34
	v_mov_b32_e32 v96, v34
	v_mov_b32_e32 v97, v34
	v_mov_b32_e32 v98, v34
	v_mov_b32_e32 v99, v34
	v_mov_b32_e32 v100, v34
	v_mov_b32_e32 v101, v34
	v_mov_b32_e32 v102, v34
	v_mov_b32_e32 v103, v34
	v_mov_b32_e32 v104, v34
	v_mov_b32_e32 v105, v34
	v_mov_b32_e32 v106, v34
	v_mov_b32_e32 v107, v34
	v_mov_b32_e32 v108, v34
	v_mov_b32_e32 v109, v34
	v_mov_b32_e32 v110, v34
	v_mov_b32_e32 v111, v34
	v_mov_b32_e32 v112, v34
	v_mov_b32_e32 v113, v34
	v_mov_b32_e32 v114, v34
	v_mov_b32_e32 v115, v34
	v_mov_b32_e32 v116, v34
	v_mov_b32_e32 v117, v34
	v_mov_b32_e32 v118, v34
	v_mov_b32_e32 v119, v34
	v_mov_b32_e32 v120, v34
	v_mov_b32_e32 v121, v34
	v_mov_b32_e32 v122, v34
	v_mov_b32_e32 v123, v34
	v_mov_b32_e32 v124, v34
	v_mov_b32_e32 v125, v34
	v_mov_b32_e32 v126, v34
	v_mov_b32_e32 v127, v34
	v_mov_b32_e32 v128, v34
	v_mov_b32_e32 v129, v34
	v_mov_b32_e32 v130, v34
	v_mov_b32_e32 v131, v34
	v_mov_b32_e32 v132, v34
	v_mov_b32_e32 v133, v34
	v_mov_b32_e32 v134, v34
	v_mov_b32_e32 v135, v34
	v_mov_b32_e32 v136, v34
	v_mov_b32_e32 v137, v34
	v_mov_b32_e32 v138, v34
	v_mov_b32_e32 v139, v34
	v_mov_b32_e32 v140, v34
	v_mov_b32_e32 v141, v34
	v_mov_b32_e32 v142, v34
	v_mov_b32_e32 v143, v34
	v_mov_b32_e32 v144, v34
	v_mov_b32_e32 v145, v34
	v_mov_b32_e32 v146, v34
	v_mov_b32_e32 v147, v34
	v_mov_b32_e32 v148, v34
	v_mov_b32_e32 v149, v34
	v_mov_b32_e32 v150, v34
	v_mov_b32_e32 v151, v34
	v_mov_b32_e32 v152, v34
	v_mov_b32_e32 v153, v34
	v_mov_b32_e32 v154, v34
	v_mov_b32_e32 v155, v34
	v_mov_b32_e32 v156, v34
	v_mov_b32_e32 v157, v34
	v_mov_b32_e32 v158, v34
	v_mov_b32_e32 v159, v34
	v_mov_b32_e32 v160, v34
	v_mov_b32_e32 v161, v34
.LBB0_76:
	s_mul_i32 s100, s0, 0x800
	s_mul_i32 s41, s12, 0x6000
	s_add_i32 s42, s41, 0xffffa000
	s_cmp_gt_i32 s12, 0
	s_waitcnt vmcnt(6)
	s_cselect_b32 s42, s42, 0xc000
	s_waitcnt lgkmcnt(0)
	s_barrier
	s_setprio 2
	v_add3_u32 v0, s41, v177, v176
	v_add_u32_e32 v0, s13, v0
	v_add3_u32 v212, s41, v178, v176
	ds_read_b128 v[196:199], v212 offset:8192
	ds_read_b128 v[180:183], v0
	ds_read_b128 v[184:187], v0 offset:1024
	ds_read_b128 v[188:191], v0 offset:2048
	ds_read_b128 v[192:195], v0 offset:3072
	ds_read_b128 v[200:203], v212 offset:9216
	ds_read_b128 v[204:207], v212 offset:10240
	ds_read_b128 v[208:211], v212 offset:11264
	ds_read_b128 v[216:219], v212 offset:12288
	ds_read_b128 v[226:229], v212 offset:13312
	ds_read_b128 v[230:233], v212 offset:14336
	ds_read_b128 v[234:237], v212 offset:15360
	v_lshl_add_u64 v[212:213], v[174:175], 0, s[0:1]
	v_lshl_add_u64 v[212:213], v[162:163], 1, v[212:213]
	s_add_i32 s43, s42, s40
	s_mov_b32 m0, s43
	s_nop 0
	global_load_lds_dwordx4 v[212:213], off
	v_lshl_add_u64 v[212:213], v[174:175], 0, s[0:1]
	v_lshl_add_u64 v[212:213], v[164:165], 1, v[212:213]
	s_add_i32 s43, s42, s14
	s_mov_b32 m0, s43
	s_nop 0
	global_load_lds_dwordx4 v[212:213], off
	s_add_i32 s42, s15, s42
	v_lshl_add_u64 v[212:213], v[172:173], 0, s[100:101]
	s_mov_b32 m0, s42
	s_nop 0
	global_load_lds_dwordx4 v[212:213], off
	v_lshl_add_u64 v[212:213], v[170:171], 0, s[100:101]
	s_add_i32 s43, s42, 0x400
	s_mov_b32 m0, s43
	s_nop 0
	global_load_lds_dwordx4 v[212:213], off
	v_lshl_add_u64 v[212:213], v[168:169], 0, s[100:101]
	s_add_i32 s43, s42, 0x800
	s_mov_b32 m0, s43
	s_nop 0
	global_load_lds_dwordx4 v[212:213], off
	s_addk_i32 s42, 0xc00
	v_lshl_add_u64 v[212:213], v[166:167], 0, s[100:101]
	s_mov_b32 m0, s42
	s_nop 0
	global_load_lds_dwordx4 v[212:213], off
	s_setprio 0
	s_waitcnt lgkmcnt(10)
	v_mfma_f32_16x16x32_bf16 v[34:37], v[196:199], v[180:183], v[34:37]
	s_waitcnt lgkmcnt(9)
	v_mfma_f32_16x16x32_bf16 v[38:41], v[196:199], v[184:187], v[38:41]
	s_waitcnt lgkmcnt(8)
	v_mfma_f32_16x16x32_bf16 v[42:45], v[196:199], v[188:191], v[42:45]
	s_waitcnt lgkmcnt(7)
	v_mfma_f32_16x16x32_bf16 v[46:49], v[196:199], v[192:195], v[46:49]
	s_waitcnt lgkmcnt(6)
	v_mfma_f32_16x16x32_bf16 v[50:53], v[200:203], v[180:183], v[50:53]
	v_mfma_f32_16x16x32_bf16 v[54:57], v[200:203], v[184:187], v[54:57]
	v_mfma_f32_16x16x32_bf16 v[58:61], v[200:203], v[188:191], v[58:61]
	v_mfma_f32_16x16x32_bf16 v[62:65], v[200:203], v[192:195], v[62:65]
	s_waitcnt lgkmcnt(5)
	v_mfma_f32_16x16x32_bf16 v[66:69], v[204:207], v[180:183], v[66:69]
	v_mfma_f32_16x16x32_bf16 v[70:73], v[204:207], v[184:187], v[70:73]
	v_mfma_f32_16x16x32_bf16 v[74:77], v[204:207], v[188:191], v[74:77]
	v_mfma_f32_16x16x32_bf16 v[78:81], v[204:207], v[192:195], v[78:81]
	s_waitcnt lgkmcnt(4)
	v_mfma_f32_16x16x32_bf16 v[82:85], v[208:211], v[180:183], v[82:85]
	v_mfma_f32_16x16x32_bf16 v[86:89], v[208:211], v[184:187], v[86:89]
	v_mfma_f32_16x16x32_bf16 v[90:93], v[208:211], v[188:191], v[90:93]
	v_mfma_f32_16x16x32_bf16 v[94:97], v[208:211], v[192:195], v[94:97]
	s_waitcnt lgkmcnt(3)
	v_mfma_f32_16x16x32_bf16 v[98:101], v[216:219], v[180:183], v[98:101]
	v_mfma_f32_16x16x32_bf16 v[102:105], v[216:219], v[184:187], v[102:105]
	v_mfma_f32_16x16x32_bf16 v[106:109], v[216:219], v[188:191], v[106:109]
	v_mfma_f32_16x16x32_bf16 v[110:113], v[216:219], v[192:195], v[110:113]
	s_waitcnt lgkmcnt(2)
	v_mfma_f32_16x16x32_bf16 v[114:117], v[226:229], v[180:183], v[114:117]
	v_mfma_f32_16x16x32_bf16 v[118:121], v[226:229], v[184:187], v[118:121]
	v_mfma_f32_16x16x32_bf16 v[122:125], v[226:229], v[188:191], v[122:125]
	v_mfma_f32_16x16x32_bf16 v[126:129], v[226:229], v[192:195], v[126:129]
	s_waitcnt lgkmcnt(1)
	v_mfma_f32_16x16x32_bf16 v[130:133], v[230:233], v[180:183], v[130:133]
	v_mfma_f32_16x16x32_bf16 v[134:137], v[230:233], v[184:187], v[134:137]
	v_mfma_f32_16x16x32_bf16 v[138:141], v[230:233], v[188:191], v[138:141]
	v_mfma_f32_16x16x32_bf16 v[142:145], v[230:233], v[192:195], v[142:145]
	s_waitcnt lgkmcnt(0)
	v_mfma_f32_16x16x32_bf16 v[146:149], v[234:237], v[180:183], v[146:149]
	v_mfma_f32_16x16x32_bf16 v[150:153], v[234:237], v[184:187], v[150:153]
	v_mfma_f32_16x16x32_bf16 v[154:157], v[234:237], v[188:191], v[154:157]
	v_mfma_f32_16x16x32_bf16 v[158:161], v[234:237], v[192:195], v[158:161]
	s_add_i32 s41, s12, 1
	s_cmp_lg_u32 s12, 2
	s_cselect_b32 s12, s41, 0
	s_add_u32 s0, s0, 64
	s_addc_u32 s1, s1, 0
	s_cmpk_eq_i32 s0, 0x780
	s_cbranch_scc0 .LBB0_76
	s_waitcnt vmcnt(6)
	v_mov_b32_e32 v162, v23
	v_mov_b32_e32 v163, v24
	v_mov_b32_e32 v23, v25
	v_mov_b32_e32 v164, v7
	v_mov_b32_e32 v165, v8
	v_pk_add_f32 v[22:23], v[162:163], v[22:23]
	v_mov_b32_e32 v7, v9
	v_pk_add_f32 v[6:7], v[164:165], v[6:7]
	v_add_f32_e32 v0, v22, v23
	v_add_f32_e32 v0, v0, v6
	v_add_f32_e32 v0, v0, v7
	v_fmamk_f32 v0, v0, 0x3a800000, v250
	s_mov_b32 s0, 0x800000
	s_waitcnt vmcnt(4)
	v_mov_b32_e32 v166, v19
	v_mov_b32_e32 v167, v20
	v_mov_b32_e32 v168, v3
	v_mul_f32_e32 v3, 0x4b800000, v0
	v_cmp_gt_f32_e32 vcc, s0, v0
	v_mov_b32_e32 v19, v21
	v_mov_b32_e32 v169, v4
	v_cndmask_b32_e32 v0, v0, v3, vcc
	v_pk_add_f32 v[6:7], v[166:167], v[18:19]
	v_mov_b32_e32 v3, v5
	v_pk_add_f32 v[2:3], v[168:169], v[2:3]
	v_add_f32_e32 v4, v6, v7
	v_add_f32_e32 v2, v4, v2
	v_add_f32_e32 v2, v2, v3
	v_fmamk_f32 v2, v2, 0x3a800000, v250
	v_mul_f32_e32 v3, 0x4b800000, v2
	v_cmp_gt_f32_e64 s[40:41], s0, v2
	s_waitcnt vmcnt(2)
	v_mov_b32_e32 v170, v27
	v_mov_b32_e32 v171, v28
	v_cndmask_b32_e64 v2, v2, v3, s[40:41]
	v_mov_b32_e32 v27, v29
	v_mov_b32_e32 v172, v11
	v_mov_b32_e32 v173, v12
	v_rsq_f32_e32 v179, v2
	v_pk_add_f32 v[2:3], v[170:171], v[26:27]
	v_mov_b32_e32 v11, v13
	v_pk_add_f32 v[4:5], v[172:173], v[10:11]
	v_add_f32_e32 v2, v2, v3
	v_add_f32_e32 v2, v2, v4
	v_add_f32_e32 v2, v2, v5
	v_fmamk_f32 v2, v2, 0x3a800000, v250
	v_mul_f32_e32 v3, 0x4b800000, v2
	v_cmp_gt_f32_e64 s[42:43], s0, v2
	s_waitcnt vmcnt(0)
	v_mov_b32_e32 v174, v31
	v_mov_b32_e32 v175, v32
	v_cndmask_b32_e64 v2, v2, v3, s[42:43]
	v_mov_b32_e32 v31, v33
	v_mov_b32_e32 v180, v15
	v_mov_b32_e32 v181, v16
	v_rsq_f32_e32 v182, v2
	v_pk_add_f32 v[2:3], v[174:175], v[30:31]
	v_mov_b32_e32 v15, v17
	v_pk_add_f32 v[4:5], v[180:181], v[14:15]
	v_add_f32_e32 v2, v2, v3
	v_add_f32_e32 v2, v2, v4
	v_add_f32_e32 v2, v2, v5
	v_fmamk_f32 v2, v2, 0x3a800000, v250
	v_mul_f32_e32 v3, 0x4b800000, v2
	v_cmp_gt_f32_e64 s[44:45], s0, v2
	s_waitcnt vmcnt(6)
	v_add_u32_e32 v183, v178, v176
	s_waitcnt lgkmcnt(0)
	s_barrier
	v_cndmask_b32_e64 v2, v2, v3, s[44:45]
	v_rsq_f32_e32 v180, v2
	ds_read_b128 v[2:5], v183 offset:15360
	ds_read_b128 v[6:9], v183 offset:14336
	ds_read_b128 v[10:13], v183 offset:13312
	ds_read_b128 v[14:17], v183 offset:12288
	ds_read_b128 v[18:21], v183 offset:11264
	ds_read_b128 v[22:25], v183 offset:10240
	ds_read_b128 v[26:29], v183 offset:9216
	ds_read_b128 v[30:33], v183 offset:8192
	v_add3_u32 v178, s13, v177, v176
	ds_read_b128 v[162:165], v178 offset:3072
	ds_read_b128 v[166:169], v178 offset:2048
	ds_read_b128 v[170:173], v178 offset:1024
	ds_read_b128 v[174:177], v178
	v_rsq_f32_e32 v0, v0
	v_mul_f32_e32 v184, 0x45800000, v179
	v_mul_f32_e32 v185, 0x45800000, v182
	v_mul_f32_e32 v186, 0x45800000, v180
	v_mul_f32_e32 v181, 0x45800000, v0
	s_waitcnt lgkmcnt(0)
	v_mfma_f32_16x16x32_bf16 v[34:37], v[30:33], v[174:177], v[34:37]
	v_mfma_f32_16x16x32_bf16 v[38:41], v[30:33], v[170:173], v[38:41]
	v_mfma_f32_16x16x32_bf16 v[42:45], v[30:33], v[166:169], v[42:45]
	v_mfma_f32_16x16x32_bf16 v[46:49], v[30:33], v[162:165], v[46:49]
	v_mfma_f32_16x16x32_bf16 v[50:53], v[26:29], v[174:177], v[50:53]
	v_mfma_f32_16x16x32_bf16 v[54:57], v[26:29], v[170:173], v[54:57]
	v_mfma_f32_16x16x32_bf16 v[58:61], v[26:29], v[166:169], v[58:61]
	v_mfma_f32_16x16x32_bf16 v[62:65], v[26:29], v[162:165], v[62:65]
	v_mfma_f32_16x16x32_bf16 v[66:69], v[22:25], v[174:177], v[66:69]
	v_mfma_f32_16x16x32_bf16 v[70:73], v[22:25], v[170:173], v[70:73]
	v_mfma_f32_16x16x32_bf16 v[74:77], v[22:25], v[166:169], v[74:77]
	v_mfma_f32_16x16x32_bf16 v[22:25], v[22:25], v[162:165], v[78:81]
	v_mfma_f32_16x16x32_bf16 v[78:81], v[18:21], v[174:177], v[82:85]
	v_mfma_f32_16x16x32_bf16 v[82:85], v[18:21], v[170:173], v[86:89]
	v_mfma_f32_16x16x32_bf16 v[86:89], v[18:21], v[166:169], v[90:93]
	v_mfma_f32_16x16x32_bf16 v[18:21], v[18:21], v[162:165], v[94:97]
	v_mfma_f32_16x16x32_bf16 v[90:93], v[14:17], v[174:177], v[98:101]
	v_mfma_f32_16x16x32_bf16 v[94:97], v[14:17], v[170:173], v[102:105]
	v_mfma_f32_16x16x32_bf16 v[98:101], v[14:17], v[166:169], v[106:109]
	v_mfma_f32_16x16x32_bf16 v[14:17], v[14:17], v[162:165], v[110:113]
	v_mfma_f32_16x16x32_bf16 v[102:105], v[10:13], v[174:177], v[114:117]
	v_mfma_f32_16x16x32_bf16 v[106:109], v[10:13], v[170:173], v[118:121]
	v_mfma_f32_16x16x32_bf16 v[110:113], v[10:13], v[166:169], v[122:125]
	v_mfma_f32_16x16x32_bf16 v[10:13], v[10:13], v[162:165], v[126:129]
	v_mfma_f32_16x16x32_bf16 v[114:117], v[6:9], v[174:177], v[130:133]
	v_mfma_f32_16x16x32_bf16 v[118:121], v[6:9], v[170:173], v[134:137]
	v_mfma_f32_16x16x32_bf16 v[122:125], v[6:9], v[166:169], v[138:141]
	v_mfma_f32_16x16x32_bf16 v[6:9], v[6:9], v[162:165], v[142:145]
	v_mfma_f32_16x16x32_bf16 v[126:129], v[2:5], v[174:177], v[146:149]
	v_mfma_f32_16x16x32_bf16 v[130:133], v[2:5], v[170:173], v[150:153]
	v_mfma_f32_16x16x32_bf16 v[134:137], v[2:5], v[166:169], v[154:157]
	v_mfma_f32_16x16x32_bf16 v[2:5], v[2:5], v[162:165], v[158:161]
	s_waitcnt vmcnt(0)
	v_cndmask_b32_e32 v30, v0, v181, vcc
	v_cndmask_b32_e64 v28, v179, v184, s[40:41]
	v_cndmask_b32_e64 v26, v182, v185, s[42:43]
	v_cndmask_b32_e64 v0, v180, v186, s[44:45]
	s_waitcnt lgkmcnt(0)
	s_barrier
	ds_read_b128 v[138:141], v178 offset:24576
	ds_read_b128 v[142:145], v178 offset:25600
	ds_read_b128 v[146:149], v178 offset:26624
	ds_read_b128 v[150:153], v178 offset:27648
	ds_read_b128 v[154:157], v183 offset:32768
	ds_read_b128 v[158:161], v183 offset:33792
	ds_read_b128 v[162:165], v183 offset:34816
	ds_read_b128 v[166:169], v183 offset:35840
	ds_read_b128 v[170:173], v183 offset:36864
	ds_read_b128 v[174:177], v183 offset:37888
	ds_read_b128 v[178:181], v183 offset:38912
	ds_read_b128 v[182:185], v183 offset:39936
	s_waitcnt lgkmcnt(7)
	v_mfma_f32_16x16x32_bf16 v[32:35], v[154:157], v[138:141], v[34:37]
	v_mfma_f32_16x16x32_bf16 v[36:39], v[154:157], v[142:145], v[38:41]
	v_mfma_f32_16x16x32_bf16 v[40:43], v[154:157], v[146:149], v[42:45]
	v_mfma_f32_16x16x32_bf16 v[44:47], v[154:157], v[150:153], v[46:49]
	s_waitcnt lgkmcnt(6)
	v_mfma_f32_16x16x32_bf16 v[48:51], v[158:161], v[138:141], v[50:53]
	v_mfma_f32_16x16x32_bf16 v[52:55], v[158:161], v[142:145], v[54:57]
	v_mfma_f32_16x16x32_bf16 v[56:59], v[158:161], v[146:149], v[58:61]
	v_mfma_f32_16x16x32_bf16 v[60:63], v[158:161], v[150:153], v[62:65]
	s_waitcnt lgkmcnt(5)
	v_mfma_f32_16x16x32_bf16 v[64:67], v[162:165], v[138:141], v[66:69]
	v_mfma_f32_16x16x32_bf16 v[68:71], v[162:165], v[142:145], v[70:73]
	v_mfma_f32_16x16x32_bf16 v[72:75], v[162:165], v[146:149], v[74:77]
	v_mfma_f32_16x16x32_bf16 v[154:157], v[162:165], v[150:153], v[22:25]
	s_waitcnt lgkmcnt(4)
	v_mfma_f32_16x16x32_bf16 v[76:79], v[166:169], v[138:141], v[78:81]
	v_mfma_f32_16x16x32_bf16 v[80:83], v[166:169], v[142:145], v[82:85]
	v_mfma_f32_16x16x32_bf16 v[84:87], v[166:169], v[146:149], v[86:89]
	v_mfma_f32_16x16x32_bf16 v[158:161], v[166:169], v[150:153], v[18:21]
	s_waitcnt lgkmcnt(3)
	v_mfma_f32_16x16x32_bf16 v[88:91], v[170:173], v[138:141], v[90:93]
	v_mfma_f32_16x16x32_bf16 v[92:95], v[170:173], v[142:145], v[94:97]
	v_mfma_f32_16x16x32_bf16 v[96:99], v[170:173], v[146:149], v[98:101]
	v_mfma_f32_16x16x32_bf16 v[162:165], v[170:173], v[150:153], v[14:17]
	s_waitcnt lgkmcnt(2)
	v_mfma_f32_16x16x32_bf16 v[100:103], v[174:177], v[138:141], v[102:105]
	v_mfma_f32_16x16x32_bf16 v[104:107], v[174:177], v[142:145], v[106:109]
	v_mfma_f32_16x16x32_bf16 v[108:111], v[174:177], v[146:149], v[110:113]
	v_mfma_f32_16x16x32_bf16 v[166:169], v[174:177], v[150:153], v[10:13]
	s_waitcnt lgkmcnt(1)
	v_mfma_f32_16x16x32_bf16 v[112:115], v[178:181], v[138:141], v[114:117]
	v_mfma_f32_16x16x32_bf16 v[116:119], v[178:181], v[142:145], v[118:121]
	v_mfma_f32_16x16x32_bf16 v[22:25], v[178:181], v[146:149], v[122:125]
	v_mfma_f32_16x16x32_bf16 v[18:21], v[178:181], v[150:153], v[6:9]
	s_waitcnt lgkmcnt(0)
	v_mfma_f32_16x16x32_bf16 v[14:17], v[182:185], v[138:141], v[126:129]
	v_mfma_f32_16x16x32_bf16 v[10:13], v[182:185], v[142:145], v[130:133]
	v_mfma_f32_16x16x32_bf16 v[6:9], v[182:185], v[146:149], v[134:137]
	v_mfma_f32_16x16x32_bf16 v[2:5], v[182:185], v[150:153], v[2:5]
	v_mov_b32_e32 v27, v224
	s_movk_i32 s0, 0x210
	v_lshrrev_b32_e32 v120, 1, v27
	v_and_b32_e32 v31, 0x7fffff80, v27
	v_and_b32_e32 v120, 24, v120
	v_and_b32_e32 v29, 0x4f, v27
	v_lshl_or_b32 v31, v31, 1, v120
	v_pk_mul_f32 v[32:33], v[30:31], v[32:33] op_sel_hi:[0,1]
	v_pk_mul_f32 v[34:35], v[30:31], v[34:35] op_sel_hi:[0,1]
	v_mad_u32_u24 v29, v29, s0, v31
	v_cvt_pk_bf16_f32 v32, v32, v33
	v_cvt_pk_bf16_f32 v33, v34, v35
	v_pk_mul_f32 v[34:35], v[28:29], v[36:37] op_sel_hi:[0,1]
	v_pk_mul_f32 v[36:37], v[28:29], v[38:39] op_sel_hi:[0,1]
	v_cvt_pk_bf16_f32 v34, v34, v35
	v_cvt_pk_bf16_f32 v35, v36, v37
	v_pk_mul_f32 v[36:37], v[26:27], v[40:41] op_sel_hi:[0,1]
	v_pk_mul_f32 v[38:39], v[26:27], v[42:43] op_sel_hi:[0,1]
	v_cvt_pk_bf16_f32 v36, v36, v37
	v_cvt_pk_bf16_f32 v37, v38, v39
	v_pk_mul_f32 v[38:39], v[0:1], v[44:45] op_sel_hi:[0,1]
	v_pk_mul_f32 v[40:41], v[0:1], v[46:47] op_sel_hi:[0,1]
	v_cvt_pk_bf16_f32 v38, v38, v39
	v_cvt_pk_bf16_f32 v39, v40, v41
	v_pk_mul_f32 v[40:41], v[30:31], v[48:49] op_sel_hi:[0,1]
	v_pk_mul_f32 v[42:43], v[30:31], v[50:51] op_sel_hi:[0,1]
	v_cvt_pk_bf16_f32 v40, v40, v41
	v_cvt_pk_bf16_f32 v41, v42, v43
	s_barrier
	ds_write2_b64 v29, v[32:33], v[40:41] offset1:4
	v_pk_mul_f32 v[32:33], v[28:29], v[52:53] op_sel_hi:[0,1]
	v_pk_mul_f32 v[40:41], v[28:29], v[54:55] op_sel_hi:[0,1]
	v_cvt_pk_bf16_f32 v32, v32, v33
	v_cvt_pk_bf16_f32 v33, v40, v41
	v_add_u32_e32 v31, 0x2000, v29
	ds_write2_b64 v31, v[34:35], v[32:33] offset0:32 offset1:36
	v_pk_mul_f32 v[32:33], v[26:27], v[56:57] op_sel_hi:[0,1]
	v_pk_mul_f32 v[34:35], v[26:27], v[58:59] op_sel_hi:[0,1]
	v_cvt_pk_bf16_f32 v32, v32, v33
	v_cvt_pk_bf16_f32 v33, v34, v35
	v_add_u32_e32 v44, 0x4000, v29
	ds_write2_b64 v44, v[36:37], v[32:33] offset0:64 offset1:68
	v_pk_mul_f32 v[32:33], v[0:1], v[60:61] op_sel_hi:[0,1]
	v_pk_mul_f32 v[34:35], v[0:1], v[62:63] op_sel_hi:[0,1]
	v_cvt_pk_bf16_f32 v32, v32, v33
	v_cvt_pk_bf16_f32 v33, v34, v35
	v_add_u32_e32 v45, 0x6000, v29
	ds_write2_b64 v45, v[38:39], v[32:33] offset0:96 offset1:100
	v_pk_mul_f32 v[32:33], v[30:31], v[64:65] op_sel_hi:[0,1]
	v_pk_mul_f32 v[34:35], v[30:31], v[66:67] op_sel_hi:[0,1]
	v_cvt_pk_bf16_f32 v32, v32, v33
	v_cvt_pk_bf16_f32 v33, v34, v35
	v_pk_mul_f32 v[34:35], v[28:29], v[68:69] op_sel_hi:[0,1]
	v_pk_mul_f32 v[36:37], v[28:29], v[70:71] op_sel_hi:[0,1]
	v_cvt_pk_bf16_f32 v34, v34, v35
	v_cvt_pk_bf16_f32 v35, v36, v37
	v_pk_mul_f32 v[36:37], v[26:27], v[72:73] op_sel_hi:[0,1]
	v_pk_mul_f32 v[38:39], v[26:27], v[74:75] op_sel_hi:[0,1]
	v_cvt_pk_bf16_f32 v36, v36, v37
	v_cvt_pk_bf16_f32 v37, v38, v39
	v_pk_mul_f32 v[38:39], v[0:1], v[154:155] op_sel_hi:[0,1]
	v_pk_mul_f32 v[40:41], v[0:1], v[156:157] op_sel_hi:[0,1]
	v_cvt_pk_bf16_f32 v38, v38, v39
	v_cvt_pk_bf16_f32 v39, v40, v41
	v_pk_mul_f32 v[40:41], v[30:31], v[76:77] op_sel_hi:[0,1]
	v_pk_mul_f32 v[42:43], v[30:31], v[78:79] op_sel_hi:[0,1]
	v_cvt_pk_bf16_f32 v40, v40, v41
	v_cvt_pk_bf16_f32 v41, v42, v43
	ds_write2_b64 v29, v[32:33], v[40:41] offset0:8 offset1:12
	v_pk_mul_f32 v[32:33], v[28:29], v[80:81] op_sel_hi:[0,1]
	v_pk_mul_f32 v[40:41], v[28:29], v[82:83] op_sel_hi:[0,1]
	v_cvt_pk_bf16_f32 v32, v32, v33
	v_cvt_pk_bf16_f32 v33, v40, v41
	ds_write2_b64 v31, v[34:35], v[32:33] offset0:40 offset1:44
	v_pk_mul_f32 v[32:33], v[26:27], v[84:85] op_sel_hi:[0,1]
	v_pk_mul_f32 v[34:35], v[26:27], v[86:87] op_sel_hi:[0,1]
	v_cvt_pk_bf16_f32 v32, v32, v33
	v_cvt_pk_bf16_f32 v33, v34, v35
	ds_write2_b64 v44, v[36:37], v[32:33] offset0:72 offset1:76
	v_pk_mul_f32 v[32:33], v[0:1], v[158:159] op_sel_hi:[0,1]
	v_pk_mul_f32 v[34:35], v[0:1], v[160:161] op_sel_hi:[0,1]
	v_cvt_pk_bf16_f32 v32, v32, v33
	v_cvt_pk_bf16_f32 v33, v34, v35
	ds_write2_b64 v45, v[38:39], v[32:33] offset0:104 offset1:108
	v_pk_mul_f32 v[32:33], v[30:31], v[88:89] op_sel_hi:[0,1]
	v_pk_mul_f32 v[34:35], v[30:31], v[90:91] op_sel_hi:[0,1]
	v_cvt_pk_bf16_f32 v32, v32, v33
	v_cvt_pk_bf16_f32 v33, v34, v35
	v_pk_mul_f32 v[34:35], v[28:29], v[92:93] op_sel_hi:[0,1]
	v_pk_mul_f32 v[36:37], v[28:29], v[94:95] op_sel_hi:[0,1]
	v_cvt_pk_bf16_f32 v34, v34, v35
	v_cvt_pk_bf16_f32 v35, v36, v37
	v_pk_mul_f32 v[36:37], v[26:27], v[96:97] op_sel_hi:[0,1]
	v_pk_mul_f32 v[38:39], v[26:27], v[98:99] op_sel_hi:[0,1]
	v_cvt_pk_bf16_f32 v36, v36, v37
	v_cvt_pk_bf16_f32 v37, v38, v39
	v_pk_mul_f32 v[38:39], v[0:1], v[162:163] op_sel_hi:[0,1]
	v_pk_mul_f32 v[40:41], v[0:1], v[164:165] op_sel_hi:[0,1]
	v_cvt_pk_bf16_f32 v38, v38, v39
	v_cvt_pk_bf16_f32 v39, v40, v41
	v_pk_mul_f32 v[40:41], v[30:31], v[100:101] op_sel_hi:[0,1]
	v_pk_mul_f32 v[42:43], v[30:31], v[102:103] op_sel_hi:[0,1]
	v_cvt_pk_bf16_f32 v40, v40, v41
	v_cvt_pk_bf16_f32 v41, v42, v43
	ds_write2_b64 v29, v[32:33], v[40:41] offset0:16 offset1:20
	v_pk_mul_f32 v[32:33], v[28:29], v[104:105] op_sel_hi:[0,1]
	v_pk_mul_f32 v[40:41], v[28:29], v[106:107] op_sel_hi:[0,1]
	v_cvt_pk_bf16_f32 v32, v32, v33
	v_cvt_pk_bf16_f32 v33, v40, v41
	ds_write2_b64 v31, v[34:35], v[32:33] offset0:48 offset1:52
	v_pk_mul_f32 v[32:33], v[26:27], v[108:109] op_sel_hi:[0,1]
	v_pk_mul_f32 v[34:35], v[26:27], v[110:111] op_sel_hi:[0,1]
	v_cvt_pk_bf16_f32 v32, v32, v33
	v_cvt_pk_bf16_f32 v33, v34, v35
	ds_write2_b64 v44, v[36:37], v[32:33] offset0:80 offset1:84
	v_pk_mul_f32 v[32:33], v[0:1], v[166:167] op_sel_hi:[0,1]
	v_pk_mul_f32 v[34:35], v[0:1], v[168:169] op_sel_hi:[0,1]
	v_cvt_pk_bf16_f32 v32, v32, v33
	v_cvt_pk_bf16_f32 v33, v34, v35
	v_pk_mul_f32 v[18:19], v[0:1], v[18:19] op_sel_hi:[0,1]
	v_pk_mul_f32 v[20:21], v[0:1], v[20:21] op_sel_hi:[0,1]
	v_pk_mul_f32 v[2:3], v[0:1], v[2:3] op_sel_hi:[0,1]
	v_pk_mul_f32 v[4:5], v[0:1], v[4:5] op_sel_hi:[0,1]
	v_lshlrev_b32_e32 v0, 3, v27
	ds_write2_b64 v45, v[38:39], v[32:33] offset0:112 offset1:116
	v_pk_mul_f32 v[32:33], v[30:31], v[112:113] op_sel_hi:[0,1]
	v_pk_mul_f32 v[34:35], v[30:31], v[114:115] op_sel_hi:[0,1]
	v_cvt_pk_bf16_f32 v18, v18, v19
	v_cvt_pk_bf16_f32 v19, v20, v21
	v_cvt_pk_bf16_f32 v2, v2, v3
	v_cvt_pk_bf16_f32 v3, v4, v5
	v_and_b32_e32 v0, 0xf8, v0
	v_cvt_pk_bf16_f32 v32, v32, v33
	v_cvt_pk_bf16_f32 v33, v34, v35
	v_pk_mul_f32 v[34:35], v[28:29], v[116:117] op_sel_hi:[0,1]
	v_pk_mul_f32 v[36:37], v[28:29], v[118:119] op_sel_hi:[0,1]
	v_pk_mul_f32 v[22:23], v[26:27], v[22:23] op_sel_hi:[0,1]
	v_pk_mul_f32 v[24:25], v[26:27], v[24:25] op_sel_hi:[0,1]
	v_pk_mul_f32 v[14:15], v[30:31], v[14:15] op_sel_hi:[0,1]
	v_pk_mul_f32 v[16:17], v[30:31], v[16:17] op_sel_hi:[0,1]
	v_pk_mul_f32 v[10:11], v[28:29], v[10:11] op_sel_hi:[0,1]
	v_pk_mul_f32 v[12:13], v[28:29], v[12:13] op_sel_hi:[0,1]
	v_pk_mul_f32 v[6:7], v[26:27], v[6:7] op_sel_hi:[0,1]
	v_pk_mul_f32 v[8:9], v[26:27], v[8:9] op_sel_hi:[0,1]
	ds_write2_b64 v45, v[18:19], v[2:3] offset0:120 offset1:124
	v_or_b32_e32 v2, s82, v0
	s_movk_i32 s0, 0x800
	v_cvt_pk_bf16_f32 v34, v34, v35
	v_cvt_pk_bf16_f32 v35, v36, v37
	v_cvt_pk_bf16_f32 v22, v22, v23
	v_cvt_pk_bf16_f32 v23, v24, v25
	v_cvt_pk_bf16_f32 v14, v14, v15
	v_cvt_pk_bf16_f32 v15, v16, v17
	v_cvt_pk_bf16_f32 v10, v10, v11
	v_cvt_pk_bf16_f32 v11, v12, v13
	v_cvt_pk_bf16_f32 v6, v6, v7
	v_cvt_pk_bf16_f32 v7, v8, v9
	v_cmp_gt_i32_e64 s[44:45], s0, v2
	s_mov_b64 s[12:13], 12
	s_mov_b64 s[40:41], s[54:55]
	s_mov_b32 s0, s82
	ds_write2_b64 v29, v[32:33], v[14:15] offset0:24 offset1:28
	ds_write2_b64 v31, v[34:35], v[10:11] offset0:56 offset1:60
	ds_write2_b64 v44, v[22:23], v[6:7] offset0:88 offset1:92
	s_waitcnt lgkmcnt(0)
	s_barrier

.LBB0_642:
	s_ashr_i32 s13, s12, 31
	s_lshr_b32 s13, s13, 28
	s_add_i32 s13, s12, s13
	s_and_b32 s40, s13, 0x1fffff0
	s_sub_i32 s12, s12, s40
	s_add_i32 s12, s12, s15
	s_lshl_b32 s57, s12, 7
	s_lshl_b32 s12, s13, 4
	s_waitcnt vmcnt(6)
	v_mov_b32_e32 v58, v224
	s_and_b32 s54, s12, 0xffffff00
	s_waitcnt vmcnt(0)
	s_waitcnt lgkmcnt(0)
	v_readfirstlane_b32 s12, v58
	v_bfe_u32 v59, v58, 4, 2
	s_and_b32 s40, s12, 0xffffffc0
	s_waitcnt vmcnt(4)
	v_bfe_u32 v42, v58, 2, 4
	v_sub_u32_e32 v60, 0, v59
	s_add_i32 s40, s40, s54
	v_xor_b32_e32 v0, v58, v60
	v_or_b32_e32 v6, s40, v42
	v_lshlrev_b32_e32 v0, 4, v0
	v_min_i32_e32 v4, 0xa2f, v6
	v_and_b32_e32 v0, 48, v0
	v_ashrrev_i32_e32 v5, 31, v4
	v_lshl_add_u64 v[2:3], s[48:49], 0, v[0:1]
	v_lshlrev_b64 v[4:5], 6, v[4:5]
	v_lshl_add_u64 v[34:35], v[2:3], 0, v[4:5]
	v_or_b32_e32 v4, 16, v6
	v_min_i32_e32 v4, 0xa2f, v4
	v_ashrrev_i32_e32 v5, 31, v4
	v_lshlrev_b64 v[4:5], 6, v[4:5]
	v_lshl_add_u64 v[36:37], v[2:3], 0, v[4:5]
	v_or_b32_e32 v4, 32, v6
	v_min_i32_e32 v4, 0xa2f, v4
	s_ashr_i32 s13, s12, 6
	v_ashrrev_i32_e32 v5, 31, v4
	s_and_b32 s42, s13, 1
	v_lshlrev_b64 v[4:5], 6, v[4:5]
	v_lshl_add_u64 v[38:39], v[2:3], 0, v[4:5]
	v_or_b32_e32 v4, 48, v6
	s_lshl_b32 s40, s42, 6
	v_min_i32_e32 v4, 0xa2f, v4
	v_and_b32_e32 v61, 15, v58
	s_or_b32 s40, s40, s57
	v_ashrrev_i32_e32 v5, 31, v4
	s_waitcnt vmcnt(1)
	v_or_b32_e32 v14, s40, v61
	v_lshlrev_b64 v[4:5], 6, v[4:5]
	v_ashrrev_i32_e32 v15, 31, v14
	v_lshl_add_u64 v[40:41], v[2:3], 0, v[4:5]
	v_lshlrev_b64 v[2:3], 5, v[14:15]
	v_lshl_add_u64 v[6:7], s[46:47], 0, v[2:3]
	s_barrier
	global_load_dwordx4 v[2:5], v[6:7], off offset:16
	global_load_dwordx4 v[18:21], v[6:7], off
	v_or_b32_e32 v6, 16, v14
	v_ashrrev_i32_e32 v7, 31, v6
	v_lshlrev_b64 v[6:7], 5, v[6:7]
	v_lshl_add_u64 v[10:11], s[46:47], 0, v[6:7]
	global_load_dwordx4 v[6:9], v[10:11], off offset:16
	global_load_dwordx4 v[22:25], v[10:11], off
	v_or_b32_e32 v10, 32, v14
	v_or_b32_e32 v14, 48, v14
	v_ashrrev_i32_e32 v11, 31, v10
	v_ashrrev_i32_e32 v15, 31, v14
	v_lshlrev_b64 v[10:11], 5, v[10:11]
	v_lshlrev_b64 v[14:15], 5, v[14:15]
	v_lshl_add_u64 v[16:17], s[46:47], 0, v[10:11]
	v_lshl_add_u64 v[30:31], s[46:47], 0, v[14:15]
	global_load_dwordx4 v[10:13], v[16:17], off offset:16
	global_load_dwordx4 v[26:29], v[16:17], off
	s_nop 0
	global_load_dwordx4 v[14:17], v[30:31], off offset:16
	s_nop 0
	global_load_dwordx4 v[30:33], v[30:31], off
	s_lshl_b32 s40, s13, 1
	s_waitcnt vmcnt(8)
	v_or_b32_e32 v46, s57, v42
	v_lshl_add_u32 v44, s13, 5, v46
	s_lshl_b32 s41, s40, 10
	s_or_b32 s40, s40, 1
	v_ashrrev_i32_e32 v45, 31, v44
	v_lshl_add_u32 v46, s40, 4, v46
	v_lshl_add_u64 v[42:43], s[0:1], 0, v[0:1]
	v_lshlrev_b64 v[162:163], 10, v[44:45]
	v_lshlrev_b64 v[44:45], 11, v[44:45]
	v_ashrrev_i32_e32 v47, 31, v46
	v_lshl_add_u64 v[44:45], v[42:43], 0, v[44:45]
	v_lshlrev_b64 v[164:165], 10, v[46:47]
	v_lshlrev_b64 v[46:47], 11, v[46:47]
	s_mov_b32 s45, m0
	s_mov_b32 m0, s41
	s_nop 0
	global_load_lds_dwordx4 v[44:45], off
	s_mov_b32 m0, s45
	v_lshl_add_u64 v[42:43], v[42:43], 0, v[46:47]
	s_lshl_b32 s43, s13, 12
	s_add_i32 s44, s41, 0x6000
	s_lshl_b32 s40, s40, 10
	s_mov_b32 s41, m0
	s_mov_b32 m0, s40
	s_nop 0
	global_load_lds_dwordx4 v[42:43], off
	s_mov_b32 m0, s41
	s_add_i32 s41, s43, 0x2000
	s_mov_b32 s45, m0
	s_mov_b32 m0, s41
	s_nop 0
	global_load_lds_dwordx4 v[34:35], off
	s_mov_b32 m0, s45
	s_add_i32 s45, s43, 0x2400
	s_mov_b32 s55, m0
	s_mov_b32 m0, s45
	s_nop 0
	global_load_lds_dwordx4 v[36:37], off
	s_mov_b32 m0, s55
	s_add_i32 s45, s43, 0x2800
	s_mov_b32 s55, m0
	s_mov_b32 m0, s45
	s_nop 0
	global_load_lds_dwordx4 v[38:39], off
	s_mov_b32 m0, s55
	s_add_i32 s45, s43, 0x2c00
	s_mov_b32 s55, m0
	s_mov_b32 m0, s45
	s_nop 0
	global_load_lds_dwordx4 v[40:41], off
	s_mov_b32 m0, s55
	v_lshl_add_u64 v[46:47], v[44:45], 0, 64
	s_mov_b32 s45, m0
	s_mov_b32 m0, s44
	s_nop 0
	global_load_lds_dwordx4 v[46:47], off
	s_mov_b32 m0, s45
	v_lshl_add_u64 v[48:49], v[42:43], 0, 64
	s_add_i32 s44, s40, 0x6000
	s_mov_b32 s45, m0
	s_mov_b32 m0, s44
	s_nop 0
	global_load_lds_dwordx4 v[48:49], off
	s_mov_b32 m0, s45
	v_lshrrev_b32_e32 v0, 2, v58
	s_mov_b32 s100, 0x28c00
	s_mov_b32 s101, 0
	v_lshl_add_u64 v[50:51], v[34:35], 0, s[100:101]
	s_add_i32 s44, s43, 0x8000
	s_mov_b32 s45, m0
	s_mov_b32 m0, s44
	s_nop 0
	global_load_lds_dwordx4 v[50:51], off
	s_mov_b32 m0, s45
	v_sub_u32_e32 v0, 0, v0
	v_lshl_add_u64 v[52:53], v[36:37], 0, s[100:101]
	s_add_i32 s44, s43, 0x8400
	s_mov_b32 s45, m0
	s_mov_b32 m0, s44
	s_nop 0
	global_load_lds_dwordx4 v[52:53], off
	s_mov_b32 m0, s45
	v_bitop3_b32 v0, v59, v0, 3 bitop3:0x78
	s_and_b32 s12, s12, 0x3ffff80
	v_lshl_add_u64 v[54:55], v[38:39], 0, s[100:101]
	s_add_i32 s44, s43, 0x8800
	s_mov_b32 s45, m0
	s_mov_b32 m0, s44
	s_nop 0
	global_load_lds_dwordx4 v[54:55], off
	s_mov_b32 m0, s45
	v_lshlrev_b32_e32 v176, 4, v0
	v_or_b32_e32 v0, s12, v61
	v_lshl_add_u64 v[56:57], v[40:41], 0, s[100:101]
	s_add_i32 s43, s43, 0x8c00
	s_mov_b32 s44, m0
	s_mov_b32 m0, s43
	s_nop 0
	global_load_lds_dwordx4 v[56:57], off
	s_mov_b32 m0, s44
	v_lshlrev_b32_e32 v178, 6, v0
	v_bitop3_b32 v0, v58, 3, v60 bitop3:0x48
	s_mov_b32 s100, 0x51800
	v_lshl_add_u64 v[172:173], v[34:35], 0, s[100:101]
	v_lshlrev_b32_e32 v0, 4, v0
	v_mov_b32_e32 v34, 0
	s_lshl_b32 s55, s42, 12
	v_lshlrev_b32_e32 v177, 6, v61
	s_lshl_b32 s42, s13, 11
	v_lshl_add_u64 v[166:167], v[40:41], 0, s[100:101]
	v_lshl_add_u64 v[168:169], v[38:39], 0, s[100:101]
	v_lshl_add_u64 v[170:171], v[36:37], 0, s[100:101]
	v_lshl_add_u64 v[174:175], s[52:53], 0, v[0:1]
	s_mov_b64 s[12:13], 0
	s_mov_b32 s43, 0
	v_mov_b32_e32 v35, v34
	v_mov_b32_e32 v36, v34
	v_mov_b32_e32 v37, v34
	v_mov_b32_e32 v38, v34
	v_mov_b32_e32 v39, v34
	v_mov_b32_e32 v40, v34
	v_mov_b32_e32 v41, v34
	v_mov_b32_e32 v42, v34
	v_mov_b32_e32 v43, v34
	v_mov_b32_e32 v44, v34
	v_mov_b32_e32 v45, v34
	v_mov_b32_e32 v46, v34
	v_mov_b32_e32 v47, v34
	v_mov_b32_e32 v48, v34
	v_mov_b32_e32 v49, v34
	v_mov_b32_e32 v50, v34
	v_mov_b32_e32 v51, v34
	v_mov_b32_e32 v52, v34
	v_mov_b32_e32 v53, v34
	v_mov_b32_e32 v54, v34
	v_mov_b32_e32 v55, v34
	v_mov_b32_e32 v56, v34
	v_mov_b32_e32 v57, v34
	v_mov_b32_e32 v58, v34
	v_mov_b32_e32 v59, v34
	v_mov_b32_e32 v60, v34
	v_mov_b32_e32 v61, v34
	v_mov_b32_e32 v62, v34
	v_mov_b32_e32 v63, v34
	v_mov_b32_e32 v64, v34
	v_mov_b32_e32 v65, v34
	v_mov_b32_e32 v66, v34
	v_mov_b32_e32 v67, v34
	v_mov_b32_e32 v68, v34
	v_mov_b32_e32 v69, v34
	v_mov_b32_e32 v70, v34
	v_mov_b32_e32 v71, v34
	v_mov_b32_e32 v72, v34
	v_mov_b32_e32 v73, v34
	v_mov_b32_e32 v74, v34
	v_mov_b32_e32 v75, v34
	v_mov_b32_e32 v76, v34
	v_mov_b32_e32 v77, v34
	v_mov_b32_e32 v78, v34
	v_mov_b32_e32 v79, v34
	v_mov_b32_e32 v80, v34
	v_mov_b32_e32 v81, v34
	v_mov_b32_e32 v82, v34
	v_mov_b32_e32 v83, v34
	v_mov_b32_e32 v84, v34
	v_mov_b32_e32 v85, v34
	v_mov_b32_e32 v86, v34
	v_mov_b32_e32 v87, v34
	v_mov_b32_e32 v88, v34
	v_mov_b32_e32 v89, v34
	v_mov_b32_e32 v90, v34
	v_mov_b32_e32 v91, v34
	v_mov_b32_e32 v92, v34
	v_mov_b32_e32 v93, v34
	v_mov_b32_e32 v94, v34
	v_mov_b32_e32 v95, v34
	v_mov_b32_e32 v96, v34
	v_mov_b32_e32 v97, v34
	v_mov_b32_e32 v98, v34
	v_mov_b32_e32 v99, v34
	v_mov_b32_e32 v100, v34
	v_mov_b32_e32 v101, v34
	v_mov_b32_e32 v102, v34
	v_mov_b32_e32 v103, v34
	v_mov_b32_e32 v104, v34
	v_mov_b32_e32 v105, v34
	v_mov_b32_e32 v106, v34
	v_mov_b32_e32 v107, v34
	v_mov_b32_e32 v108, v34
	v_mov_b32_e32 v109, v34
	v_mov_b32_e32 v110, v34
	v_mov_b32_e32 v111, v34
	v_mov_b32_e32 v112, v34
	v_mov_b32_e32 v113, v34
	v_mov_b32_e32 v114, v34
	v_mov_b32_e32 v115, v34
	v_mov_b32_e32 v116, v34
	v_mov_b32_e32 v117, v34
	v_mov_b32_e32 v118, v34
	v_mov_b32_e32 v119, v34
	v_mov_b32_e32 v120, v34
	v_mov_b32_e32 v121, v34
	v_mov_b32_e32 v122, v34
	v_mov_b32_e32 v123, v34
	v_mov_b32_e32 v124, v34
	v_mov_b32_e32 v125, v34
	v_mov_b32_e32 v126, v34
	v_mov_b32_e32 v127, v34
	v_mov_b32_e32 v128, v34
	v_mov_b32_e32 v129, v34
	v_mov_b32_e32 v130, v34
	v_mov_b32_e32 v131, v34
	v_mov_b32_e32 v132, v34
	v_mov_b32_e32 v133, v34
	v_mov_b32_e32 v134, v34
	v_mov_b32_e32 v135, v34
	v_mov_b32_e32 v136, v34
	v_mov_b32_e32 v137, v34
	v_mov_b32_e32 v138, v34
	v_mov_b32_e32 v139, v34
	v_mov_b32_e32 v140, v34
	v_mov_b32_e32 v141, v34
	v_mov_b32_e32 v142, v34
	v_mov_b32_e32 v143, v34
	v_mov_b32_e32 v144, v34
	v_mov_b32_e32 v145, v34
	v_mov_b32_e32 v146, v34
	v_mov_b32_e32 v147, v34
	v_mov_b32_e32 v148, v34
	v_mov_b32_e32 v149, v34
	v_mov_b32_e32 v150, v34
	v_mov_b32_e32 v151, v34
	v_mov_b32_e32 v152, v34
	v_mov_b32_e32 v153, v34
	v_mov_b32_e32 v154, v34
	v_mov_b32_e32 v155, v34
	v_mov_b32_e32 v156, v34
	v_mov_b32_e32 v157, v34
	v_mov_b32_e32 v158, v34
	v_mov_b32_e32 v159, v34
	v_mov_b32_e32 v160, v34
	v_mov_b32_e32 v161, v34
.LBB0_643:
	s_mul_i32 s100, s12, 0xa30
	s_mul_i32 s44, s43, 0x6000
	s_add_i32 s45, s44, 0xffffa000
	s_cmp_gt_i32 s43, 0
	s_waitcnt vmcnt(6)
	s_cselect_b32 s45, s45, 0xc000
	s_waitcnt lgkmcnt(0)
	s_barrier
	s_setprio 2
	v_add3_u32 v0, s44, v177, v176
	v_add_u32_e32 v0, s55, v0
	v_add3_u32 v212, s44, v178, v176
	ds_read_b128 v[202:205], v212 offset:8192
	ds_read_b128 v[180:183], v0
	ds_read_b128 v[184:187], v0 offset:1024
	ds_read_b128 v[188:191], v0 offset:2048
	ds_read_b128 v[198:201], v0 offset:3072
	ds_read_b128 v[234:237], v212 offset:9216
	ds_read_b128 v[238:241], v212 offset:10240
	ds_read_b128 v[242:245], v212 offset:11264
	ds_read_b128 v[246:249], v212 offset:12288
	ds_read_b128 v[226:229], v212 offset:13312
	ds_read_b128 v[216:219], v212 offset:14336
	ds_read_b128 v[230:233], v212 offset:15360
	v_lshl_add_u64 v[212:213], v[174:175], 0, s[12:13]
	v_lshl_add_u64 v[212:213], v[162:163], 1, v[212:213]
	s_add_i32 s68, s45, s42
	s_mov_b32 m0, s68
	s_nop 0
	global_load_lds_dwordx4 v[212:213], off
	v_lshl_add_u64 v[212:213], v[174:175], 0, s[12:13]
	v_lshl_add_u64 v[212:213], v[164:165], 1, v[212:213]
	s_add_i32 s68, s45, s40
	s_mov_b32 m0, s68
	s_nop 0
	global_load_lds_dwordx4 v[212:213], off
	s_add_i32 s45, s41, s45
	v_lshl_add_u64 v[212:213], v[172:173], 0, s[100:101]
	s_mov_b32 m0, s45
	s_nop 0
	global_load_lds_dwordx4 v[212:213], off
	v_lshl_add_u64 v[212:213], v[170:171], 0, s[100:101]
	s_add_i32 s68, s45, 0x400
	s_mov_b32 m0, s68
	s_nop 0
	global_load_lds_dwordx4 v[212:213], off
	v_lshl_add_u64 v[212:213], v[168:169], 0, s[100:101]
	s_add_i32 s68, s45, 0x800
	s_mov_b32 m0, s68
	s_nop 0
	global_load_lds_dwordx4 v[212:213], off
	s_addk_i32 s45, 0xc00
	v_lshl_add_u64 v[212:213], v[166:167], 0, s[100:101]
	s_mov_b32 m0, s45
	s_nop 0
	global_load_lds_dwordx4 v[212:213], off
	s_setprio 0
	s_waitcnt lgkmcnt(10)
	v_mfma_f32_16x16x32_bf16 v[34:37], v[202:205], v[180:183], v[34:37]
	s_waitcnt lgkmcnt(9)
	v_mfma_f32_16x16x32_bf16 v[38:41], v[202:205], v[184:187], v[38:41]
	s_waitcnt lgkmcnt(8)
	v_mfma_f32_16x16x32_bf16 v[42:45], v[202:205], v[188:191], v[42:45]
	s_waitcnt lgkmcnt(7)
	v_mfma_f32_16x16x32_bf16 v[46:49], v[202:205], v[198:201], v[46:49]
	s_waitcnt lgkmcnt(6)
	v_mfma_f32_16x16x32_bf16 v[50:53], v[234:237], v[180:183], v[50:53]
	v_mfma_f32_16x16x32_bf16 v[54:57], v[234:237], v[184:187], v[54:57]
	v_mfma_f32_16x16x32_bf16 v[58:61], v[234:237], v[188:191], v[58:61]
	v_mfma_f32_16x16x32_bf16 v[62:65], v[234:237], v[198:201], v[62:65]
	s_waitcnt lgkmcnt(5)
	v_mfma_f32_16x16x32_bf16 v[66:69], v[238:241], v[180:183], v[66:69]
	v_mfma_f32_16x16x32_bf16 v[70:73], v[238:241], v[184:187], v[70:73]
	v_mfma_f32_16x16x32_bf16 v[74:77], v[238:241], v[188:191], v[74:77]
	v_mfma_f32_16x16x32_bf16 v[78:81], v[238:241], v[198:201], v[78:81]
	s_waitcnt lgkmcnt(4)
	v_mfma_f32_16x16x32_bf16 v[82:85], v[242:245], v[180:183], v[82:85]
	v_mfma_f32_16x16x32_bf16 v[86:89], v[242:245], v[184:187], v[86:89]
	v_mfma_f32_16x16x32_bf16 v[90:93], v[242:245], v[188:191], v[90:93]
	v_mfma_f32_16x16x32_bf16 v[94:97], v[242:245], v[198:201], v[94:97]
	s_waitcnt lgkmcnt(3)
	v_mfma_f32_16x16x32_bf16 v[98:101], v[246:249], v[180:183], v[98:101]
	v_mfma_f32_16x16x32_bf16 v[102:105], v[246:249], v[184:187], v[102:105]
	v_mfma_f32_16x16x32_bf16 v[106:109], v[246:249], v[188:191], v[106:109]
	v_mfma_f32_16x16x32_bf16 v[110:113], v[246:249], v[198:201], v[110:113]
	s_waitcnt lgkmcnt(2)
	v_mfma_f32_16x16x32_bf16 v[114:117], v[226:229], v[180:183], v[114:117]
	v_mfma_f32_16x16x32_bf16 v[118:121], v[226:229], v[184:187], v[118:121]
	v_mfma_f32_16x16x32_bf16 v[122:125], v[226:229], v[188:191], v[122:125]
	v_mfma_f32_16x16x32_bf16 v[126:129], v[226:229], v[198:201], v[126:129]
	s_waitcnt lgkmcnt(1)
	v_mfma_f32_16x16x32_bf16 v[130:133], v[216:219], v[180:183], v[130:133]
	v_mfma_f32_16x16x32_bf16 v[134:137], v[216:219], v[184:187], v[134:137]
	v_mfma_f32_16x16x32_bf16 v[138:141], v[216:219], v[188:191], v[138:141]
	v_mfma_f32_16x16x32_bf16 v[142:145], v[216:219], v[198:201], v[142:145]
	s_waitcnt lgkmcnt(0)
	v_mfma_f32_16x16x32_bf16 v[146:149], v[230:233], v[180:183], v[146:149]
	v_mfma_f32_16x16x32_bf16 v[150:153], v[230:233], v[184:187], v[150:153]
	v_mfma_f32_16x16x32_bf16 v[154:157], v[230:233], v[188:191], v[154:157]
	v_mfma_f32_16x16x32_bf16 v[158:161], v[230:233], v[198:201], v[158:161]
	s_add_i32 s44, s43, 1
	s_cmp_lg_u32 s43, 2
	s_cselect_b32 s43, s44, 0
	s_add_u32 s12, s12, 64
	s_addc_u32 s13, s13, 0
	s_cmpk_eq_i32 s12, 0x780
	s_cbranch_scc0 .LBB0_643
	s_waitcnt vmcnt(6)
	v_mov_b32_e32 v162, v19
	v_mov_b32_e32 v163, v20
	v_mov_b32_e32 v19, v21
	v_mov_b32_e32 v164, v3
	v_mov_b32_e32 v165, v4
	v_pk_add_f32 v[18:19], v[162:163], v[18:19]
	v_mov_b32_e32 v3, v5
	v_pk_add_f32 v[2:3], v[164:165], v[2:3]
	v_add_f32_e32 v0, v18, v19
	v_add_f32_e32 v0, v0, v2
	v_add_f32_e32 v0, v0, v3
	v_fmamk_f32 v0, v0, 0x3a800000, v250
	s_waitcnt vmcnt(4)
	v_mov_b32_e32 v166, v23
	v_mov_b32_e32 v167, v24
	v_mul_f32_e32 v2, 0x4b800000, v0
	v_cmp_gt_f32_e32 vcc, s80, v0
	v_mov_b32_e32 v23, v25
	v_mov_b32_e32 v168, v7
	v_mov_b32_e32 v169, v8
	v_cndmask_b32_e32 v0, v0, v2, vcc
	v_pk_add_f32 v[2:3], v[166:167], v[22:23]
	v_mov_b32_e32 v7, v9
	v_pk_add_f32 v[4:5], v[168:169], v[6:7]
	v_add_f32_e32 v2, v2, v3
	v_add_f32_e32 v2, v2, v4
	v_add_f32_e32 v2, v2, v5
	v_fmamk_f32 v2, v2, 0x3a800000, v250
	v_mul_f32_e32 v3, 0x4b800000, v2
	v_cmp_gt_f32_e64 s[40:41], s80, v2
	s_waitcnt vmcnt(2)
	v_mov_b32_e32 v170, v27
	v_mov_b32_e32 v171, v28
	v_cndmask_b32_e64 v2, v2, v3, s[40:41]
	v_mov_b32_e32 v27, v29
	v_mov_b32_e32 v172, v11
	v_mov_b32_e32 v173, v12
	v_rsq_f32_e32 v179, v2
	v_pk_add_f32 v[2:3], v[170:171], v[26:27]
	v_mov_b32_e32 v11, v13
	v_pk_add_f32 v[4:5], v[172:173], v[10:11]
	v_add_f32_e32 v2, v2, v3
	v_add_f32_e32 v2, v2, v4
	v_add_f32_e32 v2, v2, v5
	v_fmamk_f32 v2, v2, 0x3a800000, v250
	v_mul_f32_e32 v3, 0x4b800000, v2
	v_cmp_gt_f32_e64 s[42:43], s80, v2
	s_waitcnt vmcnt(0)
	v_mov_b32_e32 v174, v31
	v_mov_b32_e32 v175, v32
	v_cndmask_b32_e64 v2, v2, v3, s[42:43]
	v_mov_b32_e32 v31, v33
	v_mov_b32_e32 v180, v15
	v_mov_b32_e32 v181, v16
	v_rsq_f32_e32 v182, v2
	v_pk_add_f32 v[2:3], v[174:175], v[30:31]
	v_mov_b32_e32 v15, v17
	v_pk_add_f32 v[4:5], v[180:181], v[14:15]
	v_add_f32_e32 v2, v2, v3
	v_add_f32_e32 v2, v2, v4
	v_add_f32_e32 v2, v2, v5
	v_fmamk_f32 v2, v2, 0x3a800000, v250
	v_mul_f32_e32 v3, 0x4b800000, v2
	v_cmp_gt_f32_e64 s[44:45], s80, v2
	s_waitcnt vmcnt(6)
	v_add_u32_e32 v183, v178, v176
	s_waitcnt lgkmcnt(0)
	s_barrier
	v_cndmask_b32_e64 v2, v2, v3, s[44:45]
	v_rsq_f32_e32 v180, v2
	ds_read_b128 v[2:5], v183 offset:15360
	ds_read_b128 v[6:9], v183 offset:14336
	ds_read_b128 v[10:13], v183 offset:13312
	ds_read_b128 v[14:17], v183 offset:12288
	ds_read_b128 v[18:21], v183 offset:11264
	ds_read_b128 v[22:25], v183 offset:10240
	ds_read_b128 v[26:29], v183 offset:9216
	ds_read_b128 v[30:33], v183 offset:8192
	v_add3_u32 v178, s55, v177, v176
	ds_read_b128 v[162:165], v178 offset:3072
	ds_read_b128 v[166:169], v178 offset:2048
	ds_read_b128 v[170:173], v178 offset:1024
	ds_read_b128 v[174:177], v178
	v_rsq_f32_e32 v0, v0
	v_mul_f32_e32 v184, 0x45800000, v179
	v_mul_f32_e32 v185, 0x45800000, v182
	v_mul_f32_e32 v186, 0x45800000, v180
	v_mul_f32_e32 v181, 0x45800000, v0
	s_waitcnt lgkmcnt(0)
	v_mfma_f32_16x16x32_bf16 v[34:37], v[30:33], v[174:177], v[34:37]
	v_mfma_f32_16x16x32_bf16 v[38:41], v[30:33], v[170:173], v[38:41]
	v_mfma_f32_16x16x32_bf16 v[42:45], v[30:33], v[166:169], v[42:45]
	v_mfma_f32_16x16x32_bf16 v[30:33], v[30:33], v[162:165], v[46:49]
	v_mfma_f32_16x16x32_bf16 v[46:49], v[26:29], v[174:177], v[50:53]
	v_mfma_f32_16x16x32_bf16 v[50:53], v[26:29], v[170:173], v[54:57]
	v_mfma_f32_16x16x32_bf16 v[54:57], v[26:29], v[166:169], v[58:61]
	v_mfma_f32_16x16x32_bf16 v[58:61], v[26:29], v[162:165], v[62:65]
	v_mfma_f32_16x16x32_bf16 v[62:65], v[22:25], v[174:177], v[66:69]
	v_mfma_f32_16x16x32_bf16 v[66:69], v[22:25], v[170:173], v[70:73]
	v_mfma_f32_16x16x32_bf16 v[70:73], v[22:25], v[166:169], v[74:77]
	v_mfma_f32_16x16x32_bf16 v[74:77], v[22:25], v[162:165], v[78:81]
	v_mfma_f32_16x16x32_bf16 v[78:81], v[18:21], v[174:177], v[82:85]
	v_mfma_f32_16x16x32_bf16 v[82:85], v[18:21], v[170:173], v[86:89]
	v_mfma_f32_16x16x32_bf16 v[86:89], v[18:21], v[166:169], v[90:93]
	v_mfma_f32_16x16x32_bf16 v[18:21], v[18:21], v[162:165], v[94:97]
	v_mfma_f32_16x16x32_bf16 v[90:93], v[14:17], v[174:177], v[98:101]
	v_mfma_f32_16x16x32_bf16 v[94:97], v[14:17], v[170:173], v[102:105]
	v_mfma_f32_16x16x32_bf16 v[98:101], v[14:17], v[166:169], v[106:109]
	v_mfma_f32_16x16x32_bf16 v[14:17], v[14:17], v[162:165], v[110:113]
	v_mfma_f32_16x16x32_bf16 v[102:105], v[10:13], v[174:177], v[114:117]
	v_mfma_f32_16x16x32_bf16 v[106:109], v[10:13], v[170:173], v[118:121]
	v_mfma_f32_16x16x32_bf16 v[110:113], v[10:13], v[166:169], v[122:125]
	v_mfma_f32_16x16x32_bf16 v[10:13], v[10:13], v[162:165], v[126:129]
	v_mfma_f32_16x16x32_bf16 v[114:117], v[6:9], v[174:177], v[130:133]
	v_mfma_f32_16x16x32_bf16 v[118:121], v[6:9], v[170:173], v[134:137]
	v_mfma_f32_16x16x32_bf16 v[122:125], v[6:9], v[166:169], v[138:141]
	v_mfma_f32_16x16x32_bf16 v[6:9], v[6:9], v[162:165], v[142:145]
	v_mfma_f32_16x16x32_bf16 v[126:129], v[2:5], v[174:177], v[146:149]
	v_mfma_f32_16x16x32_bf16 v[130:133], v[2:5], v[170:173], v[150:153]
	v_mfma_f32_16x16x32_bf16 v[134:137], v[2:5], v[166:169], v[154:157]
	v_mfma_f32_16x16x32_bf16 v[2:5], v[2:5], v[162:165], v[158:161]
	s_waitcnt vmcnt(0)
	v_cndmask_b32_e32 v26, v0, v181, vcc
	v_cndmask_b32_e64 v24, v179, v184, s[40:41]
	v_cndmask_b32_e64 v22, v182, v185, s[42:43]
	v_cndmask_b32_e64 v0, v180, v186, s[44:45]
	s_waitcnt lgkmcnt(0)
	s_barrier
	ds_read_b128 v[138:141], v178 offset:24576
	ds_read_b128 v[142:145], v178 offset:25600
	ds_read_b128 v[146:149], v178 offset:26624
	ds_read_b128 v[150:153], v178 offset:27648
	ds_read_b128 v[154:157], v183 offset:32768
	ds_read_b128 v[158:161], v183 offset:33792
	ds_read_b128 v[162:165], v183 offset:34816
	ds_read_b128 v[166:169], v183 offset:35840
	ds_read_b128 v[170:173], v183 offset:36864
	ds_read_b128 v[174:177], v183 offset:37888
	ds_read_b128 v[178:181], v183 offset:38912
	ds_read_b128 v[182:185], v183 offset:39936
	s_waitcnt lgkmcnt(7)
	v_mfma_f32_16x16x32_bf16 v[34:37], v[154:157], v[138:141], v[34:37]
	v_mfma_f32_16x16x32_bf16 v[38:41], v[154:157], v[142:145], v[38:41]
	v_mfma_f32_16x16x32_bf16 v[42:45], v[154:157], v[146:149], v[42:45]
	v_mfma_f32_16x16x32_bf16 v[28:31], v[154:157], v[150:153], v[30:33]
	s_waitcnt lgkmcnt(6)
	v_mfma_f32_16x16x32_bf16 v[46:49], v[158:161], v[138:141], v[46:49]
	v_mfma_f32_16x16x32_bf16 v[50:53], v[158:161], v[142:145], v[50:53]
	v_mfma_f32_16x16x32_bf16 v[54:57], v[158:161], v[146:149], v[54:57]
	v_mfma_f32_16x16x32_bf16 v[58:61], v[158:161], v[150:153], v[58:61]
	s_waitcnt lgkmcnt(5)
	v_mfma_f32_16x16x32_bf16 v[62:65], v[162:165], v[138:141], v[62:65]
	v_mfma_f32_16x16x32_bf16 v[66:69], v[162:165], v[142:145], v[66:69]
	v_mfma_f32_16x16x32_bf16 v[70:73], v[162:165], v[146:149], v[70:73]
	v_mfma_f32_16x16x32_bf16 v[74:77], v[162:165], v[150:153], v[74:77]
	s_waitcnt lgkmcnt(4)
	v_mfma_f32_16x16x32_bf16 v[78:81], v[166:169], v[138:141], v[78:81]
	v_mfma_f32_16x16x32_bf16 v[82:85], v[166:169], v[142:145], v[82:85]
	v_mfma_f32_16x16x32_bf16 v[86:89], v[166:169], v[146:149], v[86:89]
	v_mfma_f32_16x16x32_bf16 v[154:157], v[166:169], v[150:153], v[18:21]
	s_waitcnt lgkmcnt(3)
	v_mfma_f32_16x16x32_bf16 v[90:93], v[170:173], v[138:141], v[90:93]
	v_mfma_f32_16x16x32_bf16 v[94:97], v[170:173], v[142:145], v[94:97]
	v_mfma_f32_16x16x32_bf16 v[98:101], v[170:173], v[146:149], v[98:101]
	v_mfma_f32_16x16x32_bf16 v[158:161], v[170:173], v[150:153], v[14:17]
	s_waitcnt lgkmcnt(2)
	v_mfma_f32_16x16x32_bf16 v[102:105], v[174:177], v[138:141], v[102:105]
	v_mfma_f32_16x16x32_bf16 v[106:109], v[174:177], v[142:145], v[106:109]
	v_mfma_f32_16x16x32_bf16 v[110:113], v[174:177], v[146:149], v[110:113]
	v_mfma_f32_16x16x32_bf16 v[162:165], v[174:177], v[150:153], v[10:13]
	s_waitcnt lgkmcnt(1)
	v_mfma_f32_16x16x32_bf16 v[114:117], v[178:181], v[138:141], v[114:117]
	v_mfma_f32_16x16x32_bf16 v[118:121], v[178:181], v[142:145], v[118:121]
	v_mfma_f32_16x16x32_bf16 v[122:125], v[178:181], v[146:149], v[122:125]
	v_mfma_f32_16x16x32_bf16 v[18:21], v[178:181], v[150:153], v[6:9]
	s_waitcnt lgkmcnt(0)
	v_mfma_f32_16x16x32_bf16 v[14:17], v[182:185], v[138:141], v[126:129]
	v_mfma_f32_16x16x32_bf16 v[10:13], v[182:185], v[142:145], v[130:133]
	v_mfma_f32_16x16x32_bf16 v[6:9], v[182:185], v[146:149], v[134:137]
	v_mfma_f32_16x16x32_bf16 v[2:5], v[182:185], v[150:153], v[2:5]
	v_mov_b32_e32 v23, v224
	s_movk_i32 s12, 0x210
	v_lshrrev_b32_e32 v32, 1, v23
	v_and_b32_e32 v27, 0x7fffff80, v23
	v_and_b32_e32 v32, 24, v32
	v_and_b32_e32 v25, 0x4f, v23
	v_lshl_or_b32 v27, v27, 1, v32
	v_pk_mul_f32 v[32:33], v[26:27], v[34:35] op_sel_hi:[0,1]
	v_pk_mul_f32 v[34:35], v[26:27], v[36:37] op_sel_hi:[0,1]
	v_mad_u32_u24 v25, v25, s12, v27
	v_cvt_pk_bf16_f32 v32, v32, v33
	v_cvt_pk_bf16_f32 v33, v34, v35
	v_pk_mul_f32 v[34:35], v[24:25], v[38:39] op_sel_hi:[0,1]
	v_pk_mul_f32 v[36:37], v[24:25], v[40:41] op_sel_hi:[0,1]
	v_cvt_pk_bf16_f32 v34, v34, v35
	v_cvt_pk_bf16_f32 v35, v36, v37
	v_pk_mul_f32 v[36:37], v[22:23], v[42:43] op_sel_hi:[0,1]
	v_pk_mul_f32 v[38:39], v[22:23], v[44:45] op_sel_hi:[0,1]
	v_pk_mul_f32 v[28:29], v[0:1], v[28:29] op_sel_hi:[0,1]
	v_pk_mul_f32 v[30:31], v[0:1], v[30:31] op_sel_hi:[0,1]
	v_cvt_pk_bf16_f32 v36, v36, v37
	v_cvt_pk_bf16_f32 v37, v38, v39
	v_cvt_pk_bf16_f32 v28, v28, v29
	v_cvt_pk_bf16_f32 v29, v30, v31
	v_pk_mul_f32 v[30:31], v[26:27], v[46:47] op_sel_hi:[0,1]
	v_pk_mul_f32 v[38:39], v[26:27], v[48:49] op_sel_hi:[0,1]
	v_cvt_pk_bf16_f32 v30, v30, v31
	v_cvt_pk_bf16_f32 v31, v38, v39
	s_barrier
	ds_write2_b64 v25, v[32:33], v[30:31] offset1:4
	v_pk_mul_f32 v[30:31], v[24:25], v[50:51] op_sel_hi:[0,1]
	v_pk_mul_f32 v[32:33], v[24:25], v[52:53] op_sel_hi:[0,1]
	v_cvt_pk_bf16_f32 v30, v30, v31
	v_cvt_pk_bf16_f32 v31, v32, v33
	v_add_u32_e32 v27, 0x2000, v25
	ds_write2_b64 v27, v[34:35], v[30:31] offset0:32 offset1:36
	v_pk_mul_f32 v[30:31], v[22:23], v[54:55] op_sel_hi:[0,1]
	v_pk_mul_f32 v[32:33], v[22:23], v[56:57] op_sel_hi:[0,1]
	v_cvt_pk_bf16_f32 v30, v30, v31
	v_cvt_pk_bf16_f32 v31, v32, v33
	v_add_u32_e32 v40, 0x4000, v25
	ds_write2_b64 v40, v[36:37], v[30:31] offset0:64 offset1:68
	v_pk_mul_f32 v[30:31], v[0:1], v[58:59] op_sel_hi:[0,1]
	v_pk_mul_f32 v[32:33], v[0:1], v[60:61] op_sel_hi:[0,1]
	v_cvt_pk_bf16_f32 v30, v30, v31
	v_cvt_pk_bf16_f32 v31, v32, v33
	v_add_u32_e32 v41, 0x6000, v25
	ds_write2_b64 v41, v[28:29], v[30:31] offset0:96 offset1:100
	v_pk_mul_f32 v[28:29], v[26:27], v[62:63] op_sel_hi:[0,1]
	v_pk_mul_f32 v[30:31], v[26:27], v[64:65] op_sel_hi:[0,1]
	v_cvt_pk_bf16_f32 v28, v28, v29
	v_cvt_pk_bf16_f32 v29, v30, v31
	v_pk_mul_f32 v[30:31], v[24:25], v[66:67] op_sel_hi:[0,1]
	v_pk_mul_f32 v[32:33], v[24:25], v[68:69] op_sel_hi:[0,1]
	v_cvt_pk_bf16_f32 v30, v30, v31
	v_cvt_pk_bf16_f32 v31, v32, v33
	v_pk_mul_f32 v[32:33], v[22:23], v[70:71] op_sel_hi:[0,1]
	v_pk_mul_f32 v[34:35], v[22:23], v[72:73] op_sel_hi:[0,1]
	v_cvt_pk_bf16_f32 v32, v32, v33
	v_cvt_pk_bf16_f32 v33, v34, v35
	v_pk_mul_f32 v[34:35], v[0:1], v[74:75] op_sel_hi:[0,1]
	v_pk_mul_f32 v[36:37], v[0:1], v[76:77] op_sel_hi:[0,1]
	v_cvt_pk_bf16_f32 v34, v34, v35
	v_cvt_pk_bf16_f32 v35, v36, v37
	v_pk_mul_f32 v[36:37], v[26:27], v[78:79] op_sel_hi:[0,1]
	v_pk_mul_f32 v[38:39], v[26:27], v[80:81] op_sel_hi:[0,1]
	v_cvt_pk_bf16_f32 v36, v36, v37
	v_cvt_pk_bf16_f32 v37, v38, v39
	ds_write2_b64 v25, v[28:29], v[36:37] offset0:8 offset1:12
	v_pk_mul_f32 v[28:29], v[24:25], v[82:83] op_sel_hi:[0,1]
	v_pk_mul_f32 v[36:37], v[24:25], v[84:85] op_sel_hi:[0,1]
	v_cvt_pk_bf16_f32 v28, v28, v29
	v_cvt_pk_bf16_f32 v29, v36, v37
	ds_write2_b64 v27, v[30:31], v[28:29] offset0:40 offset1:44
	v_pk_mul_f32 v[28:29], v[22:23], v[86:87] op_sel_hi:[0,1]
	v_pk_mul_f32 v[30:31], v[22:23], v[88:89] op_sel_hi:[0,1]
	v_cvt_pk_bf16_f32 v28, v28, v29
	v_cvt_pk_bf16_f32 v29, v30, v31
	ds_write2_b64 v40, v[32:33], v[28:29] offset0:72 offset1:76
	v_pk_mul_f32 v[28:29], v[0:1], v[154:155] op_sel_hi:[0,1]
	v_pk_mul_f32 v[30:31], v[0:1], v[156:157] op_sel_hi:[0,1]
	v_cvt_pk_bf16_f32 v28, v28, v29
	v_cvt_pk_bf16_f32 v29, v30, v31
	ds_write2_b64 v41, v[34:35], v[28:29] offset0:104 offset1:108
	v_pk_mul_f32 v[28:29], v[26:27], v[90:91] op_sel_hi:[0,1]
	v_pk_mul_f32 v[30:31], v[26:27], v[92:93] op_sel_hi:[0,1]
	v_cvt_pk_bf16_f32 v28, v28, v29
	v_cvt_pk_bf16_f32 v29, v30, v31
	v_pk_mul_f32 v[30:31], v[24:25], v[94:95] op_sel_hi:[0,1]
	v_pk_mul_f32 v[32:33], v[24:25], v[96:97] op_sel_hi:[0,1]
	v_cvt_pk_bf16_f32 v30, v30, v31
	v_cvt_pk_bf16_f32 v31, v32, v33
	v_pk_mul_f32 v[32:33], v[22:23], v[98:99] op_sel_hi:[0,1]
	v_pk_mul_f32 v[34:35], v[22:23], v[100:101] op_sel_hi:[0,1]
	v_cvt_pk_bf16_f32 v32, v32, v33
	v_cvt_pk_bf16_f32 v33, v34, v35
	v_pk_mul_f32 v[34:35], v[0:1], v[158:159] op_sel_hi:[0,1]
	v_pk_mul_f32 v[36:37], v[0:1], v[160:161] op_sel_hi:[0,1]
	v_cvt_pk_bf16_f32 v34, v34, v35
	v_cvt_pk_bf16_f32 v35, v36, v37
	v_pk_mul_f32 v[36:37], v[26:27], v[102:103] op_sel_hi:[0,1]
	v_pk_mul_f32 v[38:39], v[26:27], v[104:105] op_sel_hi:[0,1]
	v_cvt_pk_bf16_f32 v36, v36, v37
	v_cvt_pk_bf16_f32 v37, v38, v39
	ds_write2_b64 v25, v[28:29], v[36:37] offset0:16 offset1:20
	v_pk_mul_f32 v[28:29], v[24:25], v[106:107] op_sel_hi:[0,1]
	v_pk_mul_f32 v[36:37], v[24:25], v[108:109] op_sel_hi:[0,1]
	v_cvt_pk_bf16_f32 v28, v28, v29
	v_cvt_pk_bf16_f32 v29, v36, v37
	ds_write2_b64 v27, v[30:31], v[28:29] offset0:48 offset1:52
	v_pk_mul_f32 v[28:29], v[22:23], v[110:111] op_sel_hi:[0,1]
	v_pk_mul_f32 v[30:31], v[22:23], v[112:113] op_sel_hi:[0,1]
	v_cvt_pk_bf16_f32 v28, v28, v29
	v_cvt_pk_bf16_f32 v29, v30, v31
	ds_write2_b64 v40, v[32:33], v[28:29] offset0:80 offset1:84
	v_pk_mul_f32 v[28:29], v[0:1], v[162:163] op_sel_hi:[0,1]
	v_pk_mul_f32 v[30:31], v[0:1], v[164:165] op_sel_hi:[0,1]
	v_cvt_pk_bf16_f32 v28, v28, v29
	v_cvt_pk_bf16_f32 v29, v30, v31
	ds_write2_b64 v41, v[34:35], v[28:29] offset0:112 offset1:116
	v_pk_mul_f32 v[28:29], v[26:27], v[114:115] op_sel_hi:[0,1]
	v_pk_mul_f32 v[30:31], v[26:27], v[116:117] op_sel_hi:[0,1]
	v_pk_mul_f32 v[18:19], v[0:1], v[18:19] op_sel_hi:[0,1]
	v_pk_mul_f32 v[20:21], v[0:1], v[20:21] op_sel_hi:[0,1]
	v_pk_mul_f32 v[2:3], v[0:1], v[2:3] op_sel_hi:[0,1]
	v_pk_mul_f32 v[4:5], v[0:1], v[4:5] op_sel_hi:[0,1]
	v_lshlrev_b32_e32 v0, 3, v23
	v_cvt_pk_bf16_f32 v28, v28, v29
	v_cvt_pk_bf16_f32 v29, v30, v31
	v_pk_mul_f32 v[30:31], v[24:25], v[118:119] op_sel_hi:[0,1]
	v_pk_mul_f32 v[32:33], v[24:25], v[120:121] op_sel_hi:[0,1]
	v_cvt_pk_bf16_f32 v18, v18, v19
	v_cvt_pk_bf16_f32 v19, v20, v21
	v_cvt_pk_bf16_f32 v2, v2, v3
	v_cvt_pk_bf16_f32 v3, v4, v5
	v_and_b32_e32 v0, 0xf8, v0
	v_cvt_pk_bf16_f32 v30, v30, v31
	v_cvt_pk_bf16_f32 v31, v32, v33
	v_pk_mul_f32 v[32:33], v[22:23], v[122:123] op_sel_hi:[0,1]
	v_pk_mul_f32 v[34:35], v[22:23], v[124:125] op_sel_hi:[0,1]
	v_pk_mul_f32 v[14:15], v[26:27], v[14:15] op_sel_hi:[0,1]
	v_pk_mul_f32 v[16:17], v[26:27], v[16:17] op_sel_hi:[0,1]
	v_pk_mul_f32 v[10:11], v[24:25], v[10:11] op_sel_hi:[0,1]
	v_pk_mul_f32 v[12:13], v[24:25], v[12:13] op_sel_hi:[0,1]
	v_pk_mul_f32 v[6:7], v[22:23], v[6:7] op_sel_hi:[0,1]
	v_pk_mul_f32 v[8:9], v[22:23], v[8:9] op_sel_hi:[0,1]
	ds_write2_b64 v41, v[18:19], v[2:3] offset0:120 offset1:124
	v_or_b32_e32 v2, s54, v0
	s_movk_i32 s12, 0xa30
	v_cvt_pk_bf16_f32 v32, v32, v33
	v_cvt_pk_bf16_f32 v33, v34, v35
	v_cvt_pk_bf16_f32 v14, v14, v15
	v_cvt_pk_bf16_f32 v15, v16, v17
	v_cvt_pk_bf16_f32 v10, v10, v11
	v_cvt_pk_bf16_f32 v11, v12, v13
	v_cvt_pk_bf16_f32 v6, v6, v7
	v_cvt_pk_bf16_f32 v7, v8, v9
	v_cmp_gt_i32_e32 vcc, s12, v2
	ds_write2_b64 v25, v[28:29], v[14:15] offset0:24 offset1:28
	ds_write2_b64 v27, v[30:31], v[10:11] offset0:56 offset1:60
	ds_write2_b64 v40, v[32:33], v[6:7] offset0:88 offset1:92
	s_waitcnt lgkmcnt(0)
	s_barrier
	s_and_saveexec_b64 s[12:13], vcc
	s_cbranch_execz .LBB0_641
	v_ashrrev_i32_e32 v8, 5, v23
	v_lshlrev_b32_e32 v0, 1, v0
	s_movk_i32 s40, 0x210
	v_mad_u64_u32 v[6:7], s[40:41], v8, s40, v[0:1]
	ds_read_b128 v[2:5], v6
	v_add_u32_e32 v7, s57, v8
	v_mov_b64_e32 v[8:9], s[4:5]
	s_ashr_i32 s55, s54, 31
	v_mad_i64_i32 v[10:11], s[40:41], v7, s16, v[8:9]
	s_lshl_b64 s[40:41], s[54:55], 1
	s_nop 0
	v_lshl_add_u64 v[10:11], v[10:11], 0, s[40:41]
	v_lshl_add_u64 v[10:11], v[10:11], 0, v[0:1]
	s_waitcnt lgkmcnt(0)
	global_store_dwordx4 v[10:11], v[2:5], off
	ds_read_b128 v[2:5], v6 offset:4224
	v_add_u32_e32 v10, 8, v7
	v_mad_i64_i32 v[10:11], s[42:43], v10, s16, v[8:9]
	v_lshl_add_u64 v[10:11], v[10:11], 0, s[40:41]
	v_lshl_add_u64 v[10:11], v[10:11], 0, v[0:1]
	s_waitcnt lgkmcnt(0)
	global_store_dwordx4 v[10:11], v[2:5], off
	ds_read_b128 v[2:5], v6 offset:8448
	v_add_u32_e32 v10, 16, v7
	v_mad_i64_i32 v[10:11], s[42:43], v10, s16, v[8:9]
	v_lshl_add_u64 v[10:11], v[10:11], 0, s[40:41]
	v_lshl_add_u64 v[10:11], v[10:11], 0, v[0:1]
	s_waitcnt lgkmcnt(0)
	global_store_dwordx4 v[10:11], v[2:5], off
	ds_read_b128 v[2:5], v6 offset:12672
	v_add_u32_e32 v10, 24, v7
	v_mad_i64_i32 v[10:11], s[42:43], v10, s16, v[8:9]
	v_lshl_add_u64 v[10:11], v[10:11], 0, s[40:41]
	v_lshl_add_u64 v[10:11], v[10:11], 0, v[0:1]
	s_waitcnt lgkmcnt(0)
	global_store_dwordx4 v[10:11], v[2:5], off
	ds_read_b128 v[2:5], v6 offset:16896
	v_add_u32_e32 v10, 32, v7
	v_mad_i64_i32 v[10:11], s[42:43], v10, s16, v[8:9]
	v_lshl_add_u64 v[10:11], v[10:11], 0, s[40:41]
	v_lshl_add_u64 v[10:11], v[10:11], 0, v[0:1]
	s_waitcnt lgkmcnt(0)
	global_store_dwordx4 v[10:11], v[2:5], off
	ds_read_b128 v[2:5], v6 offset:21120
	v_add_u32_e32 v10, 40, v7
	v_mad_i64_i32 v[10:11], s[42:43], v10, s16, v[8:9]
	v_lshl_add_u64 v[10:11], v[10:11], 0, s[40:41]
	v_lshl_add_u64 v[10:11], v[10:11], 0, v[0:1]
	s_waitcnt lgkmcnt(0)
	global_store_dwordx4 v[10:11], v[2:5], off
	ds_read_b128 v[2:5], v6 offset:25344
	v_add_u32_e32 v10, 48, v7
	v_mad_i64_i32 v[10:11], s[42:43], v10, s16, v[8:9]
	v_lshl_add_u64 v[10:11], v[10:11], 0, s[40:41]
	v_lshl_add_u64 v[10:11], v[10:11], 0, v[0:1]
	s_waitcnt lgkmcnt(0)
	global_store_dwordx4 v[10:11], v[2:5], off
	ds_read_b128 v[2:5], v6 offset:29568
	v_add_u32_e32 v10, 56, v7
	v_mad_i64_i32 v[10:11], s[42:43], v10, s16, v[8:9]
	v_lshl_add_u64 v[10:11], v[10:11], 0, s[40:41]
	v_lshl_add_u64 v[10:11], v[10:11], 0, v[0:1]
	s_waitcnt lgkmcnt(0)
	global_store_dwordx4 v[10:11], v[2:5], off
	ds_read_b128 v[2:5], v6 offset:33792
	v_add_u32_e32 v10, 64, v7
	v_mad_i64_i32 v[10:11], s[42:43], v10, s16, v[8:9]
	v_lshl_add_u64 v[10:11], v[10:11], 0, s[40:41]
	v_lshl_add_u64 v[10:11], v[10:11], 0, v[0:1]
	s_waitcnt lgkmcnt(0)
	global_store_dwordx4 v[10:11], v[2:5], off
	ds_read_b128 v[2:5], v6 offset:38016
	v_add_u32_e32 v10, 0x48, v7
	v_mad_i64_i32 v[10:11], s[42:43], v10, s16, v[8:9]
	v_lshl_add_u64 v[10:11], v[10:11], 0, s[40:41]
	v_lshl_add_u64 v[10:11], v[10:11], 0, v[0:1]
	s_waitcnt lgkmcnt(0)
	global_store_dwordx4 v[10:11], v[2:5], off
	ds_read_b128 v[2:5], v6 offset:42240
	v_add_u32_e32 v10, 0x50, v7
	v_mad_i64_i32 v[10:11], s[42:43], v10, s16, v[8:9]
	v_lshl_add_u64 v[10:11], v[10:11], 0, s[40:41]
	v_lshl_add_u64 v[10:11], v[10:11], 0, v[0:1]
	s_waitcnt lgkmcnt(0)
	global_store_dwordx4 v[10:11], v[2:5], off
	ds_read_b128 v[2:5], v6 offset:46464
	v_add_u32_e32 v10, 0x58, v7
	v_mad_i64_i32 v[10:11], s[42:43], v10, s16, v[8:9]
	v_lshl_add_u64 v[10:11], v[10:11], 0, s[40:41]
	v_lshl_add_u64 v[10:11], v[10:11], 0, v[0:1]
	s_waitcnt lgkmcnt(0)
	global_store_dwordx4 v[10:11], v[2:5], off
	ds_read_b128 v[2:5], v6 offset:50688
	v_add_u32_e32 v10, 0x60, v7
	v_mad_i64_i32 v[10:11], s[42:43], v10, s16, v[8:9]
	v_lshl_add_u64 v[10:11], v[10:11], 0, s[40:41]
	v_lshl_add_u64 v[10:11], v[10:11], 0, v[0:1]
	s_waitcnt lgkmcnt(0)
	global_store_dwordx4 v[10:11], v[2:5], off
	ds_read_b128 v[2:5], v6 offset:54912
	v_add_u32_e32 v10, 0x68, v7
	v_mad_i64_i32 v[10:11], s[42:43], v10, s16, v[8:9]
	v_lshl_add_u64 v[10:11], v[10:11], 0, s[40:41]
	v_lshl_add_u64 v[10:11], v[10:11], 0, v[0:1]
	s_waitcnt lgkmcnt(0)
	global_store_dwordx4 v[10:11], v[2:5], off
	ds_read_b128 v[2:5], v6 offset:59136
	v_add_u32_e32 v10, 0x70, v7
	v_mad_i64_i32 v[10:11], s[42:43], v10, s16, v[8:9]
	v_lshl_add_u64 v[10:11], v[10:11], 0, s[40:41]
	v_lshl_add_u64 v[10:11], v[10:11], 0, v[0:1]
	s_waitcnt lgkmcnt(0)
	global_store_dwordx4 v[10:11], v[2:5], off
	ds_read_b128 v[2:5], v6 offset:63360
	v_add_u32_e32 v6, 0x78, v7
	v_mad_i64_i32 v[6:7], s[42:43], v6, s16, v[8:9]
	v_lshl_add_u64 v[6:7], v[6:7], 0, s[40:41]
	v_lshl_add_u64 v[6:7], v[6:7], 0, v[0:1]
	s_waitcnt lgkmcnt(0)
	global_store_dwordx4 v[6:7], v[2:5], off
	s_branch .LBB0_641

.LBB0_702:
	s_or_b64 exec, exec, s[14:15]
	s_waitcnt lgkmcnt(0)
	s_add_u32 s69, s86, s46
	s_addc_u32 s79, s87, s47
	s_movk_i32 s14, 0x104
	s_cmp_gt_i32 s53, -1
	s_mov_b32 s94, s53
	v_mul_lo_u32 v0, v37, s14
	s_cselect_b64 s[46:47], -1, 0
	s_lshl_b64 s[14:15], s[94:95], 3
	v_readlane_b32 s44, v253, 0
	v_readlane_b32 s45, v253, 1
	s_add_u32 s70, s44, s14
	s_addc_u32 s71, s45, s15
	s_ashr_i32 s55, s54, 31
	s_ashr_i32 s49, s48, 31
	v_lshl_add_u32 v0, v36, 2, v0
	s_cmp_eq_u32 s52, 0
	s_waitcnt vmcnt(0)
	ds_write2_b32 v0, v6, v7 offset1:1
	ds_write2_b32 v0, v8, v9 offset0:2 offset1:3
	v_add_u32_e32 v6, 0x1040, v0
	s_cselect_b64 s[44:45], -1, 0
	s_add_i32 s14, s68, 0xfffff540
	ds_write2_b32 v6, v2, v3 offset1:1
	v_add_u32_e32 v2, 0x1048, v0
	s_lshr_b32 s14, s14, 6
	ds_write2_b32 v2, v4, v5 offset1:1
	v_add_u32_e32 v2, 0x2080, v0
	s_cmp_gt_i32 s78, 42
	ds_write2_b32 v2, v14, v15 offset1:1
	v_add_u32_e32 v2, 0x2088, v0
	s_cselect_b32 s14, s14, s78
	ds_write2_b32 v2, v16, v17 offset1:1
	v_add_u32_e32 v2, 0x30c0, v0
	v_add_u32_e32 v0, 0x30c8, v0
	s_cselect_b32 s15, 64, 0
	s_lshl_b32 s14, s14, 7
	ds_write2_b32 v0, v12, v13 offset1:1
	v_lshlrev_b32_e32 v0, 3, v35
	s_or_b32 s14, s14, s15
	s_lshl_b64 s[52:53], s[48:49], 1
	v_ashrrev_i32_e32 v13, 3, v35
	v_and_b32_e32 v12, 56, v0
	s_add_u32 s52, s69, s52
	s_addc_u32 s53, s79, s53
	v_lshlrev_b32_e32 v0, 1, v12
	v_add_u32_e32 v14, s68, v13
	v_cndmask_b32_e64 v4, 0, 1, s[46:47]
	ds_write2_b32 v2, v10, v11 offset1:1
	v_lshl_add_u64 v[2:3], s[52:53], 0, v[0:1]
	s_mov_b32 s100, s12
	s_cmpk_eq_u32 s12, 0x400
	s_cbranch_scc0 .Lmy_kb_skip
	s_cmpk_eq_u32 s13, 0x400
	s_cbranch_scc0 .Lmy_kb_do
	s_cmp_lt_i32 s94, 0
	s_cbranch_scc1 .Lmy_kb_skip
.Lmy_kb_do:
	s_movk_i32 s100, 32
	s_lshr_b32 s101, s48, 5
	s_mul_i32 s101, s101, s13
	s_lshl_b32 s101, s101, 6
	s_add_u32 vcc_lo, s69, s101
	s_addc_u32 vcc_hi, s79, 0
	s_lshl_b32 s101, s13, 6
	v_lshrrev_b32_e32 v212, 5, v12
	v_mul_lo_u32 v212, v212, s101
	v_and_b32_e32 v213, 31, v12
	v_lshl_add_u32 v212, v213, 1, v212
	v_mov_b32_e32 v213, 0
	v_lshl_add_u64 v[2:3], vcc, 0, v[212:213]
